# fused pass-1: two accumulators per state dot, one negate-add in place of three adds
# baseline (speedup 1.0000x reference)
; #define SB __builtin_amdgcn_sched_barrier(0)
; #define TOUCH1(set) asm volatile("" :: "v"(set.w), "v"(set.a), "v"(set.b), "v"(set.kw), "v"(set.v))
; #define ST1(set) { DERIVE_BK(set); float sd[4]; ScanK<0>::dot(S, set.a, sd); ScanK<0>::updS(S, set, -((sd[0] + sd[1]) + (sd[2] + sd[3])), __uint_as_float(set.v << 16)); }
; #define TOUCH1(set) asm volatile("" :: "v"(set.w), "v"(set.a), "v"(set.b))
;     static __device__ __forceinline__ void dot(const float (&S)[64], const f32x4& a, float (&s)[4]) {
;         if constexpr (K == 0) {
;             asm volatile("v_mul_f32_dpp %0, %4, %8 row_newbcast:%16" DPPM "v_mul_f32_dpp %1, %5, %9 row_newbcast:%16" DPPM "v_mul_f32_dpp %2, %6, %10 row_newbcast:%16" DPPM "v_mul_f32_dpp %3, %7, %11 row_newbcast:%16" DPPM
;                          "v_fmac_f32_dpp %0, %4, %12 row_newbcast:%17" DPPM "v_fmac_f32_dpp %1, %5, %13 row_newbcast:%17" DPPM "v_fmac_f32_dpp %2, %6, %14 row_newbcast:%17" DPPM "v_fmac_f32_dpp %3, %7, %15 row_newbcast:%17" DPPM
;                          : "=&v"(s[0]), "=&v"(s[1]), "=&v"(s[2]), "=&v"(s[3])
;                          : "v"(a[0]), "v"(a[1]), "v"(a[2]), "v"(a[3]), "v"(S[K]), "v"(S[K + 1]), "v"(S[K + 2]), "v"(S[K + 3]), "v"(S[K + 4]), "v"(S[K + 5]), "v"(S[K + 6]), "v"(S[K + 7]), "n"(N0), "n"(N1));
;         } else
;         asm volatile("v_fmac_f32_dpp %0, %4, %8 row_newbcast:%16" DPPM "v_fmac_f32_dpp %1, %5, %9 row_newbcast:%16" DPPM "v_fmac_f32_dpp %2, %6, %10 row_newbcast:%16" DPPM "v_fmac_f32_dpp %3, %7, %11 row_newbcast:%16" DPPM
;                      "v_fmac_f32_dpp %0, %4, %12 row_newbcast:%17" DPPM "v_fmac_f32_dpp %1, %5, %13 row_newbcast:%17" DPPM "v_fmac_f32_dpp %2, %6, %14 row_newbcast:%17" DPPM "v_fmac_f32_dpp %3, %7, %15 row_newbcast:%17" DPPM
;                      : "+v"(s[0]), "+v"(s[1]), "+v"(s[2]), "+v"(s[3])
;                      : "v"(a[0]), "v"(a[1]), "v"(a[2]), "v"(a[3]), "v"(S[K]), "v"(S[K + 1]), "v"(S[K + 2]), "v"(S[K + 3]), "v"(S[K + 4]), "v"(S[K + 5]), "v"(S[K + 6]), "v"(S[K + 7]), "n"(N0), "n"(N1));
;         if constexpr (K + 8 < 64) ScanK<K + 8>::dot(S, a, s);
; template <bool MIX> __device__ __forceinline__ void scan_pass1(const Params& p, int d, float* ldsf) {
;     ...
;             In1 i0, i1; LD1(i0, 0);
; #pragma unroll 1
;             for (int s = 0; s < LC; s += 2) { TOUCH1(i0); SB; LD1(i1, s + 1); SB; ST1(i0); TOUCH1(i1); SB; LD1(i0, s + 2); SB; ST1(i1); }
.Lmy_p1d0_loop:
	s_waitcnt vmcnt(5)
	buffer_load_dwordx4 v[192:195], v235, s[64:67], s72 offen
	buffer_load_dwordx4 v[196:199], v250, s[64:67], s72 offen
	buffer_load_dwordx4 v[200:203], v251, s[64:67], s72 offen
	buffer_load_dwordx2 v[204:205], v252, s[64:67], s76 offen
	buffer_load_ushort v206, v253, s[64:67], s76 offen
	s_add_u32 s72, s72, 0x1000
	s_add_u32 s76, s76, 0x800
	v_pk_mul_f32 v[244:245], v[164:165], v[236:237]
	v_pk_mul_f32 v[246:247], v[166:167], v[238:239]
	v_pk_mul_f32 v[236:237], v[236:237], v[160:161]
	v_pk_mul_f32 v[238:239], v[238:239], v[162:163]
	v_pk_fma_f32 v[228:229], v[168:169], v[216:217], v[220:221]
	v_pk_fma_f32 v[230:231], v[170:171], v[218:219], v[222:223]
	v_pk_mul_f32 v[208:209], v[164:165], v[168:169]
	v_pk_mul_f32 v[210:211], v[166:167], v[170:171]
	v_rcp_f32_e32 v240, v236
	v_rcp_f32_e32 v241, v237
	v_rcp_f32_e32 v242, v238
	v_rcp_f32_e32 v243, v239
	v_lshlrev_b32_e32 v212, 16, v172
	v_and_b32_e32 v213, 0xffff0000, v172
	v_lshlrev_b32_e32 v214, 16, v173
	v_and_b32_e32 v215, 0xffff0000, v173
	v_pk_mul_f32 v[212:213], v[212:213], v[228:229]
	v_pk_mul_f32 v[214:215], v[214:215], v[230:231]
	v_lshlrev_b32_e32 v234, 16, v174
	v_pk_mul_f32 v[208:209], v[208:209], v[240:241]
	v_pk_mul_f32 v[210:211], v[210:211], v[242:243]
	v_pk_mul_f32 v[212:213], v[212:213], v[240:241]
	v_pk_mul_f32 v[214:215], v[214:215], v[242:243]
	ds_write2_b32 v248, v208, v209 offset0:0 offset1:16
	ds_write2_b32 v248, v210, v211 offset0:32 offset1:48
	ds_write2_b32 v248, v212, v213 offset0:64 offset1:80
	ds_write2_b32 v248, v214, v215 offset0:96 offset1:112
	ds_read_b128 v[128:131], v249 offset:0
	ds_read_b128 v[132:135], v249 offset:16
	ds_read_b128 v[136:139], v249 offset:32
	ds_read_b128 v[140:143], v249 offset:48
	ds_read_b128 v[144:147], v249 offset:256
	ds_read_b128 v[148:151], v249 offset:272
	ds_read_b128 v[152:155], v249 offset:288
	ds_read_b128 v[156:159], v249 offset:304
	v_mul_f32_dpp v224, v244, v0 row_newbcast:0 row_mask:0xf bank_mask:0xf
	v_mul_f32_dpp v225, v245, v1 row_newbcast:0 row_mask:0xf bank_mask:0xf
	v_fmac_f32_dpp v224, v246, v2 row_newbcast:0 row_mask:0xf bank_mask:0xf
	v_fmac_f32_dpp v225, v247, v3 row_newbcast:0 row_mask:0xf bank_mask:0xf
	v_fmac_f32_dpp v224, v244, v4 row_newbcast:1 row_mask:0xf bank_mask:0xf
	v_fmac_f32_dpp v225, v245, v5 row_newbcast:1 row_mask:0xf bank_mask:0xf
	v_fmac_f32_dpp v224, v246, v6 row_newbcast:1 row_mask:0xf bank_mask:0xf
	v_fmac_f32_dpp v225, v247, v7 row_newbcast:1 row_mask:0xf bank_mask:0xf
	v_fmac_f32_dpp v224, v244, v8 row_newbcast:2 row_mask:0xf bank_mask:0xf
	v_fmac_f32_dpp v225, v245, v9 row_newbcast:2 row_mask:0xf bank_mask:0xf
	v_fmac_f32_dpp v224, v246, v10 row_newbcast:2 row_mask:0xf bank_mask:0xf
	v_fmac_f32_dpp v225, v247, v11 row_newbcast:2 row_mask:0xf bank_mask:0xf
	v_fmac_f32_dpp v224, v244, v12 row_newbcast:3 row_mask:0xf bank_mask:0xf
	v_fmac_f32_dpp v225, v245, v13 row_newbcast:3 row_mask:0xf bank_mask:0xf
	v_fmac_f32_dpp v224, v246, v14 row_newbcast:3 row_mask:0xf bank_mask:0xf
	v_fmac_f32_dpp v225, v247, v15 row_newbcast:3 row_mask:0xf bank_mask:0xf
	v_fmac_f32_dpp v224, v244, v16 row_newbcast:4 row_mask:0xf bank_mask:0xf
	v_fmac_f32_dpp v225, v245, v17 row_newbcast:4 row_mask:0xf bank_mask:0xf
	v_fmac_f32_dpp v224, v246, v18 row_newbcast:4 row_mask:0xf bank_mask:0xf
	v_fmac_f32_dpp v225, v247, v19 row_newbcast:4 row_mask:0xf bank_mask:0xf
	v_fmac_f32_dpp v224, v244, v20 row_newbcast:5 row_mask:0xf bank_mask:0xf
	v_fmac_f32_dpp v225, v245, v21 row_newbcast:5 row_mask:0xf bank_mask:0xf
	v_fmac_f32_dpp v224, v246, v22 row_newbcast:5 row_mask:0xf bank_mask:0xf
	v_fmac_f32_dpp v225, v247, v23 row_newbcast:5 row_mask:0xf bank_mask:0xf
	v_fmac_f32_dpp v224, v244, v24 row_newbcast:6 row_mask:0xf bank_mask:0xf
	v_fmac_f32_dpp v225, v245, v25 row_newbcast:6 row_mask:0xf bank_mask:0xf
	v_fmac_f32_dpp v224, v246, v26 row_newbcast:6 row_mask:0xf bank_mask:0xf
	v_fmac_f32_dpp v225, v247, v27 row_newbcast:6 row_mask:0xf bank_mask:0xf
	v_fmac_f32_dpp v224, v244, v28 row_newbcast:7 row_mask:0xf bank_mask:0xf
	v_fmac_f32_dpp v225, v245, v29 row_newbcast:7 row_mask:0xf bank_mask:0xf
	v_fmac_f32_dpp v224, v246, v30 row_newbcast:7 row_mask:0xf bank_mask:0xf
	v_fmac_f32_dpp v225, v247, v31 row_newbcast:7 row_mask:0xf bank_mask:0xf
	v_fmac_f32_dpp v224, v244, v32 row_newbcast:8 row_mask:0xf bank_mask:0xf
	v_fmac_f32_dpp v225, v245, v33 row_newbcast:8 row_mask:0xf bank_mask:0xf
	v_fmac_f32_dpp v224, v246, v34 row_newbcast:8 row_mask:0xf bank_mask:0xf
	v_fmac_f32_dpp v225, v247, v35 row_newbcast:8 row_mask:0xf bank_mask:0xf
	v_fmac_f32_dpp v224, v244, v36 row_newbcast:9 row_mask:0xf bank_mask:0xf
	v_fmac_f32_dpp v225, v245, v37 row_newbcast:9 row_mask:0xf bank_mask:0xf
	v_fmac_f32_dpp v224, v246, v38 row_newbcast:9 row_mask:0xf bank_mask:0xf
	v_fmac_f32_dpp v225, v247, v39 row_newbcast:9 row_mask:0xf bank_mask:0xf
	v_fmac_f32_dpp v224, v244, v40 row_newbcast:10 row_mask:0xf bank_mask:0xf
	v_fmac_f32_dpp v225, v245, v41 row_newbcast:10 row_mask:0xf bank_mask:0xf
	v_fmac_f32_dpp v224, v246, v42 row_newbcast:10 row_mask:0xf bank_mask:0xf
	v_fmac_f32_dpp v225, v247, v43 row_newbcast:10 row_mask:0xf bank_mask:0xf
	v_fmac_f32_dpp v224, v244, v44 row_newbcast:11 row_mask:0xf bank_mask:0xf
	v_fmac_f32_dpp v225, v245, v45 row_newbcast:11 row_mask:0xf bank_mask:0xf
	v_fmac_f32_dpp v224, v246, v46 row_newbcast:11 row_mask:0xf bank_mask:0xf
	v_fmac_f32_dpp v225, v247, v47 row_newbcast:11 row_mask:0xf bank_mask:0xf
	v_fmac_f32_dpp v224, v244, v48 row_newbcast:12 row_mask:0xf bank_mask:0xf
	v_fmac_f32_dpp v225, v245, v49 row_newbcast:12 row_mask:0xf bank_mask:0xf
;     static __device__ __forceinline__ void dot(const float (&S)[64], const f32x4& a, float (&s)[4]) {
;         if constexpr (K == 0) {
;             asm volatile("v_mul_f32_dpp %0, %4, %8 row_newbcast:%16" DPPM "v_mul_f32_dpp %1, %5, %9 row_newbcast:%16" DPPM "v_mul_f32_dpp %2, %6, %10 row_newbcast:%16" DPPM "v_mul_f32_dpp %3, %7, %11 row_newbcast:%16" DPPM
;                          "v_fmac_f32_dpp %0, %4, %12 row_newbcast:%17" DPPM "v_fmac_f32_dpp %1, %5, %13 row_newbcast:%17" DPPM "v_fmac_f32_dpp %2, %6, %14 row_newbcast:%17" DPPM "v_fmac_f32_dpp %3, %7, %15 row_newbcast:%17" DPPM
;                          : "=&v"(s[0]), "=&v"(s[1]), "=&v"(s[2]), "=&v"(s[3])
;                          : "v"(a[0]), "v"(a[1]), "v"(a[2]), "v"(a[3]), "v"(S[K]), "v"(S[K + 1]), "v"(S[K + 2]), "v"(S[K + 3]), "v"(S[K + 4]), "v"(S[K + 5]), "v"(S[K + 6]), "v"(S[K + 7]), "n"(N0), "n"(N1));
;         } else
;         asm volatile("v_fmac_f32_dpp %0, %4, %8 row_newbcast:%16" DPPM "v_fmac_f32_dpp %1, %5, %9 row_newbcast:%16" DPPM "v_fmac_f32_dpp %2, %6, %10 row_newbcast:%16" DPPM "v_fmac_f32_dpp %3, %7, %11 row_newbcast:%16" DPPM
;                      "v_fmac_f32_dpp %0, %4, %12 row_newbcast:%17" DPPM "v_fmac_f32_dpp %1, %5, %13 row_newbcast:%17" DPPM "v_fmac_f32_dpp %2, %6, %14 row_newbcast:%17" DPPM "v_fmac_f32_dpp %3, %7, %15 row_newbcast:%17" DPPM
;                      : "+v"(s[0]), "+v"(s[1]), "+v"(s[2]), "+v"(s[3])
;                      : "v"(a[0]), "v"(a[1]), "v"(a[2]), "v"(a[3]), "v"(S[K]), "v"(S[K + 1]), "v"(S[K + 2]), "v"(S[K + 3]), "v"(S[K + 4]), "v"(S[K + 5]), "v"(S[K + 6]), "v"(S[K + 7]), "n"(N0), "n"(N1));
;         if constexpr (K + 8 < 64) ScanK<K + 8>::dot(S, a, s);
	v_fmac_f32_dpp v224, v246, v50 row_newbcast:12 row_mask:0xf bank_mask:0xf
	v_fmac_f32_dpp v225, v247, v51 row_newbcast:12 row_mask:0xf bank_mask:0xf
	v_fmac_f32_dpp v224, v244, v52 row_newbcast:13 row_mask:0xf bank_mask:0xf
	v_fmac_f32_dpp v225, v245, v53 row_newbcast:13 row_mask:0xf bank_mask:0xf
	v_fmac_f32_dpp v224, v246, v54 row_newbcast:13 row_mask:0xf bank_mask:0xf
	v_fmac_f32_dpp v225, v247, v55 row_newbcast:13 row_mask:0xf bank_mask:0xf
	v_fmac_f32_dpp v224, v244, v56 row_newbcast:14 row_mask:0xf bank_mask:0xf
	v_fmac_f32_dpp v225, v245, v57 row_newbcast:14 row_mask:0xf bank_mask:0xf
	v_fmac_f32_dpp v224, v246, v58 row_newbcast:14 row_mask:0xf bank_mask:0xf
	v_fmac_f32_dpp v225, v247, v59 row_newbcast:14 row_mask:0xf bank_mask:0xf
	v_fmac_f32_dpp v224, v244, v60 row_newbcast:15 row_mask:0xf bank_mask:0xf
	v_fmac_f32_dpp v225, v245, v61 row_newbcast:15 row_mask:0xf bank_mask:0xf
	v_fmac_f32_dpp v224, v246, v62 row_newbcast:15 row_mask:0xf bank_mask:0xf
	v_fmac_f32_dpp v225, v247, v63 row_newbcast:15 row_mask:0xf bank_mask:0xf
	v_mul_f32_dpp v228, v244, v64 row_newbcast:0 row_mask:0xf bank_mask:0xf
	v_mul_f32_dpp v229, v245, v65 row_newbcast:0 row_mask:0xf bank_mask:0xf
	v_fmac_f32_dpp v228, v246, v66 row_newbcast:0 row_mask:0xf bank_mask:0xf
	v_fmac_f32_dpp v229, v247, v67 row_newbcast:0 row_mask:0xf bank_mask:0xf
	v_fmac_f32_dpp v228, v244, v68 row_newbcast:1 row_mask:0xf bank_mask:0xf
	v_fmac_f32_dpp v229, v245, v69 row_newbcast:1 row_mask:0xf bank_mask:0xf
	v_fmac_f32_dpp v228, v246, v70 row_newbcast:1 row_mask:0xf bank_mask:0xf
	v_fmac_f32_dpp v229, v247, v71 row_newbcast:1 row_mask:0xf bank_mask:0xf
	v_fmac_f32_dpp v228, v244, v72 row_newbcast:2 row_mask:0xf bank_mask:0xf
	v_fmac_f32_dpp v229, v245, v73 row_newbcast:2 row_mask:0xf bank_mask:0xf
	v_fmac_f32_dpp v228, v246, v74 row_newbcast:2 row_mask:0xf bank_mask:0xf
	v_fmac_f32_dpp v229, v247, v75 row_newbcast:2 row_mask:0xf bank_mask:0xf
	v_fmac_f32_dpp v228, v244, v76 row_newbcast:3 row_mask:0xf bank_mask:0xf
	v_fmac_f32_dpp v229, v245, v77 row_newbcast:3 row_mask:0xf bank_mask:0xf
	v_fmac_f32_dpp v228, v246, v78 row_newbcast:3 row_mask:0xf bank_mask:0xf
	v_fmac_f32_dpp v229, v247, v79 row_newbcast:3 row_mask:0xf bank_mask:0xf
	v_fmac_f32_dpp v228, v244, v80 row_newbcast:4 row_mask:0xf bank_mask:0xf
	v_fmac_f32_dpp v229, v245, v81 row_newbcast:4 row_mask:0xf bank_mask:0xf
	v_fmac_f32_dpp v228, v246, v82 row_newbcast:4 row_mask:0xf bank_mask:0xf
	v_fmac_f32_dpp v229, v247, v83 row_newbcast:4 row_mask:0xf bank_mask:0xf
	v_fmac_f32_dpp v228, v244, v84 row_newbcast:5 row_mask:0xf bank_mask:0xf
	v_fmac_f32_dpp v229, v245, v85 row_newbcast:5 row_mask:0xf bank_mask:0xf
	v_fmac_f32_dpp v228, v246, v86 row_newbcast:5 row_mask:0xf bank_mask:0xf
	v_fmac_f32_dpp v229, v247, v87 row_newbcast:5 row_mask:0xf bank_mask:0xf
	v_fmac_f32_dpp v228, v244, v88 row_newbcast:6 row_mask:0xf bank_mask:0xf
	v_fmac_f32_dpp v229, v245, v89 row_newbcast:6 row_mask:0xf bank_mask:0xf
	v_fmac_f32_dpp v228, v246, v90 row_newbcast:6 row_mask:0xf bank_mask:0xf
	v_fmac_f32_dpp v229, v247, v91 row_newbcast:6 row_mask:0xf bank_mask:0xf
	v_fmac_f32_dpp v228, v244, v92 row_newbcast:7 row_mask:0xf bank_mask:0xf
	v_fmac_f32_dpp v229, v245, v93 row_newbcast:7 row_mask:0xf bank_mask:0xf
	v_fmac_f32_dpp v228, v246, v94 row_newbcast:7 row_mask:0xf bank_mask:0xf
	v_fmac_f32_dpp v229, v247, v95 row_newbcast:7 row_mask:0xf bank_mask:0xf
	v_fmac_f32_dpp v228, v244, v96 row_newbcast:8 row_mask:0xf bank_mask:0xf
	v_fmac_f32_dpp v229, v245, v97 row_newbcast:8 row_mask:0xf bank_mask:0xf
	v_fmac_f32_dpp v228, v246, v98 row_newbcast:8 row_mask:0xf bank_mask:0xf
	v_fmac_f32_dpp v229, v247, v99 row_newbcast:8 row_mask:0xf bank_mask:0xf
	v_fmac_f32_dpp v228, v244, v100 row_newbcast:9 row_mask:0xf bank_mask:0xf
	v_fmac_f32_dpp v229, v245, v101 row_newbcast:9 row_mask:0xf bank_mask:0xf
	v_fmac_f32_dpp v228, v246, v102 row_newbcast:9 row_mask:0xf bank_mask:0xf
	v_fmac_f32_dpp v229, v247, v103 row_newbcast:9 row_mask:0xf bank_mask:0xf
	v_fmac_f32_dpp v228, v244, v104 row_newbcast:10 row_mask:0xf bank_mask:0xf
	v_fmac_f32_dpp v229, v245, v105 row_newbcast:10 row_mask:0xf bank_mask:0xf
	v_fmac_f32_dpp v228, v246, v106 row_newbcast:10 row_mask:0xf bank_mask:0xf
	v_fmac_f32_dpp v229, v247, v107 row_newbcast:10 row_mask:0xf bank_mask:0xf
	v_fmac_f32_dpp v228, v244, v108 row_newbcast:11 row_mask:0xf bank_mask:0xf
	v_fmac_f32_dpp v229, v245, v109 row_newbcast:11 row_mask:0xf bank_mask:0xf
	v_fmac_f32_dpp v228, v246, v110 row_newbcast:11 row_mask:0xf bank_mask:0xf
	v_fmac_f32_dpp v229, v247, v111 row_newbcast:11 row_mask:0xf bank_mask:0xf
	v_fmac_f32_dpp v228, v244, v112 row_newbcast:12 row_mask:0xf bank_mask:0xf
	v_fmac_f32_dpp v229, v245, v113 row_newbcast:12 row_mask:0xf bank_mask:0xf
	v_fmac_f32_dpp v228, v246, v114 row_newbcast:12 row_mask:0xf bank_mask:0xf
	v_fmac_f32_dpp v229, v247, v115 row_newbcast:12 row_mask:0xf bank_mask:0xf
	v_fmac_f32_dpp v228, v244, v116 row_newbcast:13 row_mask:0xf bank_mask:0xf
	v_fmac_f32_dpp v229, v245, v117 row_newbcast:13 row_mask:0xf bank_mask:0xf
	v_fmac_f32_dpp v228, v246, v118 row_newbcast:13 row_mask:0xf bank_mask:0xf
	v_fmac_f32_dpp v229, v247, v119 row_newbcast:13 row_mask:0xf bank_mask:0xf
	v_fmac_f32_dpp v228, v244, v120 row_newbcast:14 row_mask:0xf bank_mask:0xf
	v_fmac_f32_dpp v229, v245, v121 row_newbcast:14 row_mask:0xf bank_mask:0xf
	v_fmac_f32_dpp v228, v246, v122 row_newbcast:14 row_mask:0xf bank_mask:0xf
	v_fmac_f32_dpp v229, v247, v123 row_newbcast:14 row_mask:0xf bank_mask:0xf
	v_fmac_f32_dpp v228, v244, v124 row_newbcast:15 row_mask:0xf bank_mask:0xf
	v_fmac_f32_dpp v229, v245, v125 row_newbcast:15 row_mask:0xf bank_mask:0xf
	v_fmac_f32_dpp v228, v246, v126 row_newbcast:15 row_mask:0xf bank_mask:0xf
	v_fmac_f32_dpp v229, v247, v127 row_newbcast:15 row_mask:0xf bank_mask:0xf
	v_sub_f32_e64 v232, -v224, v225
	v_sub_f32_e64 v233, -v228, v229
	s_waitcnt lgkmcnt(0)
;     static __device__ __forceinline__ void updS(float (&S)[64], const In1& in, float sa, float vv) {
;         float t0, t1, t2, t3;
;         asm volatile("v_mul_f32_dpp %0, %8, %21 row_newbcast:%22" DPPM "v_mul_f32_dpp %1, %9, %21 row_newbcast:%22" DPPM "v_mul_f32_dpp %2, %10, %21 row_newbcast:%22" DPPM "v_mul_f32_dpp %3, %11, %21 row_newbcast:%22" DPPM
;                      "v_fmac_f32_dpp %0, %12, %4 row_newbcast:%22" DPPM "v_fmac_f32_dpp %1, %13, %5 row_newbcast:%22" DPPM "v_fmac_f32_dpp %2, %14, %6 row_newbcast:%22" DPPM "v_fmac_f32_dpp %3, %15, %7 row_newbcast:%22" DPPM
;                      "v_fmac_f32_dpp %0, %16, %20 row_newbcast:%22" DPPM "v_fmac_f32_dpp %1, %17, %20 row_newbcast:%22" DPPM "v_fmac_f32_dpp %2, %18, %20 row_newbcast:%22" DPPM "v_fmac_f32_dpp %3, %19, %20 row_newbcast:%22" DPPM
;                      : "=&v"(t0), "=&v"(t1), "=&v"(t2), "=&v"(t3)
;                      : "v"(S[K]), "v"(S[K + 1]), "v"(S[K + 2]), "v"(S[K + 3]), "v"(in.kd[0]), "v"(in.kd[1]), "v"(in.kd[2]), "v"(in.kd[3]), "v"(in.w[0]), "v"(in.w[1]), "v"(in.w[2]), "v"(in.w[3]),
;                        "v"(in.b[0]), "v"(in.b[1]), "v"(in.b[2]), "v"(in.b[3]), "v"(sa), "v"(vv), "n"(N0));
;         S[K] = t0; S[K + 1] = t1; S[K + 2] = t2; S[K + 3] = t3;
;         if constexpr (K + 4 < 64) ScanK<K + 4>::updS(S, in, sa, vv);
;     }
;     static __device__ __forceinline__ void updP(float (&P)[64], const In1& in, float sa) {
;         float u0, u1, u2, u3;
;         asm volatile("v_mul_f32_dpp %0, %8, %4 row_newbcast:%17" DPPM "v_mul_f32_dpp %1, %9, %5 row_newbcast:%17" DPPM "v_mul_f32_dpp %2, %10, %6 row_newbcast:%17" DPPM "v_mul_f32_dpp %3, %11, %7 row_newbcast:%17" DPPM
;                      "v_fmac_f32_dpp %0, %12, %16 row_newbcast:%17" DPPM "v_fmac_f32_dpp %1, %13, %16 row_newbcast:%17" DPPM "v_fmac_f32_dpp %2, %14, %16 row_newbcast:%17" DPPM "v_fmac_f32_dpp %3, %15, %16 row_newbcast:%17" DPPM
;                      : "=&v"(u0), "=&v"(u1), "=&v"(u2), "=&v"(u3)
;                      : "v"(P[K]), "v"(P[K + 1]), "v"(P[K + 2]), "v"(P[K + 3]), "v"(in.w[0]), "v"(in.w[1]), "v"(in.w[2]), "v"(in.w[3]), "v"(in.b[0]), "v"(in.b[1]), "v"(in.b[2]), "v"(in.b[3]), "v"(sa), "n"(N0));
;         P[K] = u0; P[K + 1] = u1; P[K + 2] = u2; P[K + 3] = u3;
;         if constexpr (K + 4 < 64) ScanK<K + 4>::updP(P, in, sa);
;     }
	s_nop 1
	v_mfma_f32_4x4x1_16b_f32 v[0:3], v128, v232, v[0:3]
	v_mfma_f32_4x4x1_16b_f32 v[4:7], v129, v232, v[4:7]
	v_mfma_f32_4x4x1_16b_f32 v[8:11], v130, v232, v[8:11]
	v_mfma_f32_4x4x1_16b_f32 v[12:15], v131, v232, v[12:15]
	v_mfma_f32_4x4x1_16b_f32 v[16:19], v132, v232, v[16:19]
	v_mfma_f32_4x4x1_16b_f32 v[20:23], v133, v232, v[20:23]
	v_mfma_f32_4x4x1_16b_f32 v[24:27], v134, v232, v[24:27]
	v_mfma_f32_4x4x1_16b_f32 v[28:31], v135, v232, v[28:31]
	v_mfma_f32_4x4x1_16b_f32 v[32:35], v136, v232, v[32:35]
	v_mfma_f32_4x4x1_16b_f32 v[36:39], v137, v232, v[36:39]
	v_mfma_f32_4x4x1_16b_f32 v[40:43], v138, v232, v[40:43]
	v_mfma_f32_4x4x1_16b_f32 v[44:47], v139, v232, v[44:47]
	v_mfma_f32_4x4x1_16b_f32 v[48:51], v140, v232, v[48:51]
	v_mfma_f32_4x4x1_16b_f32 v[52:55], v141, v232, v[52:55]
	v_mfma_f32_4x4x1_16b_f32 v[56:59], v142, v232, v[56:59]
	v_mfma_f32_4x4x1_16b_f32 v[60:63], v143, v232, v[60:63]
	v_mfma_f32_4x4x1_16b_f32 v[0:3], v144, v234, v[0:3]
	v_mfma_f32_4x4x1_16b_f32 v[4:7], v145, v234, v[4:7]
	v_mfma_f32_4x4x1_16b_f32 v[8:11], v146, v234, v[8:11]
	v_mfma_f32_4x4x1_16b_f32 v[12:15], v147, v234, v[12:15]
	v_mfma_f32_4x4x1_16b_f32 v[16:19], v148, v234, v[16:19]
	v_mfma_f32_4x4x1_16b_f32 v[20:23], v149, v234, v[20:23]
	v_mfma_f32_4x4x1_16b_f32 v[24:27], v150, v234, v[24:27]
	v_mfma_f32_4x4x1_16b_f32 v[28:31], v151, v234, v[28:31]
	v_mfma_f32_4x4x1_16b_f32 v[32:35], v152, v234, v[32:35]
	v_mfma_f32_4x4x1_16b_f32 v[36:39], v153, v234, v[36:39]
	v_mfma_f32_4x4x1_16b_f32 v[40:43], v154, v234, v[40:43]
	v_mfma_f32_4x4x1_16b_f32 v[44:47], v155, v234, v[44:47]
	v_mfma_f32_4x4x1_16b_f32 v[48:51], v156, v234, v[48:51]
	v_mfma_f32_4x4x1_16b_f32 v[52:55], v157, v234, v[52:55]
	v_mfma_f32_4x4x1_16b_f32 v[56:59], v158, v234, v[56:59]
	v_mfma_f32_4x4x1_16b_f32 v[60:63], v159, v234, v[60:63]
	v_mfma_f32_4x4x1_16b_f32 v[64:67], v128, v233, v[64:67]
	v_mfma_f32_4x4x1_16b_f32 v[68:71], v129, v233, v[68:71]
	v_mfma_f32_4x4x1_16b_f32 v[72:75], v130, v233, v[72:75]
	v_mfma_f32_4x4x1_16b_f32 v[76:79], v131, v233, v[76:79]
	v_mfma_f32_4x4x1_16b_f32 v[80:83], v132, v233, v[80:83]
	v_mfma_f32_4x4x1_16b_f32 v[84:87], v133, v233, v[84:87]
	v_mfma_f32_4x4x1_16b_f32 v[88:91], v134, v233, v[88:91]
	v_mfma_f32_4x4x1_16b_f32 v[92:95], v135, v233, v[92:95]
	v_mfma_f32_4x4x1_16b_f32 v[96:99], v136, v233, v[96:99]
	v_mfma_f32_4x4x1_16b_f32 v[100:103], v137, v233, v[100:103]
	v_mfma_f32_4x4x1_16b_f32 v[104:107], v138, v233, v[104:107]
	v_mfma_f32_4x4x1_16b_f32 v[108:111], v139, v233, v[108:111]
	v_mfma_f32_4x4x1_16b_f32 v[112:115], v140, v233, v[112:115]
	v_mfma_f32_4x4x1_16b_f32 v[116:119], v141, v233, v[116:119]
	v_mfma_f32_4x4x1_16b_f32 v[120:123], v142, v233, v[120:123]
	v_mfma_f32_4x4x1_16b_f32 v[124:127], v143, v233, v[124:127]
	s_waitcnt vmcnt(5)
	buffer_load_dwordx4 v[160:163], v235, s[64:67], s72 offen
	buffer_load_dwordx4 v[164:167], v250, s[64:67], s72 offen
	buffer_load_dwordx4 v[168:171], v251, s[64:67], s72 offen
	buffer_load_dwordx2 v[172:173], v252, s[64:67], s76 offen
	buffer_load_ushort v174, v253, s[64:67], s76 offen
	s_add_u32 s72, s72, 0x1000
	s_add_u32 s76, s76, 0x800
	v_pk_mul_f32 v[244:245], v[180:181], v[236:237]
	v_pk_mul_f32 v[246:247], v[182:183], v[238:239]
	v_pk_mul_f32 v[236:237], v[236:237], v[176:177]
	v_pk_mul_f32 v[238:239], v[238:239], v[178:179]
	v_pk_fma_f32 v[228:229], v[184:185], v[216:217], v[220:221]
	v_pk_fma_f32 v[230:231], v[186:187], v[218:219], v[222:223]
	v_pk_mul_f32 v[208:209], v[180:181], v[184:185]
	v_pk_mul_f32 v[210:211], v[182:183], v[186:187]
	v_rcp_f32_e32 v240, v236
	v_rcp_f32_e32 v241, v237
	v_rcp_f32_e32 v242, v238
	v_rcp_f32_e32 v243, v239
	v_lshlrev_b32_e32 v212, 16, v188
	v_and_b32_e32 v213, 0xffff0000, v188
	v_lshlrev_b32_e32 v214, 16, v189
	v_and_b32_e32 v215, 0xffff0000, v189
	v_pk_mul_f32 v[212:213], v[212:213], v[228:229]
	v_pk_mul_f32 v[214:215], v[214:215], v[230:231]
	v_lshlrev_b32_e32 v234, 16, v190
	v_pk_mul_f32 v[208:209], v[208:209], v[240:241]
	v_pk_mul_f32 v[210:211], v[210:211], v[242:243]
	v_pk_mul_f32 v[212:213], v[212:213], v[240:241]
	v_pk_mul_f32 v[214:215], v[214:215], v[242:243]
	ds_write2_b32 v248, v208, v209 offset0:0 offset1:16
	ds_write2_b32 v248, v210, v211 offset0:32 offset1:48
	ds_write2_b32 v248, v212, v213 offset0:64 offset1:80
	ds_write2_b32 v248, v214, v215 offset0:96 offset1:112
	ds_read_b128 v[128:131], v249 offset:0
	ds_read_b128 v[132:135], v249 offset:16
	ds_read_b128 v[136:139], v249 offset:32
	ds_read_b128 v[140:143], v249 offset:48
	ds_read_b128 v[144:147], v249 offset:256
	ds_read_b128 v[148:151], v249 offset:272
	ds_read_b128 v[152:155], v249 offset:288
	ds_read_b128 v[156:159], v249 offset:304
	v_mul_f32_dpp v224, v244, v0 row_newbcast:0 row_mask:0xf bank_mask:0xf
	v_mul_f32_dpp v225, v245, v1 row_newbcast:0 row_mask:0xf bank_mask:0xf
	v_fmac_f32_dpp v224, v246, v2 row_newbcast:0 row_mask:0xf bank_mask:0xf
	v_fmac_f32_dpp v225, v247, v3 row_newbcast:0 row_mask:0xf bank_mask:0xf
	v_fmac_f32_dpp v224, v244, v4 row_newbcast:1 row_mask:0xf bank_mask:0xf
	v_fmac_f32_dpp v225, v245, v5 row_newbcast:1 row_mask:0xf bank_mask:0xf
	v_fmac_f32_dpp v224, v246, v6 row_newbcast:1 row_mask:0xf bank_mask:0xf
	v_fmac_f32_dpp v225, v247, v7 row_newbcast:1 row_mask:0xf bank_mask:0xf
	v_fmac_f32_dpp v224, v244, v8 row_newbcast:2 row_mask:0xf bank_mask:0xf
	v_fmac_f32_dpp v225, v245, v9 row_newbcast:2 row_mask:0xf bank_mask:0xf
	v_fmac_f32_dpp v224, v246, v10 row_newbcast:2 row_mask:0xf bank_mask:0xf
	v_fmac_f32_dpp v225, v247, v11 row_newbcast:2 row_mask:0xf bank_mask:0xf
	v_fmac_f32_dpp v224, v244, v12 row_newbcast:3 row_mask:0xf bank_mask:0xf
;     static __device__ __forceinline__ void dot(const float (&S)[64], const f32x4& a, float (&s)[4]) {
;         if constexpr (K == 0) {
;             asm volatile("v_mul_f32_dpp %0, %4, %8 row_newbcast:%16" DPPM "v_mul_f32_dpp %1, %5, %9 row_newbcast:%16" DPPM "v_mul_f32_dpp %2, %6, %10 row_newbcast:%16" DPPM "v_mul_f32_dpp %3, %7, %11 row_newbcast:%16" DPPM
;                          "v_fmac_f32_dpp %0, %4, %12 row_newbcast:%17" DPPM "v_fmac_f32_dpp %1, %5, %13 row_newbcast:%17" DPPM "v_fmac_f32_dpp %2, %6, %14 row_newbcast:%17" DPPM "v_fmac_f32_dpp %3, %7, %15 row_newbcast:%17" DPPM
;                          : "=&v"(s[0]), "=&v"(s[1]), "=&v"(s[2]), "=&v"(s[3])
;                          : "v"(a[0]), "v"(a[1]), "v"(a[2]), "v"(a[3]), "v"(S[K]), "v"(S[K + 1]), "v"(S[K + 2]), "v"(S[K + 3]), "v"(S[K + 4]), "v"(S[K + 5]), "v"(S[K + 6]), "v"(S[K + 7]), "n"(N0), "n"(N1));
;         } else
;         asm volatile("v_fmac_f32_dpp %0, %4, %8 row_newbcast:%16" DPPM "v_fmac_f32_dpp %1, %5, %9 row_newbcast:%16" DPPM "v_fmac_f32_dpp %2, %6, %10 row_newbcast:%16" DPPM "v_fmac_f32_dpp %3, %7, %11 row_newbcast:%16" DPPM
;                      "v_fmac_f32_dpp %0, %4, %12 row_newbcast:%17" DPPM "v_fmac_f32_dpp %1, %5, %13 row_newbcast:%17" DPPM "v_fmac_f32_dpp %2, %6, %14 row_newbcast:%17" DPPM "v_fmac_f32_dpp %3, %7, %15 row_newbcast:%17" DPPM
;                      : "+v"(s[0]), "+v"(s[1]), "+v"(s[2]), "+v"(s[3])
;                      : "v"(a[0]), "v"(a[1]), "v"(a[2]), "v"(a[3]), "v"(S[K]), "v"(S[K + 1]), "v"(S[K + 2]), "v"(S[K + 3]), "v"(S[K + 4]), "v"(S[K + 5]), "v"(S[K + 6]), "v"(S[K + 7]), "n"(N0), "n"(N1));
;         if constexpr (K + 8 < 64) ScanK<K + 8>::dot(S, a, s);
	v_fmac_f32_dpp v225, v245, v13 row_newbcast:3 row_mask:0xf bank_mask:0xf
	v_fmac_f32_dpp v224, v246, v14 row_newbcast:3 row_mask:0xf bank_mask:0xf
	v_fmac_f32_dpp v225, v247, v15 row_newbcast:3 row_mask:0xf bank_mask:0xf
	v_fmac_f32_dpp v224, v244, v16 row_newbcast:4 row_mask:0xf bank_mask:0xf
	v_fmac_f32_dpp v225, v245, v17 row_newbcast:4 row_mask:0xf bank_mask:0xf
	v_fmac_f32_dpp v224, v246, v18 row_newbcast:4 row_mask:0xf bank_mask:0xf
	v_fmac_f32_dpp v225, v247, v19 row_newbcast:4 row_mask:0xf bank_mask:0xf
	v_fmac_f32_dpp v224, v244, v20 row_newbcast:5 row_mask:0xf bank_mask:0xf
	v_fmac_f32_dpp v225, v245, v21 row_newbcast:5 row_mask:0xf bank_mask:0xf
	v_fmac_f32_dpp v224, v246, v22 row_newbcast:5 row_mask:0xf bank_mask:0xf
	v_fmac_f32_dpp v225, v247, v23 row_newbcast:5 row_mask:0xf bank_mask:0xf
	v_fmac_f32_dpp v224, v244, v24 row_newbcast:6 row_mask:0xf bank_mask:0xf
	v_fmac_f32_dpp v225, v245, v25 row_newbcast:6 row_mask:0xf bank_mask:0xf
	v_fmac_f32_dpp v224, v246, v26 row_newbcast:6 row_mask:0xf bank_mask:0xf
	v_fmac_f32_dpp v225, v247, v27 row_newbcast:6 row_mask:0xf bank_mask:0xf
	v_fmac_f32_dpp v224, v244, v28 row_newbcast:7 row_mask:0xf bank_mask:0xf
	v_fmac_f32_dpp v225, v245, v29 row_newbcast:7 row_mask:0xf bank_mask:0xf
	v_fmac_f32_dpp v224, v246, v30 row_newbcast:7 row_mask:0xf bank_mask:0xf
	v_fmac_f32_dpp v225, v247, v31 row_newbcast:7 row_mask:0xf bank_mask:0xf
	v_fmac_f32_dpp v224, v244, v32 row_newbcast:8 row_mask:0xf bank_mask:0xf
	v_fmac_f32_dpp v225, v245, v33 row_newbcast:8 row_mask:0xf bank_mask:0xf
	v_fmac_f32_dpp v224, v246, v34 row_newbcast:8 row_mask:0xf bank_mask:0xf
	v_fmac_f32_dpp v225, v247, v35 row_newbcast:8 row_mask:0xf bank_mask:0xf
	v_fmac_f32_dpp v224, v244, v36 row_newbcast:9 row_mask:0xf bank_mask:0xf
	v_fmac_f32_dpp v225, v245, v37 row_newbcast:9 row_mask:0xf bank_mask:0xf
	v_fmac_f32_dpp v224, v246, v38 row_newbcast:9 row_mask:0xf bank_mask:0xf
	v_fmac_f32_dpp v225, v247, v39 row_newbcast:9 row_mask:0xf bank_mask:0xf
	v_fmac_f32_dpp v224, v244, v40 row_newbcast:10 row_mask:0xf bank_mask:0xf
	v_fmac_f32_dpp v225, v245, v41 row_newbcast:10 row_mask:0xf bank_mask:0xf
	v_fmac_f32_dpp v224, v246, v42 row_newbcast:10 row_mask:0xf bank_mask:0xf
	v_fmac_f32_dpp v225, v247, v43 row_newbcast:10 row_mask:0xf bank_mask:0xf
	v_fmac_f32_dpp v224, v244, v44 row_newbcast:11 row_mask:0xf bank_mask:0xf
	v_fmac_f32_dpp v225, v245, v45 row_newbcast:11 row_mask:0xf bank_mask:0xf
	v_fmac_f32_dpp v224, v246, v46 row_newbcast:11 row_mask:0xf bank_mask:0xf
	v_fmac_f32_dpp v225, v247, v47 row_newbcast:11 row_mask:0xf bank_mask:0xf
	v_fmac_f32_dpp v224, v244, v48 row_newbcast:12 row_mask:0xf bank_mask:0xf
	v_fmac_f32_dpp v225, v245, v49 row_newbcast:12 row_mask:0xf bank_mask:0xf
	v_fmac_f32_dpp v224, v246, v50 row_newbcast:12 row_mask:0xf bank_mask:0xf
	v_fmac_f32_dpp v225, v247, v51 row_newbcast:12 row_mask:0xf bank_mask:0xf
	v_fmac_f32_dpp v224, v244, v52 row_newbcast:13 row_mask:0xf bank_mask:0xf
	v_fmac_f32_dpp v225, v245, v53 row_newbcast:13 row_mask:0xf bank_mask:0xf
	v_fmac_f32_dpp v224, v246, v54 row_newbcast:13 row_mask:0xf bank_mask:0xf
	v_fmac_f32_dpp v225, v247, v55 row_newbcast:13 row_mask:0xf bank_mask:0xf
	v_fmac_f32_dpp v224, v244, v56 row_newbcast:14 row_mask:0xf bank_mask:0xf
	v_fmac_f32_dpp v225, v245, v57 row_newbcast:14 row_mask:0xf bank_mask:0xf
	v_fmac_f32_dpp v224, v246, v58 row_newbcast:14 row_mask:0xf bank_mask:0xf
	v_fmac_f32_dpp v225, v247, v59 row_newbcast:14 row_mask:0xf bank_mask:0xf
	v_fmac_f32_dpp v224, v244, v60 row_newbcast:15 row_mask:0xf bank_mask:0xf
	v_fmac_f32_dpp v225, v245, v61 row_newbcast:15 row_mask:0xf bank_mask:0xf
	v_fmac_f32_dpp v224, v246, v62 row_newbcast:15 row_mask:0xf bank_mask:0xf
	v_fmac_f32_dpp v225, v247, v63 row_newbcast:15 row_mask:0xf bank_mask:0xf
	v_mul_f32_dpp v228, v244, v64 row_newbcast:0 row_mask:0xf bank_mask:0xf
	v_mul_f32_dpp v229, v245, v65 row_newbcast:0 row_mask:0xf bank_mask:0xf
	v_fmac_f32_dpp v228, v246, v66 row_newbcast:0 row_mask:0xf bank_mask:0xf
	v_fmac_f32_dpp v229, v247, v67 row_newbcast:0 row_mask:0xf bank_mask:0xf
	v_fmac_f32_dpp v228, v244, v68 row_newbcast:1 row_mask:0xf bank_mask:0xf
	v_fmac_f32_dpp v229, v245, v69 row_newbcast:1 row_mask:0xf bank_mask:0xf
	v_fmac_f32_dpp v228, v246, v70 row_newbcast:1 row_mask:0xf bank_mask:0xf
	v_fmac_f32_dpp v229, v247, v71 row_newbcast:1 row_mask:0xf bank_mask:0xf
	v_fmac_f32_dpp v228, v244, v72 row_newbcast:2 row_mask:0xf bank_mask:0xf
	v_fmac_f32_dpp v229, v245, v73 row_newbcast:2 row_mask:0xf bank_mask:0xf
	v_fmac_f32_dpp v228, v246, v74 row_newbcast:2 row_mask:0xf bank_mask:0xf
	v_fmac_f32_dpp v229, v247, v75 row_newbcast:2 row_mask:0xf bank_mask:0xf
	v_fmac_f32_dpp v228, v244, v76 row_newbcast:3 row_mask:0xf bank_mask:0xf
	v_fmac_f32_dpp v229, v245, v77 row_newbcast:3 row_mask:0xf bank_mask:0xf
	v_fmac_f32_dpp v228, v246, v78 row_newbcast:3 row_mask:0xf bank_mask:0xf
	v_fmac_f32_dpp v229, v247, v79 row_newbcast:3 row_mask:0xf bank_mask:0xf
	v_fmac_f32_dpp v228, v244, v80 row_newbcast:4 row_mask:0xf bank_mask:0xf
	v_fmac_f32_dpp v229, v245, v81 row_newbcast:4 row_mask:0xf bank_mask:0xf
	v_fmac_f32_dpp v228, v246, v82 row_newbcast:4 row_mask:0xf bank_mask:0xf
	v_fmac_f32_dpp v229, v247, v83 row_newbcast:4 row_mask:0xf bank_mask:0xf
	v_fmac_f32_dpp v228, v244, v84 row_newbcast:5 row_mask:0xf bank_mask:0xf
	v_fmac_f32_dpp v229, v245, v85 row_newbcast:5 row_mask:0xf bank_mask:0xf
	v_fmac_f32_dpp v228, v246, v86 row_newbcast:5 row_mask:0xf bank_mask:0xf
	v_fmac_f32_dpp v229, v247, v87 row_newbcast:5 row_mask:0xf bank_mask:0xf
	v_fmac_f32_dpp v228, v244, v88 row_newbcast:6 row_mask:0xf bank_mask:0xf
;     static __device__ __forceinline__ void dot(const float (&S)[64], const f32x4& a, float (&s)[4]) {
;         if constexpr (K == 0) {
;             asm volatile("v_mul_f32_dpp %0, %4, %8 row_newbcast:%16" DPPM "v_mul_f32_dpp %1, %5, %9 row_newbcast:%16" DPPM "v_mul_f32_dpp %2, %6, %10 row_newbcast:%16" DPPM "v_mul_f32_dpp %3, %7, %11 row_newbcast:%16" DPPM
;                          "v_fmac_f32_dpp %0, %4, %12 row_newbcast:%17" DPPM "v_fmac_f32_dpp %1, %5, %13 row_newbcast:%17" DPPM "v_fmac_f32_dpp %2, %6, %14 row_newbcast:%17" DPPM "v_fmac_f32_dpp %3, %7, %15 row_newbcast:%17" DPPM
;                          : "=&v"(s[0]), "=&v"(s[1]), "=&v"(s[2]), "=&v"(s[3])
;                          : "v"(a[0]), "v"(a[1]), "v"(a[2]), "v"(a[3]), "v"(S[K]), "v"(S[K + 1]), "v"(S[K + 2]), "v"(S[K + 3]), "v"(S[K + 4]), "v"(S[K + 5]), "v"(S[K + 6]), "v"(S[K + 7]), "n"(N0), "n"(N1));
;         } else
;         asm volatile("v_fmac_f32_dpp %0, %4, %8 row_newbcast:%16" DPPM "v_fmac_f32_dpp %1, %5, %9 row_newbcast:%16" DPPM "v_fmac_f32_dpp %2, %6, %10 row_newbcast:%16" DPPM "v_fmac_f32_dpp %3, %7, %11 row_newbcast:%16" DPPM
;                      "v_fmac_f32_dpp %0, %4, %12 row_newbcast:%17" DPPM "v_fmac_f32_dpp %1, %5, %13 row_newbcast:%17" DPPM "v_fmac_f32_dpp %2, %6, %14 row_newbcast:%17" DPPM "v_fmac_f32_dpp %3, %7, %15 row_newbcast:%17" DPPM
;                      : "+v"(s[0]), "+v"(s[1]), "+v"(s[2]), "+v"(s[3])
;                      : "v"(a[0]), "v"(a[1]), "v"(a[2]), "v"(a[3]), "v"(S[K]), "v"(S[K + 1]), "v"(S[K + 2]), "v"(S[K + 3]), "v"(S[K + 4]), "v"(S[K + 5]), "v"(S[K + 6]), "v"(S[K + 7]), "n"(N0), "n"(N1));
;         if constexpr (K + 8 < 64) ScanK<K + 8>::dot(S, a, s);
;     }
;     static __device__ __forceinline__ void upd(float (&S)[64], const In2& in, float sa, float vv, float& y0, float& y1) {
;         float t0, t1, t2, t3;
;         asm volatile("v_mul_f32_dpp %0, %10, %27 row_newbcast:%28" DPPM "v_mul_f32_dpp %1, %11, %27 row_newbcast:%28" DPPM "v_mul_f32_dpp %2, %12, %27 row_newbcast:%28" DPPM "v_mul_f32_dpp %3, %13, %27 row_newbcast:%28" DPPM
;                      "v_fmac_f32_dpp %0, %14, %6 row_newbcast:%28" DPPM "v_fmac_f32_dpp %1, %15, %7 row_newbcast:%28" DPPM "v_fmac_f32_dpp %2, %16, %8 row_newbcast:%28" DPPM "v_fmac_f32_dpp %3, %17, %9 row_newbcast:%28" DPPM
	v_fmac_f32_dpp v229, v245, v89 row_newbcast:6 row_mask:0xf bank_mask:0xf
	v_fmac_f32_dpp v228, v246, v90 row_newbcast:6 row_mask:0xf bank_mask:0xf
	v_fmac_f32_dpp v229, v247, v91 row_newbcast:6 row_mask:0xf bank_mask:0xf
	v_fmac_f32_dpp v228, v244, v92 row_newbcast:7 row_mask:0xf bank_mask:0xf
	v_fmac_f32_dpp v229, v245, v93 row_newbcast:7 row_mask:0xf bank_mask:0xf
	v_fmac_f32_dpp v228, v246, v94 row_newbcast:7 row_mask:0xf bank_mask:0xf
	v_fmac_f32_dpp v229, v247, v95 row_newbcast:7 row_mask:0xf bank_mask:0xf
	v_fmac_f32_dpp v228, v244, v96 row_newbcast:8 row_mask:0xf bank_mask:0xf
	v_fmac_f32_dpp v229, v245, v97 row_newbcast:8 row_mask:0xf bank_mask:0xf
	v_fmac_f32_dpp v228, v246, v98 row_newbcast:8 row_mask:0xf bank_mask:0xf
	v_fmac_f32_dpp v229, v247, v99 row_newbcast:8 row_mask:0xf bank_mask:0xf
	v_fmac_f32_dpp v228, v244, v100 row_newbcast:9 row_mask:0xf bank_mask:0xf
	v_fmac_f32_dpp v229, v245, v101 row_newbcast:9 row_mask:0xf bank_mask:0xf
	v_fmac_f32_dpp v228, v246, v102 row_newbcast:9 row_mask:0xf bank_mask:0xf
	v_fmac_f32_dpp v229, v247, v103 row_newbcast:9 row_mask:0xf bank_mask:0xf
	v_fmac_f32_dpp v228, v244, v104 row_newbcast:10 row_mask:0xf bank_mask:0xf
	v_fmac_f32_dpp v229, v245, v105 row_newbcast:10 row_mask:0xf bank_mask:0xf
	v_fmac_f32_dpp v228, v246, v106 row_newbcast:10 row_mask:0xf bank_mask:0xf
	v_fmac_f32_dpp v229, v247, v107 row_newbcast:10 row_mask:0xf bank_mask:0xf
	v_fmac_f32_dpp v228, v244, v108 row_newbcast:11 row_mask:0xf bank_mask:0xf
	v_fmac_f32_dpp v229, v245, v109 row_newbcast:11 row_mask:0xf bank_mask:0xf
	v_fmac_f32_dpp v228, v246, v110 row_newbcast:11 row_mask:0xf bank_mask:0xf
	v_fmac_f32_dpp v229, v247, v111 row_newbcast:11 row_mask:0xf bank_mask:0xf
	v_fmac_f32_dpp v228, v244, v112 row_newbcast:12 row_mask:0xf bank_mask:0xf
	v_fmac_f32_dpp v229, v245, v113 row_newbcast:12 row_mask:0xf bank_mask:0xf
	v_fmac_f32_dpp v228, v246, v114 row_newbcast:12 row_mask:0xf bank_mask:0xf
	v_fmac_f32_dpp v229, v247, v115 row_newbcast:12 row_mask:0xf bank_mask:0xf
	v_fmac_f32_dpp v228, v244, v116 row_newbcast:13 row_mask:0xf bank_mask:0xf
	v_fmac_f32_dpp v229, v245, v117 row_newbcast:13 row_mask:0xf bank_mask:0xf
	v_fmac_f32_dpp v228, v246, v118 row_newbcast:13 row_mask:0xf bank_mask:0xf
	v_fmac_f32_dpp v229, v247, v119 row_newbcast:13 row_mask:0xf bank_mask:0xf
	v_fmac_f32_dpp v228, v244, v120 row_newbcast:14 row_mask:0xf bank_mask:0xf
	v_fmac_f32_dpp v229, v245, v121 row_newbcast:14 row_mask:0xf bank_mask:0xf
	v_fmac_f32_dpp v228, v246, v122 row_newbcast:14 row_mask:0xf bank_mask:0xf
	v_fmac_f32_dpp v229, v247, v123 row_newbcast:14 row_mask:0xf bank_mask:0xf
	v_fmac_f32_dpp v228, v244, v124 row_newbcast:15 row_mask:0xf bank_mask:0xf
	v_fmac_f32_dpp v229, v245, v125 row_newbcast:15 row_mask:0xf bank_mask:0xf
	v_fmac_f32_dpp v228, v246, v126 row_newbcast:15 row_mask:0xf bank_mask:0xf
	v_fmac_f32_dpp v229, v247, v127 row_newbcast:15 row_mask:0xf bank_mask:0xf
	v_sub_f32_e64 v232, -v224, v225
	v_sub_f32_e64 v233, -v228, v229
	s_waitcnt lgkmcnt(0)
	s_nop 1
	v_mfma_f32_4x4x1_16b_f32 v[0:3], v128, v232, v[0:3]
	v_mfma_f32_4x4x1_16b_f32 v[4:7], v129, v232, v[4:7]
	v_mfma_f32_4x4x1_16b_f32 v[8:11], v130, v232, v[8:11]
	v_mfma_f32_4x4x1_16b_f32 v[12:15], v131, v232, v[12:15]
	v_mfma_f32_4x4x1_16b_f32 v[16:19], v132, v232, v[16:19]
	v_mfma_f32_4x4x1_16b_f32 v[20:23], v133, v232, v[20:23]
	v_mfma_f32_4x4x1_16b_f32 v[24:27], v134, v232, v[24:27]
	v_mfma_f32_4x4x1_16b_f32 v[28:31], v135, v232, v[28:31]
	v_mfma_f32_4x4x1_16b_f32 v[32:35], v136, v232, v[32:35]
	v_mfma_f32_4x4x1_16b_f32 v[36:39], v137, v232, v[36:39]
	v_mfma_f32_4x4x1_16b_f32 v[40:43], v138, v232, v[40:43]
	v_mfma_f32_4x4x1_16b_f32 v[44:47], v139, v232, v[44:47]
	v_mfma_f32_4x4x1_16b_f32 v[48:51], v140, v232, v[48:51]
	v_mfma_f32_4x4x1_16b_f32 v[52:55], v141, v232, v[52:55]
	v_mfma_f32_4x4x1_16b_f32 v[56:59], v142, v232, v[56:59]
	v_mfma_f32_4x4x1_16b_f32 v[60:63], v143, v232, v[60:63]
	v_mfma_f32_4x4x1_16b_f32 v[0:3], v144, v234, v[0:3]
	v_mfma_f32_4x4x1_16b_f32 v[4:7], v145, v234, v[4:7]
	v_mfma_f32_4x4x1_16b_f32 v[8:11], v146, v234, v[8:11]
	v_mfma_f32_4x4x1_16b_f32 v[12:15], v147, v234, v[12:15]
	v_mfma_f32_4x4x1_16b_f32 v[16:19], v148, v234, v[16:19]
	v_mfma_f32_4x4x1_16b_f32 v[20:23], v149, v234, v[20:23]
	v_mfma_f32_4x4x1_16b_f32 v[24:27], v150, v234, v[24:27]
	v_mfma_f32_4x4x1_16b_f32 v[28:31], v151, v234, v[28:31]
	v_mfma_f32_4x4x1_16b_f32 v[32:35], v152, v234, v[32:35]
	v_mfma_f32_4x4x1_16b_f32 v[36:39], v153, v234, v[36:39]
	v_mfma_f32_4x4x1_16b_f32 v[40:43], v154, v234, v[40:43]
	v_mfma_f32_4x4x1_16b_f32 v[44:47], v155, v234, v[44:47]
	v_mfma_f32_4x4x1_16b_f32 v[48:51], v156, v234, v[48:51]
	v_mfma_f32_4x4x1_16b_f32 v[52:55], v157, v234, v[52:55]
	v_mfma_f32_4x4x1_16b_f32 v[56:59], v158, v234, v[56:59]
	v_mfma_f32_4x4x1_16b_f32 v[60:63], v159, v234, v[60:63]
	v_mfma_f32_4x4x1_16b_f32 v[64:67], v128, v233, v[64:67]
	v_mfma_f32_4x4x1_16b_f32 v[68:71], v129, v233, v[68:71]
	v_mfma_f32_4x4x1_16b_f32 v[72:75], v130, v233, v[72:75]
	v_mfma_f32_4x4x1_16b_f32 v[76:79], v131, v233, v[76:79]
	v_mfma_f32_4x4x1_16b_f32 v[80:83], v132, v233, v[80:83]
	v_mfma_f32_4x4x1_16b_f32 v[84:87], v133, v233, v[84:87]
	v_mfma_f32_4x4x1_16b_f32 v[88:91], v134, v233, v[88:91]
	v_mfma_f32_4x4x1_16b_f32 v[92:95], v135, v233, v[92:95]
	v_mfma_f32_4x4x1_16b_f32 v[96:99], v136, v233, v[96:99]
	v_mfma_f32_4x4x1_16b_f32 v[100:103], v137, v233, v[100:103]
	v_mfma_f32_4x4x1_16b_f32 v[104:107], v138, v233, v[104:107]
	v_mfma_f32_4x4x1_16b_f32 v[108:111], v139, v233, v[108:111]
	v_mfma_f32_4x4x1_16b_f32 v[112:115], v140, v233, v[112:115]
	v_mfma_f32_4x4x1_16b_f32 v[116:119], v141, v233, v[116:119]
	v_mfma_f32_4x4x1_16b_f32 v[120:123], v142, v233, v[120:123]
	v_mfma_f32_4x4x1_16b_f32 v[124:127], v143, v233, v[124:127]
	s_waitcnt vmcnt(5)
;     static __device__ __forceinline__ void dot(const float (&S)[64], const f32x4& a, float (&s)[4]) {
;         if constexpr (K == 0) {
;             asm volatile("v_mul_f32_dpp %0, %4, %8 row_newbcast:%16" DPPM "v_mul_f32_dpp %1, %5, %9 row_newbcast:%16" DPPM "v_mul_f32_dpp %2, %6, %10 row_newbcast:%16" DPPM "v_mul_f32_dpp %3, %7, %11 row_newbcast:%16" DPPM
;                          "v_fmac_f32_dpp %0, %4, %12 row_newbcast:%17" DPPM "v_fmac_f32_dpp %1, %5, %13 row_newbcast:%17" DPPM "v_fmac_f32_dpp %2, %6, %14 row_newbcast:%17" DPPM "v_fmac_f32_dpp %3, %7, %15 row_newbcast:%17" DPPM
;                          : "=&v"(s[0]), "=&v"(s[1]), "=&v"(s[2]), "=&v"(s[3])
;                          : "v"(a[0]), "v"(a[1]), "v"(a[2]), "v"(a[3]), "v"(S[K]), "v"(S[K + 1]), "v"(S[K + 2]), "v"(S[K + 3]), "v"(S[K + 4]), "v"(S[K + 5]), "v"(S[K + 6]), "v"(S[K + 7]), "n"(N0), "n"(N1));
;         } else
;         asm volatile("v_fmac_f32_dpp %0, %4, %8 row_newbcast:%16" DPPM "v_fmac_f32_dpp %1, %5, %9 row_newbcast:%16" DPPM "v_fmac_f32_dpp %2, %6, %10 row_newbcast:%16" DPPM "v_fmac_f32_dpp %3, %7, %11 row_newbcast:%16" DPPM
;                      "v_fmac_f32_dpp %0, %4, %12 row_newbcast:%17" DPPM "v_fmac_f32_dpp %1, %5, %13 row_newbcast:%17" DPPM "v_fmac_f32_dpp %2, %6, %14 row_newbcast:%17" DPPM "v_fmac_f32_dpp %3, %7, %15 row_newbcast:%17" DPPM
;                      : "+v"(s[0]), "+v"(s[1]), "+v"(s[2]), "+v"(s[3])
;                      : "v"(a[0]), "v"(a[1]), "v"(a[2]), "v"(a[3]), "v"(S[K]), "v"(S[K + 1]), "v"(S[K + 2]), "v"(S[K + 3]), "v"(S[K + 4]), "v"(S[K + 5]), "v"(S[K + 6]), "v"(S[K + 7]), "n"(N0), "n"(N1));
;         if constexpr (K + 8 < 64) ScanK<K + 8>::dot(S, a, s);
	buffer_load_dwordx4 v[176:179], v235, s[64:67], s72 offen
	buffer_load_dwordx4 v[180:183], v250, s[64:67], s72 offen
	buffer_load_dwordx4 v[184:187], v251, s[64:67], s72 offen
	buffer_load_dwordx2 v[188:189], v252, s[64:67], s76 offen
	buffer_load_ushort v190, v253, s[64:67], s76 offen
	s_add_u32 s72, s72, 0x1000
	s_add_u32 s76, s76, 0x800
	v_pk_mul_f32 v[244:245], v[196:197], v[236:237]
	v_pk_mul_f32 v[246:247], v[198:199], v[238:239]
	v_pk_mul_f32 v[236:237], v[236:237], v[192:193]
	v_pk_mul_f32 v[238:239], v[238:239], v[194:195]
	v_pk_fma_f32 v[228:229], v[200:201], v[216:217], v[220:221]
	v_pk_fma_f32 v[230:231], v[202:203], v[218:219], v[222:223]
	v_pk_mul_f32 v[208:209], v[196:197], v[200:201]
	v_pk_mul_f32 v[210:211], v[198:199], v[202:203]
	v_rcp_f32_e32 v240, v236
	v_rcp_f32_e32 v241, v237
	v_rcp_f32_e32 v242, v238
	v_rcp_f32_e32 v243, v239
	v_lshlrev_b32_e32 v212, 16, v204
	v_and_b32_e32 v213, 0xffff0000, v204
	v_lshlrev_b32_e32 v214, 16, v205
	v_and_b32_e32 v215, 0xffff0000, v205
	v_pk_mul_f32 v[212:213], v[212:213], v[228:229]
	v_pk_mul_f32 v[214:215], v[214:215], v[230:231]
	v_lshlrev_b32_e32 v234, 16, v206
	v_pk_mul_f32 v[208:209], v[208:209], v[240:241]
	v_pk_mul_f32 v[210:211], v[210:211], v[242:243]
	v_pk_mul_f32 v[212:213], v[212:213], v[240:241]
	v_pk_mul_f32 v[214:215], v[214:215], v[242:243]
	ds_write2_b32 v248, v208, v209 offset0:0 offset1:16
	ds_write2_b32 v248, v210, v211 offset0:32 offset1:48
	ds_write2_b32 v248, v212, v213 offset0:64 offset1:80
	ds_write2_b32 v248, v214, v215 offset0:96 offset1:112
	ds_read_b128 v[128:131], v249 offset:0
	ds_read_b128 v[132:135], v249 offset:16
	ds_read_b128 v[136:139], v249 offset:32
	ds_read_b128 v[140:143], v249 offset:48
	ds_read_b128 v[144:147], v249 offset:256
	ds_read_b128 v[148:151], v249 offset:272
	ds_read_b128 v[152:155], v249 offset:288
	ds_read_b128 v[156:159], v249 offset:304
	v_mul_f32_dpp v224, v244, v0 row_newbcast:0 row_mask:0xf bank_mask:0xf
	v_mul_f32_dpp v225, v245, v1 row_newbcast:0 row_mask:0xf bank_mask:0xf
	v_fmac_f32_dpp v224, v246, v2 row_newbcast:0 row_mask:0xf bank_mask:0xf
	v_fmac_f32_dpp v225, v247, v3 row_newbcast:0 row_mask:0xf bank_mask:0xf
	v_fmac_f32_dpp v224, v244, v4 row_newbcast:1 row_mask:0xf bank_mask:0xf
	v_fmac_f32_dpp v225, v245, v5 row_newbcast:1 row_mask:0xf bank_mask:0xf
	v_fmac_f32_dpp v224, v246, v6 row_newbcast:1 row_mask:0xf bank_mask:0xf
	v_fmac_f32_dpp v225, v247, v7 row_newbcast:1 row_mask:0xf bank_mask:0xf
	v_fmac_f32_dpp v224, v244, v8 row_newbcast:2 row_mask:0xf bank_mask:0xf
	v_fmac_f32_dpp v225, v245, v9 row_newbcast:2 row_mask:0xf bank_mask:0xf
	v_fmac_f32_dpp v224, v246, v10 row_newbcast:2 row_mask:0xf bank_mask:0xf
	v_fmac_f32_dpp v225, v247, v11 row_newbcast:2 row_mask:0xf bank_mask:0xf
	v_fmac_f32_dpp v224, v244, v12 row_newbcast:3 row_mask:0xf bank_mask:0xf
	v_fmac_f32_dpp v225, v245, v13 row_newbcast:3 row_mask:0xf bank_mask:0xf
	v_fmac_f32_dpp v224, v246, v14 row_newbcast:3 row_mask:0xf bank_mask:0xf
	v_fmac_f32_dpp v225, v247, v15 row_newbcast:3 row_mask:0xf bank_mask:0xf
	v_fmac_f32_dpp v224, v244, v16 row_newbcast:4 row_mask:0xf bank_mask:0xf
	v_fmac_f32_dpp v225, v245, v17 row_newbcast:4 row_mask:0xf bank_mask:0xf
	v_fmac_f32_dpp v224, v246, v18 row_newbcast:4 row_mask:0xf bank_mask:0xf
	v_fmac_f32_dpp v225, v247, v19 row_newbcast:4 row_mask:0xf bank_mask:0xf
	v_fmac_f32_dpp v224, v244, v20 row_newbcast:5 row_mask:0xf bank_mask:0xf
	v_fmac_f32_dpp v225, v245, v21 row_newbcast:5 row_mask:0xf bank_mask:0xf
	v_fmac_f32_dpp v224, v246, v22 row_newbcast:5 row_mask:0xf bank_mask:0xf
	v_fmac_f32_dpp v225, v247, v23 row_newbcast:5 row_mask:0xf bank_mask:0xf
	v_fmac_f32_dpp v224, v244, v24 row_newbcast:6 row_mask:0xf bank_mask:0xf
	v_fmac_f32_dpp v225, v245, v25 row_newbcast:6 row_mask:0xf bank_mask:0xf
	v_fmac_f32_dpp v224, v246, v26 row_newbcast:6 row_mask:0xf bank_mask:0xf
	v_fmac_f32_dpp v225, v247, v27 row_newbcast:6 row_mask:0xf bank_mask:0xf
	v_fmac_f32_dpp v224, v244, v28 row_newbcast:7 row_mask:0xf bank_mask:0xf
	v_fmac_f32_dpp v225, v245, v29 row_newbcast:7 row_mask:0xf bank_mask:0xf
	v_fmac_f32_dpp v224, v246, v30 row_newbcast:7 row_mask:0xf bank_mask:0xf
	v_fmac_f32_dpp v225, v247, v31 row_newbcast:7 row_mask:0xf bank_mask:0xf
	v_fmac_f32_dpp v224, v244, v32 row_newbcast:8 row_mask:0xf bank_mask:0xf
	v_fmac_f32_dpp v225, v245, v33 row_newbcast:8 row_mask:0xf bank_mask:0xf
	v_fmac_f32_dpp v224, v246, v34 row_newbcast:8 row_mask:0xf bank_mask:0xf
	v_fmac_f32_dpp v225, v247, v35 row_newbcast:8 row_mask:0xf bank_mask:0xf
	v_fmac_f32_dpp v224, v244, v36 row_newbcast:9 row_mask:0xf bank_mask:0xf
	v_fmac_f32_dpp v225, v245, v37 row_newbcast:9 row_mask:0xf bank_mask:0xf
	v_fmac_f32_dpp v224, v246, v38 row_newbcast:9 row_mask:0xf bank_mask:0xf
	v_fmac_f32_dpp v225, v247, v39 row_newbcast:9 row_mask:0xf bank_mask:0xf
	v_fmac_f32_dpp v224, v244, v40 row_newbcast:10 row_mask:0xf bank_mask:0xf
	v_fmac_f32_dpp v225, v245, v41 row_newbcast:10 row_mask:0xf bank_mask:0xf
	v_fmac_f32_dpp v224, v246, v42 row_newbcast:10 row_mask:0xf bank_mask:0xf
	v_fmac_f32_dpp v225, v247, v43 row_newbcast:10 row_mask:0xf bank_mask:0xf
	v_fmac_f32_dpp v224, v244, v44 row_newbcast:11 row_mask:0xf bank_mask:0xf
	v_fmac_f32_dpp v225, v245, v45 row_newbcast:11 row_mask:0xf bank_mask:0xf
	v_fmac_f32_dpp v224, v246, v46 row_newbcast:11 row_mask:0xf bank_mask:0xf
	v_fmac_f32_dpp v225, v247, v47 row_newbcast:11 row_mask:0xf bank_mask:0xf
	v_fmac_f32_dpp v224, v244, v48 row_newbcast:12 row_mask:0xf bank_mask:0xf
	v_fmac_f32_dpp v225, v245, v49 row_newbcast:12 row_mask:0xf bank_mask:0xf
	v_fmac_f32_dpp v224, v246, v50 row_newbcast:12 row_mask:0xf bank_mask:0xf
;     static __device__ __forceinline__ void dot(const float (&S)[64], const f32x4& a, float (&s)[4]) {
;         if constexpr (K == 0) {
;             asm volatile("v_mul_f32_dpp %0, %4, %8 row_newbcast:%16" DPPM "v_mul_f32_dpp %1, %5, %9 row_newbcast:%16" DPPM "v_mul_f32_dpp %2, %6, %10 row_newbcast:%16" DPPM "v_mul_f32_dpp %3, %7, %11 row_newbcast:%16" DPPM
;                          "v_fmac_f32_dpp %0, %4, %12 row_newbcast:%17" DPPM "v_fmac_f32_dpp %1, %5, %13 row_newbcast:%17" DPPM "v_fmac_f32_dpp %2, %6, %14 row_newbcast:%17" DPPM "v_fmac_f32_dpp %3, %7, %15 row_newbcast:%17" DPPM
;                          : "=&v"(s[0]), "=&v"(s[1]), "=&v"(s[2]), "=&v"(s[3])
;                          : "v"(a[0]), "v"(a[1]), "v"(a[2]), "v"(a[3]), "v"(S[K]), "v"(S[K + 1]), "v"(S[K + 2]), "v"(S[K + 3]), "v"(S[K + 4]), "v"(S[K + 5]), "v"(S[K + 6]), "v"(S[K + 7]), "n"(N0), "n"(N1));
;         } else
;         asm volatile("v_fmac_f32_dpp %0, %4, %8 row_newbcast:%16" DPPM "v_fmac_f32_dpp %1, %5, %9 row_newbcast:%16" DPPM "v_fmac_f32_dpp %2, %6, %10 row_newbcast:%16" DPPM "v_fmac_f32_dpp %3, %7, %11 row_newbcast:%16" DPPM
;                      "v_fmac_f32_dpp %0, %4, %12 row_newbcast:%17" DPPM "v_fmac_f32_dpp %1, %5, %13 row_newbcast:%17" DPPM "v_fmac_f32_dpp %2, %6, %14 row_newbcast:%17" DPPM "v_fmac_f32_dpp %3, %7, %15 row_newbcast:%17" DPPM
;                      : "+v"(s[0]), "+v"(s[1]), "+v"(s[2]), "+v"(s[3])
;                      : "v"(a[0]), "v"(a[1]), "v"(a[2]), "v"(a[3]), "v"(S[K]), "v"(S[K + 1]), "v"(S[K + 2]), "v"(S[K + 3]), "v"(S[K + 4]), "v"(S[K + 5]), "v"(S[K + 6]), "v"(S[K + 7]), "n"(N0), "n"(N1));
;         if constexpr (K + 8 < 64) ScanK<K + 8>::dot(S, a, s);
	v_fmac_f32_dpp v225, v247, v51 row_newbcast:12 row_mask:0xf bank_mask:0xf
	v_fmac_f32_dpp v224, v244, v52 row_newbcast:13 row_mask:0xf bank_mask:0xf
	v_fmac_f32_dpp v225, v245, v53 row_newbcast:13 row_mask:0xf bank_mask:0xf
	v_fmac_f32_dpp v224, v246, v54 row_newbcast:13 row_mask:0xf bank_mask:0xf
	v_fmac_f32_dpp v225, v247, v55 row_newbcast:13 row_mask:0xf bank_mask:0xf
	v_fmac_f32_dpp v224, v244, v56 row_newbcast:14 row_mask:0xf bank_mask:0xf
	v_fmac_f32_dpp v225, v245, v57 row_newbcast:14 row_mask:0xf bank_mask:0xf
	v_fmac_f32_dpp v224, v246, v58 row_newbcast:14 row_mask:0xf bank_mask:0xf
	v_fmac_f32_dpp v225, v247, v59 row_newbcast:14 row_mask:0xf bank_mask:0xf
	v_fmac_f32_dpp v224, v244, v60 row_newbcast:15 row_mask:0xf bank_mask:0xf
	v_fmac_f32_dpp v225, v245, v61 row_newbcast:15 row_mask:0xf bank_mask:0xf
	v_fmac_f32_dpp v224, v246, v62 row_newbcast:15 row_mask:0xf bank_mask:0xf
	v_fmac_f32_dpp v225, v247, v63 row_newbcast:15 row_mask:0xf bank_mask:0xf
	v_mul_f32_dpp v228, v244, v64 row_newbcast:0 row_mask:0xf bank_mask:0xf
	v_mul_f32_dpp v229, v245, v65 row_newbcast:0 row_mask:0xf bank_mask:0xf
	v_fmac_f32_dpp v228, v246, v66 row_newbcast:0 row_mask:0xf bank_mask:0xf
	v_fmac_f32_dpp v229, v247, v67 row_newbcast:0 row_mask:0xf bank_mask:0xf
	v_fmac_f32_dpp v228, v244, v68 row_newbcast:1 row_mask:0xf bank_mask:0xf
	v_fmac_f32_dpp v229, v245, v69 row_newbcast:1 row_mask:0xf bank_mask:0xf
	v_fmac_f32_dpp v228, v246, v70 row_newbcast:1 row_mask:0xf bank_mask:0xf
	v_fmac_f32_dpp v229, v247, v71 row_newbcast:1 row_mask:0xf bank_mask:0xf
	v_fmac_f32_dpp v228, v244, v72 row_newbcast:2 row_mask:0xf bank_mask:0xf
	v_fmac_f32_dpp v229, v245, v73 row_newbcast:2 row_mask:0xf bank_mask:0xf
	v_fmac_f32_dpp v228, v246, v74 row_newbcast:2 row_mask:0xf bank_mask:0xf
	v_fmac_f32_dpp v229, v247, v75 row_newbcast:2 row_mask:0xf bank_mask:0xf
	v_fmac_f32_dpp v228, v244, v76 row_newbcast:3 row_mask:0xf bank_mask:0xf
	v_fmac_f32_dpp v229, v245, v77 row_newbcast:3 row_mask:0xf bank_mask:0xf
	v_fmac_f32_dpp v228, v246, v78 row_newbcast:3 row_mask:0xf bank_mask:0xf
	v_fmac_f32_dpp v229, v247, v79 row_newbcast:3 row_mask:0xf bank_mask:0xf
	v_fmac_f32_dpp v228, v244, v80 row_newbcast:4 row_mask:0xf bank_mask:0xf
	v_fmac_f32_dpp v229, v245, v81 row_newbcast:4 row_mask:0xf bank_mask:0xf
	v_fmac_f32_dpp v228, v246, v82 row_newbcast:4 row_mask:0xf bank_mask:0xf
	v_fmac_f32_dpp v229, v247, v83 row_newbcast:4 row_mask:0xf bank_mask:0xf
	v_fmac_f32_dpp v228, v244, v84 row_newbcast:5 row_mask:0xf bank_mask:0xf
	v_fmac_f32_dpp v229, v245, v85 row_newbcast:5 row_mask:0xf bank_mask:0xf
	v_fmac_f32_dpp v228, v246, v86 row_newbcast:5 row_mask:0xf bank_mask:0xf
	v_fmac_f32_dpp v229, v247, v87 row_newbcast:5 row_mask:0xf bank_mask:0xf
	v_fmac_f32_dpp v228, v244, v88 row_newbcast:6 row_mask:0xf bank_mask:0xf
	v_fmac_f32_dpp v229, v245, v89 row_newbcast:6 row_mask:0xf bank_mask:0xf
	v_fmac_f32_dpp v228, v246, v90 row_newbcast:6 row_mask:0xf bank_mask:0xf
	v_fmac_f32_dpp v229, v247, v91 row_newbcast:6 row_mask:0xf bank_mask:0xf
	v_fmac_f32_dpp v228, v244, v92 row_newbcast:7 row_mask:0xf bank_mask:0xf
	v_fmac_f32_dpp v229, v245, v93 row_newbcast:7 row_mask:0xf bank_mask:0xf
	v_fmac_f32_dpp v228, v246, v94 row_newbcast:7 row_mask:0xf bank_mask:0xf
	v_fmac_f32_dpp v229, v247, v95 row_newbcast:7 row_mask:0xf bank_mask:0xf
	v_fmac_f32_dpp v228, v244, v96 row_newbcast:8 row_mask:0xf bank_mask:0xf
	v_fmac_f32_dpp v229, v245, v97 row_newbcast:8 row_mask:0xf bank_mask:0xf
	v_fmac_f32_dpp v228, v246, v98 row_newbcast:8 row_mask:0xf bank_mask:0xf
	v_fmac_f32_dpp v229, v247, v99 row_newbcast:8 row_mask:0xf bank_mask:0xf
	v_fmac_f32_dpp v228, v244, v100 row_newbcast:9 row_mask:0xf bank_mask:0xf
	v_fmac_f32_dpp v229, v245, v101 row_newbcast:9 row_mask:0xf bank_mask:0xf
	v_fmac_f32_dpp v228, v246, v102 row_newbcast:9 row_mask:0xf bank_mask:0xf
	v_fmac_f32_dpp v229, v247, v103 row_newbcast:9 row_mask:0xf bank_mask:0xf
	v_fmac_f32_dpp v228, v244, v104 row_newbcast:10 row_mask:0xf bank_mask:0xf
	v_fmac_f32_dpp v229, v245, v105 row_newbcast:10 row_mask:0xf bank_mask:0xf
	v_fmac_f32_dpp v228, v246, v106 row_newbcast:10 row_mask:0xf bank_mask:0xf
	v_fmac_f32_dpp v229, v247, v107 row_newbcast:10 row_mask:0xf bank_mask:0xf
	v_fmac_f32_dpp v228, v244, v108 row_newbcast:11 row_mask:0xf bank_mask:0xf
	v_fmac_f32_dpp v229, v245, v109 row_newbcast:11 row_mask:0xf bank_mask:0xf
	v_fmac_f32_dpp v228, v246, v110 row_newbcast:11 row_mask:0xf bank_mask:0xf
	v_fmac_f32_dpp v229, v247, v111 row_newbcast:11 row_mask:0xf bank_mask:0xf
	v_fmac_f32_dpp v228, v244, v112 row_newbcast:12 row_mask:0xf bank_mask:0xf
	v_fmac_f32_dpp v229, v245, v113 row_newbcast:12 row_mask:0xf bank_mask:0xf
	v_fmac_f32_dpp v228, v246, v114 row_newbcast:12 row_mask:0xf bank_mask:0xf
	v_fmac_f32_dpp v229, v247, v115 row_newbcast:12 row_mask:0xf bank_mask:0xf
	v_fmac_f32_dpp v228, v244, v116 row_newbcast:13 row_mask:0xf bank_mask:0xf
	v_fmac_f32_dpp v229, v245, v117 row_newbcast:13 row_mask:0xf bank_mask:0xf
	v_fmac_f32_dpp v228, v246, v118 row_newbcast:13 row_mask:0xf bank_mask:0xf
	v_fmac_f32_dpp v229, v247, v119 row_newbcast:13 row_mask:0xf bank_mask:0xf
	v_fmac_f32_dpp v228, v244, v120 row_newbcast:14 row_mask:0xf bank_mask:0xf
	v_fmac_f32_dpp v229, v245, v121 row_newbcast:14 row_mask:0xf bank_mask:0xf
	v_fmac_f32_dpp v228, v246, v122 row_newbcast:14 row_mask:0xf bank_mask:0xf
	v_fmac_f32_dpp v229, v247, v123 row_newbcast:14 row_mask:0xf bank_mask:0xf
	v_fmac_f32_dpp v228, v244, v124 row_newbcast:15 row_mask:0xf bank_mask:0xf
	v_fmac_f32_dpp v229, v245, v125 row_newbcast:15 row_mask:0xf bank_mask:0xf
	v_fmac_f32_dpp v228, v246, v126 row_newbcast:15 row_mask:0xf bank_mask:0xf
	v_fmac_f32_dpp v229, v247, v127 row_newbcast:15 row_mask:0xf bank_mask:0xf
	v_sub_f32_e64 v232, -v224, v225
	v_sub_f32_e64 v233, -v228, v229
	s_waitcnt lgkmcnt(0)
;     static __device__ __forceinline__ void updS(float (&S)[64], const In1& in, float sa, float vv) {
;         float t0, t1, t2, t3;
;         asm volatile("v_mul_f32_dpp %0, %8, %21 row_newbcast:%22" DPPM "v_mul_f32_dpp %1, %9, %21 row_newbcast:%22" DPPM "v_mul_f32_dpp %2, %10, %21 row_newbcast:%22" DPPM "v_mul_f32_dpp %3, %11, %21 row_newbcast:%22" DPPM
;                      "v_fmac_f32_dpp %0, %12, %4 row_newbcast:%22" DPPM "v_fmac_f32_dpp %1, %13, %5 row_newbcast:%22" DPPM "v_fmac_f32_dpp %2, %14, %6 row_newbcast:%22" DPPM "v_fmac_f32_dpp %3, %15, %7 row_newbcast:%22" DPPM
;                      "v_fmac_f32_dpp %0, %16, %20 row_newbcast:%22" DPPM "v_fmac_f32_dpp %1, %17, %20 row_newbcast:%22" DPPM "v_fmac_f32_dpp %2, %18, %20 row_newbcast:%22" DPPM "v_fmac_f32_dpp %3, %19, %20 row_newbcast:%22" DPPM
;                      : "=&v"(t0), "=&v"(t1), "=&v"(t2), "=&v"(t3)
;                      : "v"(S[K]), "v"(S[K + 1]), "v"(S[K + 2]), "v"(S[K + 3]), "v"(in.kd[0]), "v"(in.kd[1]), "v"(in.kd[2]), "v"(in.kd[3]), "v"(in.w[0]), "v"(in.w[1]), "v"(in.w[2]), "v"(in.w[3]),
;                        "v"(in.b[0]), "v"(in.b[1]), "v"(in.b[2]), "v"(in.b[3]), "v"(sa), "v"(vv), "n"(N0));
;         S[K] = t0; S[K + 1] = t1; S[K + 2] = t2; S[K + 3] = t3;
;         if constexpr (K + 4 < 64) ScanK<K + 4>::updS(S, in, sa, vv);
;     }
;     static __device__ __forceinline__ void updP(float (&P)[64], const In1& in, float sa) {
;         float u0, u1, u2, u3;
;         asm volatile("v_mul_f32_dpp %0, %8, %4 row_newbcast:%17" DPPM "v_mul_f32_dpp %1, %9, %5 row_newbcast:%17" DPPM "v_mul_f32_dpp %2, %10, %6 row_newbcast:%17" DPPM "v_mul_f32_dpp %3, %11, %7 row_newbcast:%17" DPPM
;                      "v_fmac_f32_dpp %0, %12, %16 row_newbcast:%17" DPPM "v_fmac_f32_dpp %1, %13, %16 row_newbcast:%17" DPPM "v_fmac_f32_dpp %2, %14, %16 row_newbcast:%17" DPPM "v_fmac_f32_dpp %3, %15, %16 row_newbcast:%17" DPPM
;                      : "=&v"(u0), "=&v"(u1), "=&v"(u2), "=&v"(u3)
;                      : "v"(P[K]), "v"(P[K + 1]), "v"(P[K + 2]), "v"(P[K + 3]), "v"(in.w[0]), "v"(in.w[1]), "v"(in.w[2]), "v"(in.w[3]), "v"(in.b[0]), "v"(in.b[1]), "v"(in.b[2]), "v"(in.b[3]), "v"(sa), "n"(N0));
;         P[K] = u0; P[K + 1] = u1; P[K + 2] = u2; P[K + 3] = u3;
;         if constexpr (K + 4 < 64) ScanK<K + 4>::updP(P, in, sa);
;     }
	s_nop 1
	v_mfma_f32_4x4x1_16b_f32 v[0:3], v128, v232, v[0:3]
	v_mfma_f32_4x4x1_16b_f32 v[4:7], v129, v232, v[4:7]
	v_mfma_f32_4x4x1_16b_f32 v[8:11], v130, v232, v[8:11]
	v_mfma_f32_4x4x1_16b_f32 v[12:15], v131, v232, v[12:15]
	v_mfma_f32_4x4x1_16b_f32 v[16:19], v132, v232, v[16:19]
	v_mfma_f32_4x4x1_16b_f32 v[20:23], v133, v232, v[20:23]
	v_mfma_f32_4x4x1_16b_f32 v[24:27], v134, v232, v[24:27]
	v_mfma_f32_4x4x1_16b_f32 v[28:31], v135, v232, v[28:31]
	v_mfma_f32_4x4x1_16b_f32 v[32:35], v136, v232, v[32:35]
	v_mfma_f32_4x4x1_16b_f32 v[36:39], v137, v232, v[36:39]
	v_mfma_f32_4x4x1_16b_f32 v[40:43], v138, v232, v[40:43]
	v_mfma_f32_4x4x1_16b_f32 v[44:47], v139, v232, v[44:47]
	v_mfma_f32_4x4x1_16b_f32 v[48:51], v140, v232, v[48:51]
	v_mfma_f32_4x4x1_16b_f32 v[52:55], v141, v232, v[52:55]
	v_mfma_f32_4x4x1_16b_f32 v[56:59], v142, v232, v[56:59]
	v_mfma_f32_4x4x1_16b_f32 v[60:63], v143, v232, v[60:63]
	v_mfma_f32_4x4x1_16b_f32 v[0:3], v144, v234, v[0:3]
	v_mfma_f32_4x4x1_16b_f32 v[4:7], v145, v234, v[4:7]
	v_mfma_f32_4x4x1_16b_f32 v[8:11], v146, v234, v[8:11]
	v_mfma_f32_4x4x1_16b_f32 v[12:15], v147, v234, v[12:15]
	v_mfma_f32_4x4x1_16b_f32 v[16:19], v148, v234, v[16:19]
	v_mfma_f32_4x4x1_16b_f32 v[20:23], v149, v234, v[20:23]
	v_mfma_f32_4x4x1_16b_f32 v[24:27], v150, v234, v[24:27]
	v_mfma_f32_4x4x1_16b_f32 v[28:31], v151, v234, v[28:31]
	v_mfma_f32_4x4x1_16b_f32 v[32:35], v152, v234, v[32:35]
	v_mfma_f32_4x4x1_16b_f32 v[36:39], v153, v234, v[36:39]
	v_mfma_f32_4x4x1_16b_f32 v[40:43], v154, v234, v[40:43]
	v_mfma_f32_4x4x1_16b_f32 v[44:47], v155, v234, v[44:47]
	v_mfma_f32_4x4x1_16b_f32 v[48:51], v156, v234, v[48:51]
	v_mfma_f32_4x4x1_16b_f32 v[52:55], v157, v234, v[52:55]
	v_mfma_f32_4x4x1_16b_f32 v[56:59], v158, v234, v[56:59]
	v_mfma_f32_4x4x1_16b_f32 v[60:63], v159, v234, v[60:63]
	v_mfma_f32_4x4x1_16b_f32 v[64:67], v128, v233, v[64:67]
	v_mfma_f32_4x4x1_16b_f32 v[68:71], v129, v233, v[68:71]
	v_mfma_f32_4x4x1_16b_f32 v[72:75], v130, v233, v[72:75]
	v_mfma_f32_4x4x1_16b_f32 v[76:79], v131, v233, v[76:79]
	v_mfma_f32_4x4x1_16b_f32 v[80:83], v132, v233, v[80:83]
	v_mfma_f32_4x4x1_16b_f32 v[84:87], v133, v233, v[84:87]
	v_mfma_f32_4x4x1_16b_f32 v[88:91], v134, v233, v[88:91]
	v_mfma_f32_4x4x1_16b_f32 v[92:95], v135, v233, v[92:95]
	v_mfma_f32_4x4x1_16b_f32 v[96:99], v136, v233, v[96:99]
	v_mfma_f32_4x4x1_16b_f32 v[100:103], v137, v233, v[100:103]
	v_mfma_f32_4x4x1_16b_f32 v[104:107], v138, v233, v[104:107]
	v_mfma_f32_4x4x1_16b_f32 v[108:111], v139, v233, v[108:111]
	v_mfma_f32_4x4x1_16b_f32 v[112:115], v140, v233, v[112:115]
	v_mfma_f32_4x4x1_16b_f32 v[116:119], v141, v233, v[116:119]
	v_mfma_f32_4x4x1_16b_f32 v[120:123], v142, v233, v[120:123]
	v_mfma_f32_4x4x1_16b_f32 v[124:127], v143, v233, v[124:127]
	s_sub_u32 s83, s83, 1
	s_cmp_eq_u32 s83, 0
	s_cbranch_scc1 .Lmy_p1d0_ldone
	s_sub_u32 s9, s9, 1
	s_cmp_eq_u32 s9, 0
	s_cbranch_scc1 .Lmy_p1d0_renorm
	s_branch .Lmy_p1d0_loop
.Lmy_p1d0_ldone:
	s_waitcnt vmcnt(5)
	buffer_load_dwordx4 v[192:195], v235, s[64:67], s72 offen
	buffer_load_dwordx4 v[196:199], v250, s[64:67], s72 offen
	buffer_load_dwordx4 v[200:203], v251, s[64:67], s72 offen
	buffer_load_dwordx2 v[204:205], v252, s[64:67], s76 offen
	buffer_load_ushort v206, v253, s[64:67], s76 offen
	s_add_u32 s72, s72, 0x1000
	s_add_u32 s76, s76, 0x800
	v_pk_mul_f32 v[244:245], v[164:165], v[236:237]
	v_pk_mul_f32 v[246:247], v[166:167], v[238:239]
	v_pk_mul_f32 v[236:237], v[236:237], v[160:161]
	v_pk_mul_f32 v[238:239], v[238:239], v[162:163]
	v_pk_fma_f32 v[228:229], v[168:169], v[216:217], v[220:221]
	v_pk_fma_f32 v[230:231], v[170:171], v[218:219], v[222:223]
	v_pk_mul_f32 v[208:209], v[164:165], v[168:169]
	v_pk_mul_f32 v[210:211], v[166:167], v[170:171]
	v_rcp_f32_e32 v240, v236
	v_rcp_f32_e32 v241, v237
	v_rcp_f32_e32 v242, v238
	v_rcp_f32_e32 v243, v239
	v_lshlrev_b32_e32 v212, 16, v172
	v_and_b32_e32 v213, 0xffff0000, v172
	v_lshlrev_b32_e32 v214, 16, v173
	v_and_b32_e32 v215, 0xffff0000, v173
	v_pk_mul_f32 v[212:213], v[212:213], v[228:229]
	v_pk_mul_f32 v[214:215], v[214:215], v[230:231]
	v_lshlrev_b32_e32 v234, 16, v174
	v_pk_mul_f32 v[208:209], v[208:209], v[240:241]
	v_pk_mul_f32 v[210:211], v[210:211], v[242:243]
	v_pk_mul_f32 v[212:213], v[212:213], v[240:241]
	v_pk_mul_f32 v[214:215], v[214:215], v[242:243]
	ds_write2_b32 v248, v208, v209 offset0:0 offset1:16
	ds_write2_b32 v248, v210, v211 offset0:32 offset1:48
	ds_write2_b32 v248, v212, v213 offset0:64 offset1:80
	ds_write2_b32 v248, v214, v215 offset0:96 offset1:112
	ds_read_b128 v[128:131], v249 offset:0
	ds_read_b128 v[132:135], v249 offset:16
	ds_read_b128 v[136:139], v249 offset:32
	ds_read_b128 v[140:143], v249 offset:48
	ds_read_b128 v[144:147], v249 offset:256
	ds_read_b128 v[148:151], v249 offset:272
	ds_read_b128 v[152:155], v249 offset:288
	ds_read_b128 v[156:159], v249 offset:304
	v_mul_f32_dpp v224, v244, v0 row_newbcast:0 row_mask:0xf bank_mask:0xf
	v_mul_f32_dpp v225, v245, v1 row_newbcast:0 row_mask:0xf bank_mask:0xf
	v_fmac_f32_dpp v224, v246, v2 row_newbcast:0 row_mask:0xf bank_mask:0xf
	v_fmac_f32_dpp v225, v247, v3 row_newbcast:0 row_mask:0xf bank_mask:0xf
	v_fmac_f32_dpp v224, v244, v4 row_newbcast:1 row_mask:0xf bank_mask:0xf
	v_fmac_f32_dpp v225, v245, v5 row_newbcast:1 row_mask:0xf bank_mask:0xf
	v_fmac_f32_dpp v224, v246, v6 row_newbcast:1 row_mask:0xf bank_mask:0xf
	v_fmac_f32_dpp v225, v247, v7 row_newbcast:1 row_mask:0xf bank_mask:0xf
	v_fmac_f32_dpp v224, v244, v8 row_newbcast:2 row_mask:0xf bank_mask:0xf
	v_fmac_f32_dpp v225, v245, v9 row_newbcast:2 row_mask:0xf bank_mask:0xf
	v_fmac_f32_dpp v224, v246, v10 row_newbcast:2 row_mask:0xf bank_mask:0xf
;     static __device__ __forceinline__ void dot(const float (&S)[64], const f32x4& a, float (&s)[4]) {
;         if constexpr (K == 0) {
;             asm volatile("v_mul_f32_dpp %0, %4, %8 row_newbcast:%16" DPPM "v_mul_f32_dpp %1, %5, %9 row_newbcast:%16" DPPM "v_mul_f32_dpp %2, %6, %10 row_newbcast:%16" DPPM "v_mul_f32_dpp %3, %7, %11 row_newbcast:%16" DPPM
;                          "v_fmac_f32_dpp %0, %4, %12 row_newbcast:%17" DPPM "v_fmac_f32_dpp %1, %5, %13 row_newbcast:%17" DPPM "v_fmac_f32_dpp %2, %6, %14 row_newbcast:%17" DPPM "v_fmac_f32_dpp %3, %7, %15 row_newbcast:%17" DPPM
;                          : "=&v"(s[0]), "=&v"(s[1]), "=&v"(s[2]), "=&v"(s[3])
;                          : "v"(a[0]), "v"(a[1]), "v"(a[2]), "v"(a[3]), "v"(S[K]), "v"(S[K + 1]), "v"(S[K + 2]), "v"(S[K + 3]), "v"(S[K + 4]), "v"(S[K + 5]), "v"(S[K + 6]), "v"(S[K + 7]), "n"(N0), "n"(N1));
;         } else
;         asm volatile("v_fmac_f32_dpp %0, %4, %8 row_newbcast:%16" DPPM "v_fmac_f32_dpp %1, %5, %9 row_newbcast:%16" DPPM "v_fmac_f32_dpp %2, %6, %10 row_newbcast:%16" DPPM "v_fmac_f32_dpp %3, %7, %11 row_newbcast:%16" DPPM
;                      "v_fmac_f32_dpp %0, %4, %12 row_newbcast:%17" DPPM "v_fmac_f32_dpp %1, %5, %13 row_newbcast:%17" DPPM "v_fmac_f32_dpp %2, %6, %14 row_newbcast:%17" DPPM "v_fmac_f32_dpp %3, %7, %15 row_newbcast:%17" DPPM
;                      : "+v"(s[0]), "+v"(s[1]), "+v"(s[2]), "+v"(s[3])
;                      : "v"(a[0]), "v"(a[1]), "v"(a[2]), "v"(a[3]), "v"(S[K]), "v"(S[K + 1]), "v"(S[K + 2]), "v"(S[K + 3]), "v"(S[K + 4]), "v"(S[K + 5]), "v"(S[K + 6]), "v"(S[K + 7]), "n"(N0), "n"(N1));
;         if constexpr (K + 8 < 64) ScanK<K + 8>::dot(S, a, s);
	v_fmac_f32_dpp v225, v247, v11 row_newbcast:2 row_mask:0xf bank_mask:0xf
	v_fmac_f32_dpp v224, v244, v12 row_newbcast:3 row_mask:0xf bank_mask:0xf
	v_fmac_f32_dpp v225, v245, v13 row_newbcast:3 row_mask:0xf bank_mask:0xf
	v_fmac_f32_dpp v224, v246, v14 row_newbcast:3 row_mask:0xf bank_mask:0xf
	v_fmac_f32_dpp v225, v247, v15 row_newbcast:3 row_mask:0xf bank_mask:0xf
	v_fmac_f32_dpp v224, v244, v16 row_newbcast:4 row_mask:0xf bank_mask:0xf
	v_fmac_f32_dpp v225, v245, v17 row_newbcast:4 row_mask:0xf bank_mask:0xf
	v_fmac_f32_dpp v224, v246, v18 row_newbcast:4 row_mask:0xf bank_mask:0xf
	v_fmac_f32_dpp v225, v247, v19 row_newbcast:4 row_mask:0xf bank_mask:0xf
	v_fmac_f32_dpp v224, v244, v20 row_newbcast:5 row_mask:0xf bank_mask:0xf
	v_fmac_f32_dpp v225, v245, v21 row_newbcast:5 row_mask:0xf bank_mask:0xf
	v_fmac_f32_dpp v224, v246, v22 row_newbcast:5 row_mask:0xf bank_mask:0xf
	v_fmac_f32_dpp v225, v247, v23 row_newbcast:5 row_mask:0xf bank_mask:0xf
	v_fmac_f32_dpp v224, v244, v24 row_newbcast:6 row_mask:0xf bank_mask:0xf
	v_fmac_f32_dpp v225, v245, v25 row_newbcast:6 row_mask:0xf bank_mask:0xf
	v_fmac_f32_dpp v224, v246, v26 row_newbcast:6 row_mask:0xf bank_mask:0xf
	v_fmac_f32_dpp v225, v247, v27 row_newbcast:6 row_mask:0xf bank_mask:0xf
	v_fmac_f32_dpp v224, v244, v28 row_newbcast:7 row_mask:0xf bank_mask:0xf
	v_fmac_f32_dpp v225, v245, v29 row_newbcast:7 row_mask:0xf bank_mask:0xf
	v_fmac_f32_dpp v224, v246, v30 row_newbcast:7 row_mask:0xf bank_mask:0xf
	v_fmac_f32_dpp v225, v247, v31 row_newbcast:7 row_mask:0xf bank_mask:0xf
	v_fmac_f32_dpp v224, v244, v32 row_newbcast:8 row_mask:0xf bank_mask:0xf
	v_fmac_f32_dpp v225, v245, v33 row_newbcast:8 row_mask:0xf bank_mask:0xf
	v_fmac_f32_dpp v224, v246, v34 row_newbcast:8 row_mask:0xf bank_mask:0xf
	v_fmac_f32_dpp v225, v247, v35 row_newbcast:8 row_mask:0xf bank_mask:0xf
	v_fmac_f32_dpp v224, v244, v36 row_newbcast:9 row_mask:0xf bank_mask:0xf
	v_fmac_f32_dpp v225, v245, v37 row_newbcast:9 row_mask:0xf bank_mask:0xf
	v_fmac_f32_dpp v224, v246, v38 row_newbcast:9 row_mask:0xf bank_mask:0xf
	v_fmac_f32_dpp v225, v247, v39 row_newbcast:9 row_mask:0xf bank_mask:0xf
	v_fmac_f32_dpp v224, v244, v40 row_newbcast:10 row_mask:0xf bank_mask:0xf
	v_fmac_f32_dpp v225, v245, v41 row_newbcast:10 row_mask:0xf bank_mask:0xf
	v_fmac_f32_dpp v224, v246, v42 row_newbcast:10 row_mask:0xf bank_mask:0xf
	v_fmac_f32_dpp v225, v247, v43 row_newbcast:10 row_mask:0xf bank_mask:0xf
	v_fmac_f32_dpp v224, v244, v44 row_newbcast:11 row_mask:0xf bank_mask:0xf
	v_fmac_f32_dpp v225, v245, v45 row_newbcast:11 row_mask:0xf bank_mask:0xf
	v_fmac_f32_dpp v224, v246, v46 row_newbcast:11 row_mask:0xf bank_mask:0xf
	v_fmac_f32_dpp v225, v247, v47 row_newbcast:11 row_mask:0xf bank_mask:0xf
	v_fmac_f32_dpp v224, v244, v48 row_newbcast:12 row_mask:0xf bank_mask:0xf
	v_fmac_f32_dpp v225, v245, v49 row_newbcast:12 row_mask:0xf bank_mask:0xf
	v_fmac_f32_dpp v224, v246, v50 row_newbcast:12 row_mask:0xf bank_mask:0xf
	v_fmac_f32_dpp v225, v247, v51 row_newbcast:12 row_mask:0xf bank_mask:0xf
	v_fmac_f32_dpp v224, v244, v52 row_newbcast:13 row_mask:0xf bank_mask:0xf
	v_fmac_f32_dpp v225, v245, v53 row_newbcast:13 row_mask:0xf bank_mask:0xf
	v_fmac_f32_dpp v224, v246, v54 row_newbcast:13 row_mask:0xf bank_mask:0xf
	v_fmac_f32_dpp v225, v247, v55 row_newbcast:13 row_mask:0xf bank_mask:0xf
	v_fmac_f32_dpp v224, v244, v56 row_newbcast:14 row_mask:0xf bank_mask:0xf
	v_fmac_f32_dpp v225, v245, v57 row_newbcast:14 row_mask:0xf bank_mask:0xf
	v_fmac_f32_dpp v224, v246, v58 row_newbcast:14 row_mask:0xf bank_mask:0xf
	v_fmac_f32_dpp v225, v247, v59 row_newbcast:14 row_mask:0xf bank_mask:0xf
	v_fmac_f32_dpp v224, v244, v60 row_newbcast:15 row_mask:0xf bank_mask:0xf
	v_fmac_f32_dpp v225, v245, v61 row_newbcast:15 row_mask:0xf bank_mask:0xf
	v_fmac_f32_dpp v224, v246, v62 row_newbcast:15 row_mask:0xf bank_mask:0xf
	v_fmac_f32_dpp v225, v247, v63 row_newbcast:15 row_mask:0xf bank_mask:0xf
	v_mul_f32_dpp v228, v244, v64 row_newbcast:0 row_mask:0xf bank_mask:0xf
	v_mul_f32_dpp v229, v245, v65 row_newbcast:0 row_mask:0xf bank_mask:0xf
	v_fmac_f32_dpp v228, v246, v66 row_newbcast:0 row_mask:0xf bank_mask:0xf
	v_fmac_f32_dpp v229, v247, v67 row_newbcast:0 row_mask:0xf bank_mask:0xf
	v_fmac_f32_dpp v228, v244, v68 row_newbcast:1 row_mask:0xf bank_mask:0xf
	v_fmac_f32_dpp v229, v245, v69 row_newbcast:1 row_mask:0xf bank_mask:0xf
	v_fmac_f32_dpp v228, v246, v70 row_newbcast:1 row_mask:0xf bank_mask:0xf
	v_fmac_f32_dpp v229, v247, v71 row_newbcast:1 row_mask:0xf bank_mask:0xf
	v_fmac_f32_dpp v228, v244, v72 row_newbcast:2 row_mask:0xf bank_mask:0xf
	v_fmac_f32_dpp v229, v245, v73 row_newbcast:2 row_mask:0xf bank_mask:0xf
	v_fmac_f32_dpp v228, v246, v74 row_newbcast:2 row_mask:0xf bank_mask:0xf
	v_fmac_f32_dpp v229, v247, v75 row_newbcast:2 row_mask:0xf bank_mask:0xf
	v_fmac_f32_dpp v228, v244, v76 row_newbcast:3 row_mask:0xf bank_mask:0xf
	v_fmac_f32_dpp v229, v245, v77 row_newbcast:3 row_mask:0xf bank_mask:0xf
	v_fmac_f32_dpp v228, v246, v78 row_newbcast:3 row_mask:0xf bank_mask:0xf
	v_fmac_f32_dpp v229, v247, v79 row_newbcast:3 row_mask:0xf bank_mask:0xf
	v_fmac_f32_dpp v228, v244, v80 row_newbcast:4 row_mask:0xf bank_mask:0xf
	v_fmac_f32_dpp v229, v245, v81 row_newbcast:4 row_mask:0xf bank_mask:0xf
	v_fmac_f32_dpp v228, v246, v82 row_newbcast:4 row_mask:0xf bank_mask:0xf
	v_fmac_f32_dpp v229, v247, v83 row_newbcast:4 row_mask:0xf bank_mask:0xf
	v_fmac_f32_dpp v228, v244, v84 row_newbcast:5 row_mask:0xf bank_mask:0xf
	v_fmac_f32_dpp v229, v245, v85 row_newbcast:5 row_mask:0xf bank_mask:0xf
	v_fmac_f32_dpp v228, v246, v86 row_newbcast:5 row_mask:0xf bank_mask:0xf
;     static __device__ __forceinline__ void dot(const float (&S)[64], const f32x4& a, float (&s)[4]) {
;         if constexpr (K == 0) {
;             asm volatile("v_mul_f32_dpp %0, %4, %8 row_newbcast:%16" DPPM "v_mul_f32_dpp %1, %5, %9 row_newbcast:%16" DPPM "v_mul_f32_dpp %2, %6, %10 row_newbcast:%16" DPPM "v_mul_f32_dpp %3, %7, %11 row_newbcast:%16" DPPM
;                          "v_fmac_f32_dpp %0, %4, %12 row_newbcast:%17" DPPM "v_fmac_f32_dpp %1, %5, %13 row_newbcast:%17" DPPM "v_fmac_f32_dpp %2, %6, %14 row_newbcast:%17" DPPM "v_fmac_f32_dpp %3, %7, %15 row_newbcast:%17" DPPM
;                          : "=&v"(s[0]), "=&v"(s[1]), "=&v"(s[2]), "=&v"(s[3])
;                          : "v"(a[0]), "v"(a[1]), "v"(a[2]), "v"(a[3]), "v"(S[K]), "v"(S[K + 1]), "v"(S[K + 2]), "v"(S[K + 3]), "v"(S[K + 4]), "v"(S[K + 5]), "v"(S[K + 6]), "v"(S[K + 7]), "n"(N0), "n"(N1));
;         } else
;         asm volatile("v_fmac_f32_dpp %0, %4, %8 row_newbcast:%16" DPPM "v_fmac_f32_dpp %1, %5, %9 row_newbcast:%16" DPPM "v_fmac_f32_dpp %2, %6, %10 row_newbcast:%16" DPPM "v_fmac_f32_dpp %3, %7, %11 row_newbcast:%16" DPPM
;                      "v_fmac_f32_dpp %0, %4, %12 row_newbcast:%17" DPPM "v_fmac_f32_dpp %1, %5, %13 row_newbcast:%17" DPPM "v_fmac_f32_dpp %2, %6, %14 row_newbcast:%17" DPPM "v_fmac_f32_dpp %3, %7, %15 row_newbcast:%17" DPPM
;                      : "+v"(s[0]), "+v"(s[1]), "+v"(s[2]), "+v"(s[3])
;                      : "v"(a[0]), "v"(a[1]), "v"(a[2]), "v"(a[3]), "v"(S[K]), "v"(S[K + 1]), "v"(S[K + 2]), "v"(S[K + 3]), "v"(S[K + 4]), "v"(S[K + 5]), "v"(S[K + 6]), "v"(S[K + 7]), "n"(N0), "n"(N1));
;         if constexpr (K + 8 < 64) ScanK<K + 8>::dot(S, a, s);
;     }
;     static __device__ __forceinline__ void upd(float (&S)[64], const In2& in, float sa, float vv, float& y0, float& y1) {
;         float t0, t1, t2, t3;
;         asm volatile("v_mul_f32_dpp %0, %10, %27 row_newbcast:%28" DPPM "v_mul_f32_dpp %1, %11, %27 row_newbcast:%28" DPPM "v_mul_f32_dpp %2, %12, %27 row_newbcast:%28" DPPM "v_mul_f32_dpp %3, %13, %27 row_newbcast:%28" DPPM
;                      "v_fmac_f32_dpp %0, %14, %6 row_newbcast:%28" DPPM "v_fmac_f32_dpp %1, %15, %7 row_newbcast:%28" DPPM "v_fmac_f32_dpp %2, %16, %8 row_newbcast:%28" DPPM "v_fmac_f32_dpp %3, %17, %9 row_newbcast:%28" DPPM
	v_fmac_f32_dpp v229, v247, v87 row_newbcast:5 row_mask:0xf bank_mask:0xf
	v_fmac_f32_dpp v228, v244, v88 row_newbcast:6 row_mask:0xf bank_mask:0xf
	v_fmac_f32_dpp v229, v245, v89 row_newbcast:6 row_mask:0xf bank_mask:0xf
	v_fmac_f32_dpp v228, v246, v90 row_newbcast:6 row_mask:0xf bank_mask:0xf
	v_fmac_f32_dpp v229, v247, v91 row_newbcast:6 row_mask:0xf bank_mask:0xf
	v_fmac_f32_dpp v228, v244, v92 row_newbcast:7 row_mask:0xf bank_mask:0xf
	v_fmac_f32_dpp v229, v245, v93 row_newbcast:7 row_mask:0xf bank_mask:0xf
	v_fmac_f32_dpp v228, v246, v94 row_newbcast:7 row_mask:0xf bank_mask:0xf
	v_fmac_f32_dpp v229, v247, v95 row_newbcast:7 row_mask:0xf bank_mask:0xf
	v_fmac_f32_dpp v228, v244, v96 row_newbcast:8 row_mask:0xf bank_mask:0xf
	v_fmac_f32_dpp v229, v245, v97 row_newbcast:8 row_mask:0xf bank_mask:0xf
	v_fmac_f32_dpp v228, v246, v98 row_newbcast:8 row_mask:0xf bank_mask:0xf
	v_fmac_f32_dpp v229, v247, v99 row_newbcast:8 row_mask:0xf bank_mask:0xf
	v_fmac_f32_dpp v228, v244, v100 row_newbcast:9 row_mask:0xf bank_mask:0xf
	v_fmac_f32_dpp v229, v245, v101 row_newbcast:9 row_mask:0xf bank_mask:0xf
	v_fmac_f32_dpp v228, v246, v102 row_newbcast:9 row_mask:0xf bank_mask:0xf
	v_fmac_f32_dpp v229, v247, v103 row_newbcast:9 row_mask:0xf bank_mask:0xf
	v_fmac_f32_dpp v228, v244, v104 row_newbcast:10 row_mask:0xf bank_mask:0xf
	v_fmac_f32_dpp v229, v245, v105 row_newbcast:10 row_mask:0xf bank_mask:0xf
	v_fmac_f32_dpp v228, v246, v106 row_newbcast:10 row_mask:0xf bank_mask:0xf
	v_fmac_f32_dpp v229, v247, v107 row_newbcast:10 row_mask:0xf bank_mask:0xf
	v_fmac_f32_dpp v228, v244, v108 row_newbcast:11 row_mask:0xf bank_mask:0xf
	v_fmac_f32_dpp v229, v245, v109 row_newbcast:11 row_mask:0xf bank_mask:0xf
	v_fmac_f32_dpp v228, v246, v110 row_newbcast:11 row_mask:0xf bank_mask:0xf
	v_fmac_f32_dpp v229, v247, v111 row_newbcast:11 row_mask:0xf bank_mask:0xf
	v_fmac_f32_dpp v228, v244, v112 row_newbcast:12 row_mask:0xf bank_mask:0xf
	v_fmac_f32_dpp v229, v245, v113 row_newbcast:12 row_mask:0xf bank_mask:0xf
	v_fmac_f32_dpp v228, v246, v114 row_newbcast:12 row_mask:0xf bank_mask:0xf
	v_fmac_f32_dpp v229, v247, v115 row_newbcast:12 row_mask:0xf bank_mask:0xf
	v_fmac_f32_dpp v228, v244, v116 row_newbcast:13 row_mask:0xf bank_mask:0xf
	v_fmac_f32_dpp v229, v245, v117 row_newbcast:13 row_mask:0xf bank_mask:0xf
	v_fmac_f32_dpp v228, v246, v118 row_newbcast:13 row_mask:0xf bank_mask:0xf
	v_fmac_f32_dpp v229, v247, v119 row_newbcast:13 row_mask:0xf bank_mask:0xf
	v_fmac_f32_dpp v228, v244, v120 row_newbcast:14 row_mask:0xf bank_mask:0xf
	v_fmac_f32_dpp v229, v245, v121 row_newbcast:14 row_mask:0xf bank_mask:0xf
	v_fmac_f32_dpp v228, v246, v122 row_newbcast:14 row_mask:0xf bank_mask:0xf
	v_fmac_f32_dpp v229, v247, v123 row_newbcast:14 row_mask:0xf bank_mask:0xf
	v_fmac_f32_dpp v228, v244, v124 row_newbcast:15 row_mask:0xf bank_mask:0xf
	v_fmac_f32_dpp v229, v245, v125 row_newbcast:15 row_mask:0xf bank_mask:0xf
	v_fmac_f32_dpp v228, v246, v126 row_newbcast:15 row_mask:0xf bank_mask:0xf
	v_fmac_f32_dpp v229, v247, v127 row_newbcast:15 row_mask:0xf bank_mask:0xf
	v_sub_f32_e64 v232, -v224, v225
	v_sub_f32_e64 v233, -v228, v229
	s_waitcnt lgkmcnt(0)
	s_nop 1
	v_mfma_f32_4x4x1_16b_f32 v[0:3], v128, v232, v[0:3]
	v_mfma_f32_4x4x1_16b_f32 v[4:7], v129, v232, v[4:7]
	v_mfma_f32_4x4x1_16b_f32 v[8:11], v130, v232, v[8:11]
	v_mfma_f32_4x4x1_16b_f32 v[12:15], v131, v232, v[12:15]
	v_mfma_f32_4x4x1_16b_f32 v[16:19], v132, v232, v[16:19]
	v_mfma_f32_4x4x1_16b_f32 v[20:23], v133, v232, v[20:23]
	v_mfma_f32_4x4x1_16b_f32 v[24:27], v134, v232, v[24:27]
	v_mfma_f32_4x4x1_16b_f32 v[28:31], v135, v232, v[28:31]
	v_mfma_f32_4x4x1_16b_f32 v[32:35], v136, v232, v[32:35]
	v_mfma_f32_4x4x1_16b_f32 v[36:39], v137, v232, v[36:39]
	v_mfma_f32_4x4x1_16b_f32 v[40:43], v138, v232, v[40:43]
	v_mfma_f32_4x4x1_16b_f32 v[44:47], v139, v232, v[44:47]
	v_mfma_f32_4x4x1_16b_f32 v[48:51], v140, v232, v[48:51]
	v_mfma_f32_4x4x1_16b_f32 v[52:55], v141, v232, v[52:55]
	v_mfma_f32_4x4x1_16b_f32 v[56:59], v142, v232, v[56:59]
	v_mfma_f32_4x4x1_16b_f32 v[60:63], v143, v232, v[60:63]
	v_mfma_f32_4x4x1_16b_f32 v[0:3], v144, v234, v[0:3]
	v_mfma_f32_4x4x1_16b_f32 v[4:7], v145, v234, v[4:7]
	v_mfma_f32_4x4x1_16b_f32 v[8:11], v146, v234, v[8:11]
	v_mfma_f32_4x4x1_16b_f32 v[12:15], v147, v234, v[12:15]
	v_mfma_f32_4x4x1_16b_f32 v[16:19], v148, v234, v[16:19]
	v_mfma_f32_4x4x1_16b_f32 v[20:23], v149, v234, v[20:23]
	v_mfma_f32_4x4x1_16b_f32 v[24:27], v150, v234, v[24:27]
	v_mfma_f32_4x4x1_16b_f32 v[28:31], v151, v234, v[28:31]
	v_mfma_f32_4x4x1_16b_f32 v[32:35], v152, v234, v[32:35]
	v_mfma_f32_4x4x1_16b_f32 v[36:39], v153, v234, v[36:39]
	v_mfma_f32_4x4x1_16b_f32 v[40:43], v154, v234, v[40:43]
	v_mfma_f32_4x4x1_16b_f32 v[44:47], v155, v234, v[44:47]
	v_mfma_f32_4x4x1_16b_f32 v[48:51], v156, v234, v[48:51]
	v_mfma_f32_4x4x1_16b_f32 v[52:55], v157, v234, v[52:55]
	v_mfma_f32_4x4x1_16b_f32 v[56:59], v158, v234, v[56:59]
	v_mfma_f32_4x4x1_16b_f32 v[60:63], v159, v234, v[60:63]
	v_mfma_f32_4x4x1_16b_f32 v[64:67], v128, v233, v[64:67]
	v_mfma_f32_4x4x1_16b_f32 v[68:71], v129, v233, v[68:71]
	v_mfma_f32_4x4x1_16b_f32 v[72:75], v130, v233, v[72:75]
	v_mfma_f32_4x4x1_16b_f32 v[76:79], v131, v233, v[76:79]
	v_mfma_f32_4x4x1_16b_f32 v[80:83], v132, v233, v[80:83]
	v_mfma_f32_4x4x1_16b_f32 v[84:87], v133, v233, v[84:87]
	v_mfma_f32_4x4x1_16b_f32 v[88:91], v134, v233, v[88:91]
	v_mfma_f32_4x4x1_16b_f32 v[92:95], v135, v233, v[92:95]
	v_mfma_f32_4x4x1_16b_f32 v[96:99], v136, v233, v[96:99]
	v_mfma_f32_4x4x1_16b_f32 v[100:103], v137, v233, v[100:103]
	v_mfma_f32_4x4x1_16b_f32 v[104:107], v138, v233, v[104:107]
;     static __device__ __forceinline__ void updS(float (&S)[64], const In1& in, float sa, float vv) {
;         float t0, t1, t2, t3;
;         asm volatile("v_mul_f32_dpp %0, %8, %21 row_newbcast:%22" DPPM "v_mul_f32_dpp %1, %9, %21 row_newbcast:%22" DPPM "v_mul_f32_dpp %2, %10, %21 row_newbcast:%22" DPPM "v_mul_f32_dpp %3, %11, %21 row_newbcast:%22" DPPM
;                      "v_fmac_f32_dpp %0, %12, %4 row_newbcast:%22" DPPM "v_fmac_f32_dpp %1, %13, %5 row_newbcast:%22" DPPM "v_fmac_f32_dpp %2, %14, %6 row_newbcast:%22" DPPM "v_fmac_f32_dpp %3, %15, %7 row_newbcast:%22" DPPM
;                      "v_fmac_f32_dpp %0, %16, %20 row_newbcast:%22" DPPM "v_fmac_f32_dpp %1, %17, %20 row_newbcast:%22" DPPM "v_fmac_f32_dpp %2, %18, %20 row_newbcast:%22" DPPM "v_fmac_f32_dpp %3, %19, %20 row_newbcast:%22" DPPM
;                      : "=&v"(t0), "=&v"(t1), "=&v"(t2), "=&v"(t3)
;                      : "v"(S[K]), "v"(S[K + 1]), "v"(S[K + 2]), "v"(S[K + 3]), "v"(in.kd[0]), "v"(in.kd[1]), "v"(in.kd[2]), "v"(in.kd[3]), "v"(in.w[0]), "v"(in.w[1]), "v"(in.w[2]), "v"(in.w[3]),
;                        "v"(in.b[0]), "v"(in.b[1]), "v"(in.b[2]), "v"(in.b[3]), "v"(sa), "v"(vv), "n"(N0));
;         S[K] = t0; S[K + 1] = t1; S[K + 2] = t2; S[K + 3] = t3;
;         if constexpr (K + 4 < 64) ScanK<K + 4>::updS(S, in, sa, vv);
	v_mfma_f32_4x4x1_16b_f32 v[108:111], v139, v233, v[108:111]
	v_mfma_f32_4x4x1_16b_f32 v[112:115], v140, v233, v[112:115]
	v_mfma_f32_4x4x1_16b_f32 v[116:119], v141, v233, v[116:119]
	v_mfma_f32_4x4x1_16b_f32 v[120:123], v142, v233, v[120:123]
	v_mfma_f32_4x4x1_16b_f32 v[124:127], v143, v233, v[124:127]
	v_mul_f32_dpp v0, v236, v0 row_newbcast:0 row_mask:0xf bank_mask:0xf
	v_mul_f32_dpp v1, v237, v1 row_newbcast:0 row_mask:0xf bank_mask:0xf
	v_mul_f32_dpp v2, v238, v2 row_newbcast:0 row_mask:0xf bank_mask:0xf
	v_mul_f32_dpp v3, v239, v3 row_newbcast:0 row_mask:0xf bank_mask:0xf
	v_mul_f32_dpp v4, v236, v4 row_newbcast:1 row_mask:0xf bank_mask:0xf
	v_mul_f32_dpp v5, v237, v5 row_newbcast:1 row_mask:0xf bank_mask:0xf
	v_mul_f32_dpp v6, v238, v6 row_newbcast:1 row_mask:0xf bank_mask:0xf
	v_mul_f32_dpp v7, v239, v7 row_newbcast:1 row_mask:0xf bank_mask:0xf
	v_mul_f32_dpp v8, v236, v8 row_newbcast:2 row_mask:0xf bank_mask:0xf
	v_mul_f32_dpp v9, v237, v9 row_newbcast:2 row_mask:0xf bank_mask:0xf
	v_mul_f32_dpp v10, v238, v10 row_newbcast:2 row_mask:0xf bank_mask:0xf
	v_mul_f32_dpp v11, v239, v11 row_newbcast:2 row_mask:0xf bank_mask:0xf
	v_mul_f32_dpp v12, v236, v12 row_newbcast:3 row_mask:0xf bank_mask:0xf
	v_mul_f32_dpp v13, v237, v13 row_newbcast:3 row_mask:0xf bank_mask:0xf
	v_mul_f32_dpp v14, v238, v14 row_newbcast:3 row_mask:0xf bank_mask:0xf
	v_mul_f32_dpp v15, v239, v15 row_newbcast:3 row_mask:0xf bank_mask:0xf
	v_mul_f32_dpp v16, v236, v16 row_newbcast:4 row_mask:0xf bank_mask:0xf
	v_mul_f32_dpp v17, v237, v17 row_newbcast:4 row_mask:0xf bank_mask:0xf
	v_mul_f32_dpp v18, v238, v18 row_newbcast:4 row_mask:0xf bank_mask:0xf
	v_mul_f32_dpp v19, v239, v19 row_newbcast:4 row_mask:0xf bank_mask:0xf
	v_mul_f32_dpp v20, v236, v20 row_newbcast:5 row_mask:0xf bank_mask:0xf
	v_mul_f32_dpp v21, v237, v21 row_newbcast:5 row_mask:0xf bank_mask:0xf
	v_mul_f32_dpp v22, v238, v22 row_newbcast:5 row_mask:0xf bank_mask:0xf
	v_mul_f32_dpp v23, v239, v23 row_newbcast:5 row_mask:0xf bank_mask:0xf
	v_mul_f32_dpp v24, v236, v24 row_newbcast:6 row_mask:0xf bank_mask:0xf
	v_mul_f32_dpp v25, v237, v25 row_newbcast:6 row_mask:0xf bank_mask:0xf
	v_mul_f32_dpp v26, v238, v26 row_newbcast:6 row_mask:0xf bank_mask:0xf
	v_mul_f32_dpp v27, v239, v27 row_newbcast:6 row_mask:0xf bank_mask:0xf
	v_mul_f32_dpp v28, v236, v28 row_newbcast:7 row_mask:0xf bank_mask:0xf
	v_mul_f32_dpp v29, v237, v29 row_newbcast:7 row_mask:0xf bank_mask:0xf
	v_mul_f32_dpp v30, v238, v30 row_newbcast:7 row_mask:0xf bank_mask:0xf
	v_mul_f32_dpp v31, v239, v31 row_newbcast:7 row_mask:0xf bank_mask:0xf
	v_mul_f32_dpp v32, v236, v32 row_newbcast:8 row_mask:0xf bank_mask:0xf
	v_mul_f32_dpp v33, v237, v33 row_newbcast:8 row_mask:0xf bank_mask:0xf
	v_mul_f32_dpp v34, v238, v34 row_newbcast:8 row_mask:0xf bank_mask:0xf
	v_mul_f32_dpp v35, v239, v35 row_newbcast:8 row_mask:0xf bank_mask:0xf
	v_mul_f32_dpp v36, v236, v36 row_newbcast:9 row_mask:0xf bank_mask:0xf
	v_mul_f32_dpp v37, v237, v37 row_newbcast:9 row_mask:0xf bank_mask:0xf
	v_mul_f32_dpp v38, v238, v38 row_newbcast:9 row_mask:0xf bank_mask:0xf
	v_mul_f32_dpp v39, v239, v39 row_newbcast:9 row_mask:0xf bank_mask:0xf
	v_mul_f32_dpp v40, v236, v40 row_newbcast:10 row_mask:0xf bank_mask:0xf
	v_mul_f32_dpp v41, v237, v41 row_newbcast:10 row_mask:0xf bank_mask:0xf
	v_mul_f32_dpp v42, v238, v42 row_newbcast:10 row_mask:0xf bank_mask:0xf
	v_mul_f32_dpp v43, v239, v43 row_newbcast:10 row_mask:0xf bank_mask:0xf
	v_mul_f32_dpp v44, v236, v44 row_newbcast:11 row_mask:0xf bank_mask:0xf
	v_mul_f32_dpp v45, v237, v45 row_newbcast:11 row_mask:0xf bank_mask:0xf
	v_mul_f32_dpp v46, v238, v46 row_newbcast:11 row_mask:0xf bank_mask:0xf
	v_mul_f32_dpp v47, v239, v47 row_newbcast:11 row_mask:0xf bank_mask:0xf
	v_mul_f32_dpp v48, v236, v48 row_newbcast:12 row_mask:0xf bank_mask:0xf
	v_mul_f32_dpp v49, v237, v49 row_newbcast:12 row_mask:0xf bank_mask:0xf
	v_mul_f32_dpp v50, v238, v50 row_newbcast:12 row_mask:0xf bank_mask:0xf
	v_mul_f32_dpp v51, v239, v51 row_newbcast:12 row_mask:0xf bank_mask:0xf
	v_mul_f32_dpp v52, v236, v52 row_newbcast:13 row_mask:0xf bank_mask:0xf
	v_mul_f32_dpp v53, v237, v53 row_newbcast:13 row_mask:0xf bank_mask:0xf
	v_mul_f32_dpp v54, v238, v54 row_newbcast:13 row_mask:0xf bank_mask:0xf
	v_mul_f32_dpp v55, v239, v55 row_newbcast:13 row_mask:0xf bank_mask:0xf
	v_mul_f32_dpp v56, v236, v56 row_newbcast:14 row_mask:0xf bank_mask:0xf
	v_mul_f32_dpp v57, v237, v57 row_newbcast:14 row_mask:0xf bank_mask:0xf
	v_mul_f32_dpp v58, v238, v58 row_newbcast:14 row_mask:0xf bank_mask:0xf
	v_mul_f32_dpp v59, v239, v59 row_newbcast:14 row_mask:0xf bank_mask:0xf
	v_mul_f32_dpp v60, v236, v60 row_newbcast:15 row_mask:0xf bank_mask:0xf
	v_mul_f32_dpp v61, v237, v61 row_newbcast:15 row_mask:0xf bank_mask:0xf
	v_mul_f32_dpp v62, v238, v62 row_newbcast:15 row_mask:0xf bank_mask:0xf
	v_mul_f32_dpp v63, v239, v63 row_newbcast:15 row_mask:0xf bank_mask:0xf
	v_mul_f32_dpp v64, v236, v64 row_newbcast:0 row_mask:0xf bank_mask:0xf
	v_mul_f32_dpp v65, v237, v65 row_newbcast:0 row_mask:0xf bank_mask:0xf
	v_mul_f32_dpp v66, v238, v66 row_newbcast:0 row_mask:0xf bank_mask:0xf
	v_mul_f32_dpp v67, v239, v67 row_newbcast:0 row_mask:0xf bank_mask:0xf
	v_mul_f32_dpp v68, v236, v68 row_newbcast:1 row_mask:0xf bank_mask:0xf
	v_mul_f32_dpp v69, v237, v69 row_newbcast:1 row_mask:0xf bank_mask:0xf
	v_mul_f32_dpp v70, v238, v70 row_newbcast:1 row_mask:0xf bank_mask:0xf
	v_mul_f32_dpp v71, v239, v71 row_newbcast:1 row_mask:0xf bank_mask:0xf
	v_mul_f32_dpp v72, v236, v72 row_newbcast:2 row_mask:0xf bank_mask:0xf
	v_mul_f32_dpp v73, v237, v73 row_newbcast:2 row_mask:0xf bank_mask:0xf
;     static __device__ __forceinline__ void updS(float (&S)[64], const In1& in, float sa, float vv) {
;         float t0, t1, t2, t3;
;         asm volatile("v_mul_f32_dpp %0, %8, %21 row_newbcast:%22" DPPM "v_mul_f32_dpp %1, %9, %21 row_newbcast:%22" DPPM "v_mul_f32_dpp %2, %10, %21 row_newbcast:%22" DPPM "v_mul_f32_dpp %3, %11, %21 row_newbcast:%22" DPPM
;                      "v_fmac_f32_dpp %0, %12, %4 row_newbcast:%22" DPPM "v_fmac_f32_dpp %1, %13, %5 row_newbcast:%22" DPPM "v_fmac_f32_dpp %2, %14, %6 row_newbcast:%22" DPPM "v_fmac_f32_dpp %3, %15, %7 row_newbcast:%22" DPPM
;                      "v_fmac_f32_dpp %0, %16, %20 row_newbcast:%22" DPPM "v_fmac_f32_dpp %1, %17, %20 row_newbcast:%22" DPPM "v_fmac_f32_dpp %2, %18, %20 row_newbcast:%22" DPPM "v_fmac_f32_dpp %3, %19, %20 row_newbcast:%22" DPPM
;                      : "=&v"(t0), "=&v"(t1), "=&v"(t2), "=&v"(t3)
;                      : "v"(S[K]), "v"(S[K + 1]), "v"(S[K + 2]), "v"(S[K + 3]), "v"(in.kd[0]), "v"(in.kd[1]), "v"(in.kd[2]), "v"(in.kd[3]), "v"(in.w[0]), "v"(in.w[1]), "v"(in.w[2]), "v"(in.w[3]),
;                        "v"(in.b[0]), "v"(in.b[1]), "v"(in.b[2]), "v"(in.b[3]), "v"(sa), "v"(vv), "n"(N0));
;         S[K] = t0; S[K + 1] = t1; S[K + 2] = t2; S[K + 3] = t3;
;         if constexpr (K + 4 < 64) ScanK<K + 4>::updS(S, in, sa, vv);
	v_mul_f32_dpp v74, v238, v74 row_newbcast:2 row_mask:0xf bank_mask:0xf
	v_mul_f32_dpp v75, v239, v75 row_newbcast:2 row_mask:0xf bank_mask:0xf
	v_mul_f32_dpp v76, v236, v76 row_newbcast:3 row_mask:0xf bank_mask:0xf
	v_mul_f32_dpp v77, v237, v77 row_newbcast:3 row_mask:0xf bank_mask:0xf
	v_mul_f32_dpp v78, v238, v78 row_newbcast:3 row_mask:0xf bank_mask:0xf
	v_mul_f32_dpp v79, v239, v79 row_newbcast:3 row_mask:0xf bank_mask:0xf
	v_mul_f32_dpp v80, v236, v80 row_newbcast:4 row_mask:0xf bank_mask:0xf
	v_mul_f32_dpp v81, v237, v81 row_newbcast:4 row_mask:0xf bank_mask:0xf
	v_mul_f32_dpp v82, v238, v82 row_newbcast:4 row_mask:0xf bank_mask:0xf
	v_mul_f32_dpp v83, v239, v83 row_newbcast:4 row_mask:0xf bank_mask:0xf
	v_mul_f32_dpp v84, v236, v84 row_newbcast:5 row_mask:0xf bank_mask:0xf
	v_mul_f32_dpp v85, v237, v85 row_newbcast:5 row_mask:0xf bank_mask:0xf
	v_mul_f32_dpp v86, v238, v86 row_newbcast:5 row_mask:0xf bank_mask:0xf
	v_mul_f32_dpp v87, v239, v87 row_newbcast:5 row_mask:0xf bank_mask:0xf
	v_mul_f32_dpp v88, v236, v88 row_newbcast:6 row_mask:0xf bank_mask:0xf
	v_mul_f32_dpp v89, v237, v89 row_newbcast:6 row_mask:0xf bank_mask:0xf
	v_mul_f32_dpp v90, v238, v90 row_newbcast:6 row_mask:0xf bank_mask:0xf
	v_mul_f32_dpp v91, v239, v91 row_newbcast:6 row_mask:0xf bank_mask:0xf
	v_mul_f32_dpp v92, v236, v92 row_newbcast:7 row_mask:0xf bank_mask:0xf
	v_mul_f32_dpp v93, v237, v93 row_newbcast:7 row_mask:0xf bank_mask:0xf
	v_mul_f32_dpp v94, v238, v94 row_newbcast:7 row_mask:0xf bank_mask:0xf
	v_mul_f32_dpp v95, v239, v95 row_newbcast:7 row_mask:0xf bank_mask:0xf
	v_mul_f32_dpp v96, v236, v96 row_newbcast:8 row_mask:0xf bank_mask:0xf
	v_mul_f32_dpp v97, v237, v97 row_newbcast:8 row_mask:0xf bank_mask:0xf
	v_mul_f32_dpp v98, v238, v98 row_newbcast:8 row_mask:0xf bank_mask:0xf
	v_mul_f32_dpp v99, v239, v99 row_newbcast:8 row_mask:0xf bank_mask:0xf
	v_mul_f32_dpp v100, v236, v100 row_newbcast:9 row_mask:0xf bank_mask:0xf
	v_mul_f32_dpp v101, v237, v101 row_newbcast:9 row_mask:0xf bank_mask:0xf
	v_mul_f32_dpp v102, v238, v102 row_newbcast:9 row_mask:0xf bank_mask:0xf
	v_mul_f32_dpp v103, v239, v103 row_newbcast:9 row_mask:0xf bank_mask:0xf
	v_mul_f32_dpp v104, v236, v104 row_newbcast:10 row_mask:0xf bank_mask:0xf
	v_mul_f32_dpp v105, v237, v105 row_newbcast:10 row_mask:0xf bank_mask:0xf
	v_mul_f32_dpp v106, v238, v106 row_newbcast:10 row_mask:0xf bank_mask:0xf
	v_mul_f32_dpp v107, v239, v107 row_newbcast:10 row_mask:0xf bank_mask:0xf
	v_mul_f32_dpp v108, v236, v108 row_newbcast:11 row_mask:0xf bank_mask:0xf
	v_mul_f32_dpp v109, v237, v109 row_newbcast:11 row_mask:0xf bank_mask:0xf
	v_mul_f32_dpp v110, v238, v110 row_newbcast:11 row_mask:0xf bank_mask:0xf
	v_mul_f32_dpp v111, v239, v111 row_newbcast:11 row_mask:0xf bank_mask:0xf
	v_mul_f32_dpp v112, v236, v112 row_newbcast:12 row_mask:0xf bank_mask:0xf
	v_mul_f32_dpp v113, v237, v113 row_newbcast:12 row_mask:0xf bank_mask:0xf
	v_mul_f32_dpp v114, v238, v114 row_newbcast:12 row_mask:0xf bank_mask:0xf
	v_mul_f32_dpp v115, v239, v115 row_newbcast:12 row_mask:0xf bank_mask:0xf
	v_mul_f32_dpp v116, v236, v116 row_newbcast:13 row_mask:0xf bank_mask:0xf
	v_mul_f32_dpp v117, v237, v117 row_newbcast:13 row_mask:0xf bank_mask:0xf
	v_mul_f32_dpp v118, v238, v118 row_newbcast:13 row_mask:0xf bank_mask:0xf
	v_mul_f32_dpp v119, v239, v119 row_newbcast:13 row_mask:0xf bank_mask:0xf
	v_mul_f32_dpp v120, v236, v120 row_newbcast:14 row_mask:0xf bank_mask:0xf
	v_mul_f32_dpp v121, v237, v121 row_newbcast:14 row_mask:0xf bank_mask:0xf
	v_mul_f32_dpp v122, v238, v122 row_newbcast:14 row_mask:0xf bank_mask:0xf
	v_mul_f32_dpp v123, v239, v123 row_newbcast:14 row_mask:0xf bank_mask:0xf
	v_mul_f32_dpp v124, v236, v124 row_newbcast:15 row_mask:0xf bank_mask:0xf
	v_mul_f32_dpp v125, v237, v125 row_newbcast:15 row_mask:0xf bank_mask:0xf
	v_mul_f32_dpp v126, v238, v126 row_newbcast:15 row_mask:0xf bank_mask:0xf
	v_mul_f32_dpp v127, v239, v127 row_newbcast:15 row_mask:0xf bank_mask:0xf
	v_mov_b32_e32 v236, 1.0
	v_mov_b32_e32 v237, 1.0
	v_mov_b32_e32 v238, 1.0
	v_mov_b32_e32 v239, 1.0
	s_waitcnt vmcnt(0)
; #define NEXT_ITEM() (MIX ? (int)__builtin_amdgcn_readfirstlane(lane == 0 ? __hip_atomic_fetch_add(qctr, 1u, __ATOMIC_RELAXED, __HIP_MEMORY_SCOPE_AGENT) : 0u) : item + (int)gridDim.x * 8)
; #define SB __builtin_amdgcn_sched_barrier(0)
; #define MKR(ptr) __builtin_amdgcn_make_buffer_rsrc((void*)(ptr), 0, 0x7fffffff, 0x00027000)
; #define TOUCH1(set) asm volatile("" :: "v"(set.w), "v"(set.a), "v"(set.b), "v"(set.kw), "v"(set.v))
; #define ST1(set) { DERIVE_BK(set); float sd[4]; ScanK<0>::dot(S, set.a, sd); ScanK<0>::updS(S, set, -((sd[0] + sd[1]) + (sd[2] + sd[3])), __uint_as_float(set.v << 16)); }
; template <bool MIX> __device__ __forceinline__ void scan_pass1(const Params& p, int d, float* ldsf) {
;     ...
;     for (int item = MIX ? NEXT_ITEM() : (int)(blockIdx.x * 8 + wid); item < 2 * NS; item = NEXT_ITEM()) {
;         const bool isP = item >= NS; const int idx = isP ? item - NS : item;
;         const int bh = idx / (NC - 1), c = idx - bh * (NC - 1), b = bh >> 4, h = bh & 15;
;         const int t0 = d ? (SEQ - 1 - c * LC) : c * LC;
;         const size_t off0 = ((size_t)(b * SEQ + t0)) * RW + h * 64; const long stp = d ? -(long)RW : (long)RW;
;         const unsigned ob4 = (unsigned)(off0 * 4), ob2 = (unsigned)(off0 * 2);
;         const f32x4 ka4 = *(const f32x4*)(p.k_a + h * 64 + (lane & 15) * 4), c04 = 1.0f - ka4;
;         float S[64]; int ln = lane; asm volatile("" : "+v"(ln));
;     ...
;         const __amdgpu_buffer_rsrc_t rW = MKR(Wd), rA = MKR(A), rB = MKR(Bd), rK = MKR(KB), rV = MKR(V);
;         if (!isP) {
; #pragma unroll
;             for (int i = 0; i < 64; ++i) S[i] = 0.f;
;     ...
;             In1 i0, i1; LD1(i0, 0);
; #pragma unroll 1
;             for (int s = 0; s < LC; s += 2) { TOUCH1(i0); SB; LD1(i1, s + 1); SB; ST1(i0); TOUCH1(i1); SB; LD1(i0, s + 2); SB; ST1(i1); }
;     ...
;         } else {
; #pragma unroll
;             for (int i = 0; i < 64; ++i) S[i] = (ln == i) ? 1.f : 0.f;
;     ...
;             In1 i0, i1; LD1(i0, 0);
; #pragma unroll 1
;             for (int s = 0; s < LC; s += 2) { TOUCH1(i0); SB; LD1(i1, s + 1); SB; ST1(i0); TOUCH1(i1); SB; LD1(i0, s + 2); SB; ST1(i1); }
;     ...
;         }
;         float* po = (isP ? PT : SLT) + ((size_t)(bh * NC + c)) * 4096 + lane * 64;
; #pragma unroll
;         for (int i = 0; i < 16; ++i) *(f32x4*)(po + 4 * i) = (f32x4){S[4 * i], S[4 * i + 1], S[4 * i + 2], S[4 * i + 3]};
	s_nop 1
	v_and_b32_e32 v128, 63, v254
	v_lshlrev_b32_e32 v129, 8, v128
	v_lshlrev_b32_e32 v130, 2, v128
	global_store_dwordx4 v129, v[0:3], s[90:91] offset:0
	global_store_dwordx4 v129, v[4:7], s[90:91] offset:16
	global_store_dwordx4 v129, v[8:11], s[90:91] offset:32
	global_store_dwordx4 v129, v[12:15], s[90:91] offset:48
	global_store_dwordx4 v129, v[16:19], s[90:91] offset:64
	global_store_dwordx4 v129, v[20:23], s[90:91] offset:80
	global_store_dwordx4 v129, v[24:27], s[90:91] offset:96
	global_store_dwordx4 v129, v[28:31], s[90:91] offset:112
	global_store_dwordx4 v129, v[32:35], s[90:91] offset:128
	global_store_dwordx4 v129, v[36:39], s[90:91] offset:144
	global_store_dwordx4 v129, v[40:43], s[90:91] offset:160
	global_store_dwordx4 v129, v[44:47], s[90:91] offset:176
	global_store_dwordx4 v129, v[48:51], s[90:91] offset:192
	global_store_dwordx4 v129, v[52:55], s[90:91] offset:208
	global_store_dwordx4 v129, v[56:59], s[90:91] offset:224
	global_store_dwordx4 v129, v[60:63], s[90:91] offset:240
	global_store_dword v130, v64, s[92:93] offset:0
	global_store_dword v130, v65, s[92:93] offset:256
	global_store_dword v130, v66, s[92:93] offset:512
	global_store_dword v130, v67, s[92:93] offset:768
	global_store_dword v130, v68, s[92:93] offset:1024
	global_store_dword v130, v69, s[92:93] offset:1280
	global_store_dword v130, v70, s[92:93] offset:1536
	global_store_dword v130, v71, s[92:93] offset:1792
	global_store_dword v130, v72, s[92:93] offset:2048
	global_store_dword v130, v73, s[92:93] offset:2304
	global_store_dword v130, v74, s[92:93] offset:2560
	global_store_dword v130, v75, s[92:93] offset:2816
	global_store_dword v130, v76, s[92:93] offset:3072
	global_store_dword v130, v77, s[92:93] offset:3328
	global_store_dword v130, v78, s[92:93] offset:3584
	global_store_dword v130, v79, s[92:93] offset:3840
	s_add_u32 s92, s92, 0x1000
	s_addc_u32 s93, s93, 0
	global_store_dword v130, v80, s[92:93] offset:0
	global_store_dword v130, v81, s[92:93] offset:256
	global_store_dword v130, v82, s[92:93] offset:512
	global_store_dword v130, v83, s[92:93] offset:768
	global_store_dword v130, v84, s[92:93] offset:1024
	global_store_dword v130, v85, s[92:93] offset:1280
	global_store_dword v130, v86, s[92:93] offset:1536
	global_store_dword v130, v87, s[92:93] offset:1792
	global_store_dword v130, v88, s[92:93] offset:2048
	global_store_dword v130, v89, s[92:93] offset:2304
	global_store_dword v130, v90, s[92:93] offset:2560
	global_store_dword v130, v91, s[92:93] offset:2816
	global_store_dword v130, v92, s[92:93] offset:3072
	global_store_dword v130, v93, s[92:93] offset:3328
	global_store_dword v130, v94, s[92:93] offset:3584
	global_store_dword v130, v95, s[92:93] offset:3840
	s_add_u32 s92, s92, 0x1000
	s_addc_u32 s93, s93, 0
	global_store_dword v130, v96, s[92:93] offset:0
	global_store_dword v130, v97, s[92:93] offset:256
	global_store_dword v130, v98, s[92:93] offset:512
	global_store_dword v130, v99, s[92:93] offset:768
	global_store_dword v130, v100, s[92:93] offset:1024
	global_store_dword v130, v101, s[92:93] offset:1280
	global_store_dword v130, v102, s[92:93] offset:1536
	global_store_dword v130, v103, s[92:93] offset:1792
	global_store_dword v130, v104, s[92:93] offset:2048
	global_store_dword v130, v105, s[92:93] offset:2304
	global_store_dword v130, v106, s[92:93] offset:2560
	global_store_dword v130, v107, s[92:93] offset:2816
	global_store_dword v130, v108, s[92:93] offset:3072
	global_store_dword v130, v109, s[92:93] offset:3328
	global_store_dword v130, v110, s[92:93] offset:3584
	global_store_dword v130, v111, s[92:93] offset:3840
	s_add_u32 s92, s92, 0x1000
	s_addc_u32 s93, s93, 0
	global_store_dword v130, v112, s[92:93] offset:0
	global_store_dword v130, v113, s[92:93] offset:256
	global_store_dword v130, v114, s[92:93] offset:512
	global_store_dword v130, v115, s[92:93] offset:768
	global_store_dword v130, v116, s[92:93] offset:1024
	global_store_dword v130, v117, s[92:93] offset:1280
	global_store_dword v130, v118, s[92:93] offset:1536
	global_store_dword v130, v119, s[92:93] offset:1792
	global_store_dword v130, v120, s[92:93] offset:2048
	global_store_dword v130, v121, s[92:93] offset:2304
	global_store_dword v130, v122, s[92:93] offset:2560
	global_store_dword v130, v123, s[92:93] offset:2816
	global_store_dword v130, v124, s[92:93] offset:3072
	global_store_dword v130, v125, s[92:93] offset:3328
	global_store_dword v130, v126, s[92:93] offset:3584
	global_store_dword v130, v127, s[92:93] offset:3840
	s_nop 1
	s_lshl_b32 s6, s96, 3
	s_add_i32 s0, s0, s6
	s_branch .Lmy_p1d0_item

;     static __device__ __forceinline__ void dot(const float (&S)[64], const f32x4& a, float (&s)[4]) {
;         if constexpr (K == 0) {
;             asm volatile("v_mul_f32_dpp %0, %4, %8 row_newbcast:%16" DPPM "v_mul_f32_dpp %1, %5, %9 row_newbcast:%16" DPPM "v_mul_f32_dpp %2, %6, %10 row_newbcast:%16" DPPM "v_mul_f32_dpp %3, %7, %11 row_newbcast:%16" DPPM
;                          "v_fmac_f32_dpp %0, %4, %12 row_newbcast:%17" DPPM "v_fmac_f32_dpp %1, %5, %13 row_newbcast:%17" DPPM "v_fmac_f32_dpp %2, %6, %14 row_newbcast:%17" DPPM "v_fmac_f32_dpp %3, %7, %15 row_newbcast:%17" DPPM
;                          : "=&v"(s[0]), "=&v"(s[1]), "=&v"(s[2]), "=&v"(s[3])
;                          : "v"(a[0]), "v"(a[1]), "v"(a[2]), "v"(a[3]), "v"(S[K]), "v"(S[K + 1]), "v"(S[K + 2]), "v"(S[K + 3]), "v"(S[K + 4]), "v"(S[K + 5]), "v"(S[K + 6]), "v"(S[K + 7]), "n"(N0), "n"(N1));
;         } else
;         asm volatile("v_fmac_f32_dpp %0, %4, %8 row_newbcast:%16" DPPM "v_fmac_f32_dpp %1, %5, %9 row_newbcast:%16" DPPM "v_fmac_f32_dpp %2, %6, %10 row_newbcast:%16" DPPM "v_fmac_f32_dpp %3, %7, %11 row_newbcast:%16" DPPM
;                      "v_fmac_f32_dpp %0, %4, %12 row_newbcast:%17" DPPM "v_fmac_f32_dpp %1, %5, %13 row_newbcast:%17" DPPM "v_fmac_f32_dpp %2, %6, %14 row_newbcast:%17" DPPM "v_fmac_f32_dpp %3, %7, %15 row_newbcast:%17" DPPM
;                      : "+v"(s[0]), "+v"(s[1]), "+v"(s[2]), "+v"(s[3])
;                      : "v"(a[0]), "v"(a[1]), "v"(a[2]), "v"(a[3]), "v"(S[K]), "v"(S[K + 1]), "v"(S[K + 2]), "v"(S[K + 3]), "v"(S[K + 4]), "v"(S[K + 5]), "v"(S[K + 6]), "v"(S[K + 7]), "n"(N0), "n"(N1));
;         if constexpr (K + 8 < 64) ScanK<K + 8>::dot(S, a, s);
.Lmy_p1d1_loop:
	s_waitcnt vmcnt(5)
	buffer_load_dwordx4 v[192:195], v235, s[64:67], s72 offen
	buffer_load_dwordx4 v[196:199], v250, s[64:67], s72 offen
	buffer_load_dwordx4 v[200:203], v251, s[64:67], s72 offen
	buffer_load_dwordx2 v[204:205], v252, s[64:67], s76 offen
	buffer_load_ushort v206, v253, s[64:67], s76 offen
	s_add_i32 s72, s72, 0xfffff000
	s_max_i32 s72, s72, 0
	s_add_i32 s76, s76, 0xfffff800
	s_max_i32 s76, s76, 0
	v_pk_mul_f32 v[244:245], v[164:165], v[236:237]
	v_pk_mul_f32 v[246:247], v[166:167], v[238:239]
	v_pk_mul_f32 v[236:237], v[236:237], v[160:161]
	v_pk_mul_f32 v[238:239], v[238:239], v[162:163]
	v_pk_fma_f32 v[228:229], v[168:169], v[216:217], v[220:221]
	v_pk_fma_f32 v[230:231], v[170:171], v[218:219], v[222:223]
	v_pk_mul_f32 v[208:209], v[164:165], v[168:169]
	v_pk_mul_f32 v[210:211], v[166:167], v[170:171]
	v_rcp_f32_e32 v240, v236
	v_rcp_f32_e32 v241, v237
	v_rcp_f32_e32 v242, v238
	v_rcp_f32_e32 v243, v239
	v_lshlrev_b32_e32 v212, 16, v172
	v_and_b32_e32 v213, 0xffff0000, v172
	v_lshlrev_b32_e32 v214, 16, v173
	v_and_b32_e32 v215, 0xffff0000, v173
	v_pk_mul_f32 v[212:213], v[212:213], v[228:229]
	v_pk_mul_f32 v[214:215], v[214:215], v[230:231]
	v_lshlrev_b32_e32 v234, 16, v174
	v_pk_mul_f32 v[208:209], v[208:209], v[240:241]
	v_pk_mul_f32 v[210:211], v[210:211], v[242:243]
	v_pk_mul_f32 v[212:213], v[212:213], v[240:241]
	v_pk_mul_f32 v[214:215], v[214:215], v[242:243]
	ds_write2_b32 v248, v208, v209 offset0:0 offset1:16
	ds_write2_b32 v248, v210, v211 offset0:32 offset1:48
	ds_write2_b32 v248, v212, v213 offset0:64 offset1:80
	ds_write2_b32 v248, v214, v215 offset0:96 offset1:112
	ds_read_b128 v[128:131], v249 offset:0
	ds_read_b128 v[132:135], v249 offset:16
	ds_read_b128 v[136:139], v249 offset:32
	ds_read_b128 v[140:143], v249 offset:48
	ds_read_b128 v[144:147], v249 offset:256
	ds_read_b128 v[148:151], v249 offset:272
	ds_read_b128 v[152:155], v249 offset:288
	ds_read_b128 v[156:159], v249 offset:304
	v_mul_f32_dpp v224, v244, v0 row_newbcast:0 row_mask:0xf bank_mask:0xf
	v_mul_f32_dpp v225, v245, v1 row_newbcast:0 row_mask:0xf bank_mask:0xf
	v_fmac_f32_dpp v224, v246, v2 row_newbcast:0 row_mask:0xf bank_mask:0xf
	v_fmac_f32_dpp v225, v247, v3 row_newbcast:0 row_mask:0xf bank_mask:0xf
	v_fmac_f32_dpp v224, v244, v4 row_newbcast:1 row_mask:0xf bank_mask:0xf
	v_fmac_f32_dpp v225, v245, v5 row_newbcast:1 row_mask:0xf bank_mask:0xf
	v_fmac_f32_dpp v224, v246, v6 row_newbcast:1 row_mask:0xf bank_mask:0xf
	v_fmac_f32_dpp v225, v247, v7 row_newbcast:1 row_mask:0xf bank_mask:0xf
	v_fmac_f32_dpp v224, v244, v8 row_newbcast:2 row_mask:0xf bank_mask:0xf
	v_fmac_f32_dpp v225, v245, v9 row_newbcast:2 row_mask:0xf bank_mask:0xf
	v_fmac_f32_dpp v224, v246, v10 row_newbcast:2 row_mask:0xf bank_mask:0xf
	v_fmac_f32_dpp v225, v247, v11 row_newbcast:2 row_mask:0xf bank_mask:0xf
	v_fmac_f32_dpp v224, v244, v12 row_newbcast:3 row_mask:0xf bank_mask:0xf
	v_fmac_f32_dpp v225, v245, v13 row_newbcast:3 row_mask:0xf bank_mask:0xf
	v_fmac_f32_dpp v224, v246, v14 row_newbcast:3 row_mask:0xf bank_mask:0xf
	v_fmac_f32_dpp v225, v247, v15 row_newbcast:3 row_mask:0xf bank_mask:0xf
	v_fmac_f32_dpp v224, v244, v16 row_newbcast:4 row_mask:0xf bank_mask:0xf
	v_fmac_f32_dpp v225, v245, v17 row_newbcast:4 row_mask:0xf bank_mask:0xf
	v_fmac_f32_dpp v224, v246, v18 row_newbcast:4 row_mask:0xf bank_mask:0xf
	v_fmac_f32_dpp v225, v247, v19 row_newbcast:4 row_mask:0xf bank_mask:0xf
	v_fmac_f32_dpp v224, v244, v20 row_newbcast:5 row_mask:0xf bank_mask:0xf
	v_fmac_f32_dpp v225, v245, v21 row_newbcast:5 row_mask:0xf bank_mask:0xf
	v_fmac_f32_dpp v224, v246, v22 row_newbcast:5 row_mask:0xf bank_mask:0xf
	v_fmac_f32_dpp v225, v247, v23 row_newbcast:5 row_mask:0xf bank_mask:0xf
	v_fmac_f32_dpp v224, v244, v24 row_newbcast:6 row_mask:0xf bank_mask:0xf
	v_fmac_f32_dpp v225, v245, v25 row_newbcast:6 row_mask:0xf bank_mask:0xf
	v_fmac_f32_dpp v224, v246, v26 row_newbcast:6 row_mask:0xf bank_mask:0xf
	v_fmac_f32_dpp v225, v247, v27 row_newbcast:6 row_mask:0xf bank_mask:0xf
	v_fmac_f32_dpp v224, v244, v28 row_newbcast:7 row_mask:0xf bank_mask:0xf
	v_fmac_f32_dpp v225, v245, v29 row_newbcast:7 row_mask:0xf bank_mask:0xf
	v_fmac_f32_dpp v224, v246, v30 row_newbcast:7 row_mask:0xf bank_mask:0xf
	v_fmac_f32_dpp v225, v247, v31 row_newbcast:7 row_mask:0xf bank_mask:0xf
	v_fmac_f32_dpp v224, v244, v32 row_newbcast:8 row_mask:0xf bank_mask:0xf
	v_fmac_f32_dpp v225, v245, v33 row_newbcast:8 row_mask:0xf bank_mask:0xf
	v_fmac_f32_dpp v224, v246, v34 row_newbcast:8 row_mask:0xf bank_mask:0xf
	v_fmac_f32_dpp v225, v247, v35 row_newbcast:8 row_mask:0xf bank_mask:0xf
	v_fmac_f32_dpp v224, v244, v36 row_newbcast:9 row_mask:0xf bank_mask:0xf
	v_fmac_f32_dpp v225, v245, v37 row_newbcast:9 row_mask:0xf bank_mask:0xf
	v_fmac_f32_dpp v224, v246, v38 row_newbcast:9 row_mask:0xf bank_mask:0xf
	v_fmac_f32_dpp v225, v247, v39 row_newbcast:9 row_mask:0xf bank_mask:0xf
	v_fmac_f32_dpp v224, v244, v40 row_newbcast:10 row_mask:0xf bank_mask:0xf
	v_fmac_f32_dpp v225, v245, v41 row_newbcast:10 row_mask:0xf bank_mask:0xf
	v_fmac_f32_dpp v224, v246, v42 row_newbcast:10 row_mask:0xf bank_mask:0xf
	v_fmac_f32_dpp v225, v247, v43 row_newbcast:10 row_mask:0xf bank_mask:0xf
	v_fmac_f32_dpp v224, v244, v44 row_newbcast:11 row_mask:0xf bank_mask:0xf
	v_fmac_f32_dpp v225, v245, v45 row_newbcast:11 row_mask:0xf bank_mask:0xf
	v_fmac_f32_dpp v224, v246, v46 row_newbcast:11 row_mask:0xf bank_mask:0xf
	v_fmac_f32_dpp v225, v247, v47 row_newbcast:11 row_mask:0xf bank_mask:0xf
	v_fmac_f32_dpp v224, v244, v48 row_newbcast:12 row_mask:0xf bank_mask:0xf
	v_fmac_f32_dpp v225, v245, v49 row_newbcast:12 row_mask:0xf bank_mask:0xf
;     static __device__ __forceinline__ void dot(const float (&S)[64], const f32x4& a, float (&s)[4]) {
;         if constexpr (K == 0) {
;             asm volatile("v_mul_f32_dpp %0, %4, %8 row_newbcast:%16" DPPM "v_mul_f32_dpp %1, %5, %9 row_newbcast:%16" DPPM "v_mul_f32_dpp %2, %6, %10 row_newbcast:%16" DPPM "v_mul_f32_dpp %3, %7, %11 row_newbcast:%16" DPPM
;                          "v_fmac_f32_dpp %0, %4, %12 row_newbcast:%17" DPPM "v_fmac_f32_dpp %1, %5, %13 row_newbcast:%17" DPPM "v_fmac_f32_dpp %2, %6, %14 row_newbcast:%17" DPPM "v_fmac_f32_dpp %3, %7, %15 row_newbcast:%17" DPPM
;                          : "=&v"(s[0]), "=&v"(s[1]), "=&v"(s[2]), "=&v"(s[3])
;                          : "v"(a[0]), "v"(a[1]), "v"(a[2]), "v"(a[3]), "v"(S[K]), "v"(S[K + 1]), "v"(S[K + 2]), "v"(S[K + 3]), "v"(S[K + 4]), "v"(S[K + 5]), "v"(S[K + 6]), "v"(S[K + 7]), "n"(N0), "n"(N1));
;         } else
;         asm volatile("v_fmac_f32_dpp %0, %4, %8 row_newbcast:%16" DPPM "v_fmac_f32_dpp %1, %5, %9 row_newbcast:%16" DPPM "v_fmac_f32_dpp %2, %6, %10 row_newbcast:%16" DPPM "v_fmac_f32_dpp %3, %7, %11 row_newbcast:%16" DPPM
;                      "v_fmac_f32_dpp %0, %4, %12 row_newbcast:%17" DPPM "v_fmac_f32_dpp %1, %5, %13 row_newbcast:%17" DPPM "v_fmac_f32_dpp %2, %6, %14 row_newbcast:%17" DPPM "v_fmac_f32_dpp %3, %7, %15 row_newbcast:%17" DPPM
;                      : "+v"(s[0]), "+v"(s[1]), "+v"(s[2]), "+v"(s[3])
;                      : "v"(a[0]), "v"(a[1]), "v"(a[2]), "v"(a[3]), "v"(S[K]), "v"(S[K + 1]), "v"(S[K + 2]), "v"(S[K + 3]), "v"(S[K + 4]), "v"(S[K + 5]), "v"(S[K + 6]), "v"(S[K + 7]), "n"(N0), "n"(N1));
;         if constexpr (K + 8 < 64) ScanK<K + 8>::dot(S, a, s);
	v_fmac_f32_dpp v224, v246, v50 row_newbcast:12 row_mask:0xf bank_mask:0xf
	v_fmac_f32_dpp v225, v247, v51 row_newbcast:12 row_mask:0xf bank_mask:0xf
	v_fmac_f32_dpp v224, v244, v52 row_newbcast:13 row_mask:0xf bank_mask:0xf
	v_fmac_f32_dpp v225, v245, v53 row_newbcast:13 row_mask:0xf bank_mask:0xf
	v_fmac_f32_dpp v224, v246, v54 row_newbcast:13 row_mask:0xf bank_mask:0xf
	v_fmac_f32_dpp v225, v247, v55 row_newbcast:13 row_mask:0xf bank_mask:0xf
	v_fmac_f32_dpp v224, v244, v56 row_newbcast:14 row_mask:0xf bank_mask:0xf
	v_fmac_f32_dpp v225, v245, v57 row_newbcast:14 row_mask:0xf bank_mask:0xf
	v_fmac_f32_dpp v224, v246, v58 row_newbcast:14 row_mask:0xf bank_mask:0xf
	v_fmac_f32_dpp v225, v247, v59 row_newbcast:14 row_mask:0xf bank_mask:0xf
	v_fmac_f32_dpp v224, v244, v60 row_newbcast:15 row_mask:0xf bank_mask:0xf
	v_fmac_f32_dpp v225, v245, v61 row_newbcast:15 row_mask:0xf bank_mask:0xf
	v_fmac_f32_dpp v224, v246, v62 row_newbcast:15 row_mask:0xf bank_mask:0xf
	v_fmac_f32_dpp v225, v247, v63 row_newbcast:15 row_mask:0xf bank_mask:0xf
	v_mul_f32_dpp v228, v244, v64 row_newbcast:0 row_mask:0xf bank_mask:0xf
	v_mul_f32_dpp v229, v245, v65 row_newbcast:0 row_mask:0xf bank_mask:0xf
	v_fmac_f32_dpp v228, v246, v66 row_newbcast:0 row_mask:0xf bank_mask:0xf
	v_fmac_f32_dpp v229, v247, v67 row_newbcast:0 row_mask:0xf bank_mask:0xf
	v_fmac_f32_dpp v228, v244, v68 row_newbcast:1 row_mask:0xf bank_mask:0xf
	v_fmac_f32_dpp v229, v245, v69 row_newbcast:1 row_mask:0xf bank_mask:0xf
	v_fmac_f32_dpp v228, v246, v70 row_newbcast:1 row_mask:0xf bank_mask:0xf
	v_fmac_f32_dpp v229, v247, v71 row_newbcast:1 row_mask:0xf bank_mask:0xf
	v_fmac_f32_dpp v228, v244, v72 row_newbcast:2 row_mask:0xf bank_mask:0xf
	v_fmac_f32_dpp v229, v245, v73 row_newbcast:2 row_mask:0xf bank_mask:0xf
	v_fmac_f32_dpp v228, v246, v74 row_newbcast:2 row_mask:0xf bank_mask:0xf
	v_fmac_f32_dpp v229, v247, v75 row_newbcast:2 row_mask:0xf bank_mask:0xf
	v_fmac_f32_dpp v228, v244, v76 row_newbcast:3 row_mask:0xf bank_mask:0xf
	v_fmac_f32_dpp v229, v245, v77 row_newbcast:3 row_mask:0xf bank_mask:0xf
	v_fmac_f32_dpp v228, v246, v78 row_newbcast:3 row_mask:0xf bank_mask:0xf
	v_fmac_f32_dpp v229, v247, v79 row_newbcast:3 row_mask:0xf bank_mask:0xf
	v_fmac_f32_dpp v228, v244, v80 row_newbcast:4 row_mask:0xf bank_mask:0xf
	v_fmac_f32_dpp v229, v245, v81 row_newbcast:4 row_mask:0xf bank_mask:0xf
	v_fmac_f32_dpp v228, v246, v82 row_newbcast:4 row_mask:0xf bank_mask:0xf
	v_fmac_f32_dpp v229, v247, v83 row_newbcast:4 row_mask:0xf bank_mask:0xf
	v_fmac_f32_dpp v228, v244, v84 row_newbcast:5 row_mask:0xf bank_mask:0xf
	v_fmac_f32_dpp v229, v245, v85 row_newbcast:5 row_mask:0xf bank_mask:0xf
	v_fmac_f32_dpp v228, v246, v86 row_newbcast:5 row_mask:0xf bank_mask:0xf
	v_fmac_f32_dpp v229, v247, v87 row_newbcast:5 row_mask:0xf bank_mask:0xf
	v_fmac_f32_dpp v228, v244, v88 row_newbcast:6 row_mask:0xf bank_mask:0xf
	v_fmac_f32_dpp v229, v245, v89 row_newbcast:6 row_mask:0xf bank_mask:0xf
	v_fmac_f32_dpp v228, v246, v90 row_newbcast:6 row_mask:0xf bank_mask:0xf
	v_fmac_f32_dpp v229, v247, v91 row_newbcast:6 row_mask:0xf bank_mask:0xf
	v_fmac_f32_dpp v228, v244, v92 row_newbcast:7 row_mask:0xf bank_mask:0xf
	v_fmac_f32_dpp v229, v245, v93 row_newbcast:7 row_mask:0xf bank_mask:0xf
	v_fmac_f32_dpp v228, v246, v94 row_newbcast:7 row_mask:0xf bank_mask:0xf
	v_fmac_f32_dpp v229, v247, v95 row_newbcast:7 row_mask:0xf bank_mask:0xf
	v_fmac_f32_dpp v228, v244, v96 row_newbcast:8 row_mask:0xf bank_mask:0xf
	v_fmac_f32_dpp v229, v245, v97 row_newbcast:8 row_mask:0xf bank_mask:0xf
	v_fmac_f32_dpp v228, v246, v98 row_newbcast:8 row_mask:0xf bank_mask:0xf
	v_fmac_f32_dpp v229, v247, v99 row_newbcast:8 row_mask:0xf bank_mask:0xf
	v_fmac_f32_dpp v228, v244, v100 row_newbcast:9 row_mask:0xf bank_mask:0xf
	v_fmac_f32_dpp v229, v245, v101 row_newbcast:9 row_mask:0xf bank_mask:0xf
	v_fmac_f32_dpp v228, v246, v102 row_newbcast:9 row_mask:0xf bank_mask:0xf
	v_fmac_f32_dpp v229, v247, v103 row_newbcast:9 row_mask:0xf bank_mask:0xf
	v_fmac_f32_dpp v228, v244, v104 row_newbcast:10 row_mask:0xf bank_mask:0xf
	v_fmac_f32_dpp v229, v245, v105 row_newbcast:10 row_mask:0xf bank_mask:0xf
	v_fmac_f32_dpp v228, v246, v106 row_newbcast:10 row_mask:0xf bank_mask:0xf
	v_fmac_f32_dpp v229, v247, v107 row_newbcast:10 row_mask:0xf bank_mask:0xf
	v_fmac_f32_dpp v228, v244, v108 row_newbcast:11 row_mask:0xf bank_mask:0xf
	v_fmac_f32_dpp v229, v245, v109 row_newbcast:11 row_mask:0xf bank_mask:0xf
	v_fmac_f32_dpp v228, v246, v110 row_newbcast:11 row_mask:0xf bank_mask:0xf
	v_fmac_f32_dpp v229, v247, v111 row_newbcast:11 row_mask:0xf bank_mask:0xf
	v_fmac_f32_dpp v228, v244, v112 row_newbcast:12 row_mask:0xf bank_mask:0xf
	v_fmac_f32_dpp v229, v245, v113 row_newbcast:12 row_mask:0xf bank_mask:0xf
	v_fmac_f32_dpp v228, v246, v114 row_newbcast:12 row_mask:0xf bank_mask:0xf
	v_fmac_f32_dpp v229, v247, v115 row_newbcast:12 row_mask:0xf bank_mask:0xf
	v_fmac_f32_dpp v228, v244, v116 row_newbcast:13 row_mask:0xf bank_mask:0xf
	v_fmac_f32_dpp v229, v245, v117 row_newbcast:13 row_mask:0xf bank_mask:0xf
	v_fmac_f32_dpp v228, v246, v118 row_newbcast:13 row_mask:0xf bank_mask:0xf
	v_fmac_f32_dpp v229, v247, v119 row_newbcast:13 row_mask:0xf bank_mask:0xf
	v_fmac_f32_dpp v228, v244, v120 row_newbcast:14 row_mask:0xf bank_mask:0xf
	v_fmac_f32_dpp v229, v245, v121 row_newbcast:14 row_mask:0xf bank_mask:0xf
	v_fmac_f32_dpp v228, v246, v122 row_newbcast:14 row_mask:0xf bank_mask:0xf
	v_fmac_f32_dpp v229, v247, v123 row_newbcast:14 row_mask:0xf bank_mask:0xf
	v_fmac_f32_dpp v228, v244, v124 row_newbcast:15 row_mask:0xf bank_mask:0xf
	v_fmac_f32_dpp v229, v245, v125 row_newbcast:15 row_mask:0xf bank_mask:0xf
	v_fmac_f32_dpp v228, v246, v126 row_newbcast:15 row_mask:0xf bank_mask:0xf
	v_fmac_f32_dpp v229, v247, v127 row_newbcast:15 row_mask:0xf bank_mask:0xf
	v_sub_f32_e64 v232, -v224, v225
	v_sub_f32_e64 v233, -v228, v229
	s_waitcnt lgkmcnt(0)
;     static __device__ __forceinline__ void updS(float (&S)[64], const In1& in, float sa, float vv) {
;         float t0, t1, t2, t3;
;         asm volatile("v_mul_f32_dpp %0, %8, %21 row_newbcast:%22" DPPM "v_mul_f32_dpp %1, %9, %21 row_newbcast:%22" DPPM "v_mul_f32_dpp %2, %10, %21 row_newbcast:%22" DPPM "v_mul_f32_dpp %3, %11, %21 row_newbcast:%22" DPPM
;                      "v_fmac_f32_dpp %0, %12, %4 row_newbcast:%22" DPPM "v_fmac_f32_dpp %1, %13, %5 row_newbcast:%22" DPPM "v_fmac_f32_dpp %2, %14, %6 row_newbcast:%22" DPPM "v_fmac_f32_dpp %3, %15, %7 row_newbcast:%22" DPPM
;                      "v_fmac_f32_dpp %0, %16, %20 row_newbcast:%22" DPPM "v_fmac_f32_dpp %1, %17, %20 row_newbcast:%22" DPPM "v_fmac_f32_dpp %2, %18, %20 row_newbcast:%22" DPPM "v_fmac_f32_dpp %3, %19, %20 row_newbcast:%22" DPPM
;                      : "=&v"(t0), "=&v"(t1), "=&v"(t2), "=&v"(t3)
;                      : "v"(S[K]), "v"(S[K + 1]), "v"(S[K + 2]), "v"(S[K + 3]), "v"(in.kd[0]), "v"(in.kd[1]), "v"(in.kd[2]), "v"(in.kd[3]), "v"(in.w[0]), "v"(in.w[1]), "v"(in.w[2]), "v"(in.w[3]),
;                        "v"(in.b[0]), "v"(in.b[1]), "v"(in.b[2]), "v"(in.b[3]), "v"(sa), "v"(vv), "n"(N0));
;         S[K] = t0; S[K + 1] = t1; S[K + 2] = t2; S[K + 3] = t3;
;         if constexpr (K + 4 < 64) ScanK<K + 4>::updS(S, in, sa, vv);
;     }
;     static __device__ __forceinline__ void updP(float (&P)[64], const In1& in, float sa) {
;         float u0, u1, u2, u3;
;         asm volatile("v_mul_f32_dpp %0, %8, %4 row_newbcast:%17" DPPM "v_mul_f32_dpp %1, %9, %5 row_newbcast:%17" DPPM "v_mul_f32_dpp %2, %10, %6 row_newbcast:%17" DPPM "v_mul_f32_dpp %3, %11, %7 row_newbcast:%17" DPPM
;                      "v_fmac_f32_dpp %0, %12, %16 row_newbcast:%17" DPPM "v_fmac_f32_dpp %1, %13, %16 row_newbcast:%17" DPPM "v_fmac_f32_dpp %2, %14, %16 row_newbcast:%17" DPPM "v_fmac_f32_dpp %3, %15, %16 row_newbcast:%17" DPPM
;                      : "=&v"(u0), "=&v"(u1), "=&v"(u2), "=&v"(u3)
;                      : "v"(P[K]), "v"(P[K + 1]), "v"(P[K + 2]), "v"(P[K + 3]), "v"(in.w[0]), "v"(in.w[1]), "v"(in.w[2]), "v"(in.w[3]), "v"(in.b[0]), "v"(in.b[1]), "v"(in.b[2]), "v"(in.b[3]), "v"(sa), "n"(N0));
;         P[K] = u0; P[K + 1] = u1; P[K + 2] = u2; P[K + 3] = u3;
;         if constexpr (K + 4 < 64) ScanK<K + 4>::updP(P, in, sa);
;     }
	s_nop 1
	v_mfma_f32_4x4x1_16b_f32 v[0:3], v128, v232, v[0:3]
	v_mfma_f32_4x4x1_16b_f32 v[4:7], v129, v232, v[4:7]
	v_mfma_f32_4x4x1_16b_f32 v[8:11], v130, v232, v[8:11]
	v_mfma_f32_4x4x1_16b_f32 v[12:15], v131, v232, v[12:15]
	v_mfma_f32_4x4x1_16b_f32 v[16:19], v132, v232, v[16:19]
	v_mfma_f32_4x4x1_16b_f32 v[20:23], v133, v232, v[20:23]
	v_mfma_f32_4x4x1_16b_f32 v[24:27], v134, v232, v[24:27]
	v_mfma_f32_4x4x1_16b_f32 v[28:31], v135, v232, v[28:31]
	v_mfma_f32_4x4x1_16b_f32 v[32:35], v136, v232, v[32:35]
	v_mfma_f32_4x4x1_16b_f32 v[36:39], v137, v232, v[36:39]
	v_mfma_f32_4x4x1_16b_f32 v[40:43], v138, v232, v[40:43]
	v_mfma_f32_4x4x1_16b_f32 v[44:47], v139, v232, v[44:47]
	v_mfma_f32_4x4x1_16b_f32 v[48:51], v140, v232, v[48:51]
	v_mfma_f32_4x4x1_16b_f32 v[52:55], v141, v232, v[52:55]
	v_mfma_f32_4x4x1_16b_f32 v[56:59], v142, v232, v[56:59]
	v_mfma_f32_4x4x1_16b_f32 v[60:63], v143, v232, v[60:63]
	v_mfma_f32_4x4x1_16b_f32 v[0:3], v144, v234, v[0:3]
	v_mfma_f32_4x4x1_16b_f32 v[4:7], v145, v234, v[4:7]
	v_mfma_f32_4x4x1_16b_f32 v[8:11], v146, v234, v[8:11]
	v_mfma_f32_4x4x1_16b_f32 v[12:15], v147, v234, v[12:15]
	v_mfma_f32_4x4x1_16b_f32 v[16:19], v148, v234, v[16:19]
	v_mfma_f32_4x4x1_16b_f32 v[20:23], v149, v234, v[20:23]
	v_mfma_f32_4x4x1_16b_f32 v[24:27], v150, v234, v[24:27]
	v_mfma_f32_4x4x1_16b_f32 v[28:31], v151, v234, v[28:31]
	v_mfma_f32_4x4x1_16b_f32 v[32:35], v152, v234, v[32:35]
	v_mfma_f32_4x4x1_16b_f32 v[36:39], v153, v234, v[36:39]
	v_mfma_f32_4x4x1_16b_f32 v[40:43], v154, v234, v[40:43]
	v_mfma_f32_4x4x1_16b_f32 v[44:47], v155, v234, v[44:47]
	v_mfma_f32_4x4x1_16b_f32 v[48:51], v156, v234, v[48:51]
	v_mfma_f32_4x4x1_16b_f32 v[52:55], v157, v234, v[52:55]
	v_mfma_f32_4x4x1_16b_f32 v[56:59], v158, v234, v[56:59]
	v_mfma_f32_4x4x1_16b_f32 v[60:63], v159, v234, v[60:63]
	v_mfma_f32_4x4x1_16b_f32 v[64:67], v128, v233, v[64:67]
	v_mfma_f32_4x4x1_16b_f32 v[68:71], v129, v233, v[68:71]
	v_mfma_f32_4x4x1_16b_f32 v[72:75], v130, v233, v[72:75]
	v_mfma_f32_4x4x1_16b_f32 v[76:79], v131, v233, v[76:79]
	v_mfma_f32_4x4x1_16b_f32 v[80:83], v132, v233, v[80:83]
	v_mfma_f32_4x4x1_16b_f32 v[84:87], v133, v233, v[84:87]
	v_mfma_f32_4x4x1_16b_f32 v[88:91], v134, v233, v[88:91]
	v_mfma_f32_4x4x1_16b_f32 v[92:95], v135, v233, v[92:95]
	v_mfma_f32_4x4x1_16b_f32 v[96:99], v136, v233, v[96:99]
	v_mfma_f32_4x4x1_16b_f32 v[100:103], v137, v233, v[100:103]
	v_mfma_f32_4x4x1_16b_f32 v[104:107], v138, v233, v[104:107]
	v_mfma_f32_4x4x1_16b_f32 v[108:111], v139, v233, v[108:111]
	v_mfma_f32_4x4x1_16b_f32 v[112:115], v140, v233, v[112:115]
	v_mfma_f32_4x4x1_16b_f32 v[116:119], v141, v233, v[116:119]
	v_mfma_f32_4x4x1_16b_f32 v[120:123], v142, v233, v[120:123]
	v_mfma_f32_4x4x1_16b_f32 v[124:127], v143, v233, v[124:127]
	s_waitcnt vmcnt(5)
	buffer_load_dwordx4 v[160:163], v235, s[64:67], s72 offen
	buffer_load_dwordx4 v[164:167], v250, s[64:67], s72 offen
	buffer_load_dwordx4 v[168:171], v251, s[64:67], s72 offen
	buffer_load_dwordx2 v[172:173], v252, s[64:67], s76 offen
	buffer_load_ushort v174, v253, s[64:67], s76 offen
	s_add_i32 s72, s72, 0xfffff000
	s_max_i32 s72, s72, 0
	s_add_i32 s76, s76, 0xfffff800
	s_max_i32 s76, s76, 0
	v_pk_mul_f32 v[244:245], v[180:181], v[236:237]
	v_pk_mul_f32 v[246:247], v[182:183], v[238:239]
	v_pk_mul_f32 v[236:237], v[236:237], v[176:177]
	v_pk_mul_f32 v[238:239], v[238:239], v[178:179]
	v_pk_fma_f32 v[228:229], v[184:185], v[216:217], v[220:221]
	v_pk_fma_f32 v[230:231], v[186:187], v[218:219], v[222:223]
	v_pk_mul_f32 v[208:209], v[180:181], v[184:185]
	v_pk_mul_f32 v[210:211], v[182:183], v[186:187]
	v_rcp_f32_e32 v240, v236
	v_rcp_f32_e32 v241, v237
	v_rcp_f32_e32 v242, v238
	v_rcp_f32_e32 v243, v239
	v_lshlrev_b32_e32 v212, 16, v188
	v_and_b32_e32 v213, 0xffff0000, v188
	v_lshlrev_b32_e32 v214, 16, v189
	v_and_b32_e32 v215, 0xffff0000, v189
	v_pk_mul_f32 v[212:213], v[212:213], v[228:229]
	v_pk_mul_f32 v[214:215], v[214:215], v[230:231]
	v_lshlrev_b32_e32 v234, 16, v190
	v_pk_mul_f32 v[208:209], v[208:209], v[240:241]
	v_pk_mul_f32 v[210:211], v[210:211], v[242:243]
	v_pk_mul_f32 v[212:213], v[212:213], v[240:241]
	v_pk_mul_f32 v[214:215], v[214:215], v[242:243]
	ds_write2_b32 v248, v208, v209 offset0:0 offset1:16
	ds_write2_b32 v248, v210, v211 offset0:32 offset1:48
	ds_write2_b32 v248, v212, v213 offset0:64 offset1:80
	ds_write2_b32 v248, v214, v215 offset0:96 offset1:112
	ds_read_b128 v[128:131], v249 offset:0
	ds_read_b128 v[132:135], v249 offset:16
	ds_read_b128 v[136:139], v249 offset:32
	ds_read_b128 v[140:143], v249 offset:48
	ds_read_b128 v[144:147], v249 offset:256
	ds_read_b128 v[148:151], v249 offset:272
	ds_read_b128 v[152:155], v249 offset:288
	ds_read_b128 v[156:159], v249 offset:304
	v_mul_f32_dpp v224, v244, v0 row_newbcast:0 row_mask:0xf bank_mask:0xf
	v_mul_f32_dpp v225, v245, v1 row_newbcast:0 row_mask:0xf bank_mask:0xf
	v_fmac_f32_dpp v224, v246, v2 row_newbcast:0 row_mask:0xf bank_mask:0xf
	v_fmac_f32_dpp v225, v247, v3 row_newbcast:0 row_mask:0xf bank_mask:0xf
	v_fmac_f32_dpp v224, v244, v4 row_newbcast:1 row_mask:0xf bank_mask:0xf
	v_fmac_f32_dpp v225, v245, v5 row_newbcast:1 row_mask:0xf bank_mask:0xf
	v_fmac_f32_dpp v224, v246, v6 row_newbcast:1 row_mask:0xf bank_mask:0xf
	v_fmac_f32_dpp v225, v247, v7 row_newbcast:1 row_mask:0xf bank_mask:0xf
	v_fmac_f32_dpp v224, v244, v8 row_newbcast:2 row_mask:0xf bank_mask:0xf
	v_fmac_f32_dpp v225, v245, v9 row_newbcast:2 row_mask:0xf bank_mask:0xf
	v_fmac_f32_dpp v224, v246, v10 row_newbcast:2 row_mask:0xf bank_mask:0xf
	v_fmac_f32_dpp v225, v247, v11 row_newbcast:2 row_mask:0xf bank_mask:0xf
	v_fmac_f32_dpp v224, v244, v12 row_newbcast:3 row_mask:0xf bank_mask:0xf
;     static __device__ __forceinline__ void dot(const float (&S)[64], const f32x4& a, float (&s)[4]) {
;         if constexpr (K == 0) {
;             asm volatile("v_mul_f32_dpp %0, %4, %8 row_newbcast:%16" DPPM "v_mul_f32_dpp %1, %5, %9 row_newbcast:%16" DPPM "v_mul_f32_dpp %2, %6, %10 row_newbcast:%16" DPPM "v_mul_f32_dpp %3, %7, %11 row_newbcast:%16" DPPM
;                          "v_fmac_f32_dpp %0, %4, %12 row_newbcast:%17" DPPM "v_fmac_f32_dpp %1, %5, %13 row_newbcast:%17" DPPM "v_fmac_f32_dpp %2, %6, %14 row_newbcast:%17" DPPM "v_fmac_f32_dpp %3, %7, %15 row_newbcast:%17" DPPM
;                          : "=&v"(s[0]), "=&v"(s[1]), "=&v"(s[2]), "=&v"(s[3])
;                          : "v"(a[0]), "v"(a[1]), "v"(a[2]), "v"(a[3]), "v"(S[K]), "v"(S[K + 1]), "v"(S[K + 2]), "v"(S[K + 3]), "v"(S[K + 4]), "v"(S[K + 5]), "v"(S[K + 6]), "v"(S[K + 7]), "n"(N0), "n"(N1));
;         } else
;         asm volatile("v_fmac_f32_dpp %0, %4, %8 row_newbcast:%16" DPPM "v_fmac_f32_dpp %1, %5, %9 row_newbcast:%16" DPPM "v_fmac_f32_dpp %2, %6, %10 row_newbcast:%16" DPPM "v_fmac_f32_dpp %3, %7, %11 row_newbcast:%16" DPPM
;                      "v_fmac_f32_dpp %0, %4, %12 row_newbcast:%17" DPPM "v_fmac_f32_dpp %1, %5, %13 row_newbcast:%17" DPPM "v_fmac_f32_dpp %2, %6, %14 row_newbcast:%17" DPPM "v_fmac_f32_dpp %3, %7, %15 row_newbcast:%17" DPPM
;                      : "+v"(s[0]), "+v"(s[1]), "+v"(s[2]), "+v"(s[3])
;                      : "v"(a[0]), "v"(a[1]), "v"(a[2]), "v"(a[3]), "v"(S[K]), "v"(S[K + 1]), "v"(S[K + 2]), "v"(S[K + 3]), "v"(S[K + 4]), "v"(S[K + 5]), "v"(S[K + 6]), "v"(S[K + 7]), "n"(N0), "n"(N1));
;         if constexpr (K + 8 < 64) ScanK<K + 8>::dot(S, a, s);
	v_fmac_f32_dpp v225, v245, v13 row_newbcast:3 row_mask:0xf bank_mask:0xf
	v_fmac_f32_dpp v224, v246, v14 row_newbcast:3 row_mask:0xf bank_mask:0xf
	v_fmac_f32_dpp v225, v247, v15 row_newbcast:3 row_mask:0xf bank_mask:0xf
	v_fmac_f32_dpp v224, v244, v16 row_newbcast:4 row_mask:0xf bank_mask:0xf
	v_fmac_f32_dpp v225, v245, v17 row_newbcast:4 row_mask:0xf bank_mask:0xf
	v_fmac_f32_dpp v224, v246, v18 row_newbcast:4 row_mask:0xf bank_mask:0xf
	v_fmac_f32_dpp v225, v247, v19 row_newbcast:4 row_mask:0xf bank_mask:0xf
	v_fmac_f32_dpp v224, v244, v20 row_newbcast:5 row_mask:0xf bank_mask:0xf
	v_fmac_f32_dpp v225, v245, v21 row_newbcast:5 row_mask:0xf bank_mask:0xf
	v_fmac_f32_dpp v224, v246, v22 row_newbcast:5 row_mask:0xf bank_mask:0xf
	v_fmac_f32_dpp v225, v247, v23 row_newbcast:5 row_mask:0xf bank_mask:0xf
	v_fmac_f32_dpp v224, v244, v24 row_newbcast:6 row_mask:0xf bank_mask:0xf
	v_fmac_f32_dpp v225, v245, v25 row_newbcast:6 row_mask:0xf bank_mask:0xf
	v_fmac_f32_dpp v224, v246, v26 row_newbcast:6 row_mask:0xf bank_mask:0xf
	v_fmac_f32_dpp v225, v247, v27 row_newbcast:6 row_mask:0xf bank_mask:0xf
	v_fmac_f32_dpp v224, v244, v28 row_newbcast:7 row_mask:0xf bank_mask:0xf
	v_fmac_f32_dpp v225, v245, v29 row_newbcast:7 row_mask:0xf bank_mask:0xf
	v_fmac_f32_dpp v224, v246, v30 row_newbcast:7 row_mask:0xf bank_mask:0xf
	v_fmac_f32_dpp v225, v247, v31 row_newbcast:7 row_mask:0xf bank_mask:0xf
	v_fmac_f32_dpp v224, v244, v32 row_newbcast:8 row_mask:0xf bank_mask:0xf
	v_fmac_f32_dpp v225, v245, v33 row_newbcast:8 row_mask:0xf bank_mask:0xf
	v_fmac_f32_dpp v224, v246, v34 row_newbcast:8 row_mask:0xf bank_mask:0xf
	v_fmac_f32_dpp v225, v247, v35 row_newbcast:8 row_mask:0xf bank_mask:0xf
	v_fmac_f32_dpp v224, v244, v36 row_newbcast:9 row_mask:0xf bank_mask:0xf
	v_fmac_f32_dpp v225, v245, v37 row_newbcast:9 row_mask:0xf bank_mask:0xf
	v_fmac_f32_dpp v224, v246, v38 row_newbcast:9 row_mask:0xf bank_mask:0xf
	v_fmac_f32_dpp v225, v247, v39 row_newbcast:9 row_mask:0xf bank_mask:0xf
	v_fmac_f32_dpp v224, v244, v40 row_newbcast:10 row_mask:0xf bank_mask:0xf
	v_fmac_f32_dpp v225, v245, v41 row_newbcast:10 row_mask:0xf bank_mask:0xf
	v_fmac_f32_dpp v224, v246, v42 row_newbcast:10 row_mask:0xf bank_mask:0xf
	v_fmac_f32_dpp v225, v247, v43 row_newbcast:10 row_mask:0xf bank_mask:0xf
	v_fmac_f32_dpp v224, v244, v44 row_newbcast:11 row_mask:0xf bank_mask:0xf
	v_fmac_f32_dpp v225, v245, v45 row_newbcast:11 row_mask:0xf bank_mask:0xf
	v_fmac_f32_dpp v224, v246, v46 row_newbcast:11 row_mask:0xf bank_mask:0xf
	v_fmac_f32_dpp v225, v247, v47 row_newbcast:11 row_mask:0xf bank_mask:0xf
	v_fmac_f32_dpp v224, v244, v48 row_newbcast:12 row_mask:0xf bank_mask:0xf
	v_fmac_f32_dpp v225, v245, v49 row_newbcast:12 row_mask:0xf bank_mask:0xf
	v_fmac_f32_dpp v224, v246, v50 row_newbcast:12 row_mask:0xf bank_mask:0xf
	v_fmac_f32_dpp v225, v247, v51 row_newbcast:12 row_mask:0xf bank_mask:0xf
	v_fmac_f32_dpp v224, v244, v52 row_newbcast:13 row_mask:0xf bank_mask:0xf
	v_fmac_f32_dpp v225, v245, v53 row_newbcast:13 row_mask:0xf bank_mask:0xf
	v_fmac_f32_dpp v224, v246, v54 row_newbcast:13 row_mask:0xf bank_mask:0xf
	v_fmac_f32_dpp v225, v247, v55 row_newbcast:13 row_mask:0xf bank_mask:0xf
	v_fmac_f32_dpp v224, v244, v56 row_newbcast:14 row_mask:0xf bank_mask:0xf
	v_fmac_f32_dpp v225, v245, v57 row_newbcast:14 row_mask:0xf bank_mask:0xf
	v_fmac_f32_dpp v224, v246, v58 row_newbcast:14 row_mask:0xf bank_mask:0xf
	v_fmac_f32_dpp v225, v247, v59 row_newbcast:14 row_mask:0xf bank_mask:0xf
	v_fmac_f32_dpp v224, v244, v60 row_newbcast:15 row_mask:0xf bank_mask:0xf
	v_fmac_f32_dpp v225, v245, v61 row_newbcast:15 row_mask:0xf bank_mask:0xf
	v_fmac_f32_dpp v224, v246, v62 row_newbcast:15 row_mask:0xf bank_mask:0xf
	v_fmac_f32_dpp v225, v247, v63 row_newbcast:15 row_mask:0xf bank_mask:0xf
	v_mul_f32_dpp v228, v244, v64 row_newbcast:0 row_mask:0xf bank_mask:0xf
	v_mul_f32_dpp v229, v245, v65 row_newbcast:0 row_mask:0xf bank_mask:0xf
	v_fmac_f32_dpp v228, v246, v66 row_newbcast:0 row_mask:0xf bank_mask:0xf
	v_fmac_f32_dpp v229, v247, v67 row_newbcast:0 row_mask:0xf bank_mask:0xf
	v_fmac_f32_dpp v228, v244, v68 row_newbcast:1 row_mask:0xf bank_mask:0xf
	v_fmac_f32_dpp v229, v245, v69 row_newbcast:1 row_mask:0xf bank_mask:0xf
	v_fmac_f32_dpp v228, v246, v70 row_newbcast:1 row_mask:0xf bank_mask:0xf
	v_fmac_f32_dpp v229, v247, v71 row_newbcast:1 row_mask:0xf bank_mask:0xf
	v_fmac_f32_dpp v228, v244, v72 row_newbcast:2 row_mask:0xf bank_mask:0xf
	v_fmac_f32_dpp v229, v245, v73 row_newbcast:2 row_mask:0xf bank_mask:0xf
	v_fmac_f32_dpp v228, v246, v74 row_newbcast:2 row_mask:0xf bank_mask:0xf
	v_fmac_f32_dpp v229, v247, v75 row_newbcast:2 row_mask:0xf bank_mask:0xf
	v_fmac_f32_dpp v228, v244, v76 row_newbcast:3 row_mask:0xf bank_mask:0xf
	v_fmac_f32_dpp v229, v245, v77 row_newbcast:3 row_mask:0xf bank_mask:0xf
	v_fmac_f32_dpp v228, v246, v78 row_newbcast:3 row_mask:0xf bank_mask:0xf
	v_fmac_f32_dpp v229, v247, v79 row_newbcast:3 row_mask:0xf bank_mask:0xf
	v_fmac_f32_dpp v228, v244, v80 row_newbcast:4 row_mask:0xf bank_mask:0xf
	v_fmac_f32_dpp v229, v245, v81 row_newbcast:4 row_mask:0xf bank_mask:0xf
	v_fmac_f32_dpp v228, v246, v82 row_newbcast:4 row_mask:0xf bank_mask:0xf
	v_fmac_f32_dpp v229, v247, v83 row_newbcast:4 row_mask:0xf bank_mask:0xf
	v_fmac_f32_dpp v228, v244, v84 row_newbcast:5 row_mask:0xf bank_mask:0xf
	v_fmac_f32_dpp v229, v245, v85 row_newbcast:5 row_mask:0xf bank_mask:0xf
	v_fmac_f32_dpp v228, v246, v86 row_newbcast:5 row_mask:0xf bank_mask:0xf
	v_fmac_f32_dpp v229, v247, v87 row_newbcast:5 row_mask:0xf bank_mask:0xf
	v_fmac_f32_dpp v228, v244, v88 row_newbcast:6 row_mask:0xf bank_mask:0xf
;     static __device__ __forceinline__ void dot(const float (&S)[64], const f32x4& a, float (&s)[4]) {
;         if constexpr (K == 0) {
;             asm volatile("v_mul_f32_dpp %0, %4, %8 row_newbcast:%16" DPPM "v_mul_f32_dpp %1, %5, %9 row_newbcast:%16" DPPM "v_mul_f32_dpp %2, %6, %10 row_newbcast:%16" DPPM "v_mul_f32_dpp %3, %7, %11 row_newbcast:%16" DPPM
;                          "v_fmac_f32_dpp %0, %4, %12 row_newbcast:%17" DPPM "v_fmac_f32_dpp %1, %5, %13 row_newbcast:%17" DPPM "v_fmac_f32_dpp %2, %6, %14 row_newbcast:%17" DPPM "v_fmac_f32_dpp %3, %7, %15 row_newbcast:%17" DPPM
;                          : "=&v"(s[0]), "=&v"(s[1]), "=&v"(s[2]), "=&v"(s[3])
;                          : "v"(a[0]), "v"(a[1]), "v"(a[2]), "v"(a[3]), "v"(S[K]), "v"(S[K + 1]), "v"(S[K + 2]), "v"(S[K + 3]), "v"(S[K + 4]), "v"(S[K + 5]), "v"(S[K + 6]), "v"(S[K + 7]), "n"(N0), "n"(N1));
;         } else
;         asm volatile("v_fmac_f32_dpp %0, %4, %8 row_newbcast:%16" DPPM "v_fmac_f32_dpp %1, %5, %9 row_newbcast:%16" DPPM "v_fmac_f32_dpp %2, %6, %10 row_newbcast:%16" DPPM "v_fmac_f32_dpp %3, %7, %11 row_newbcast:%16" DPPM
;                      "v_fmac_f32_dpp %0, %4, %12 row_newbcast:%17" DPPM "v_fmac_f32_dpp %1, %5, %13 row_newbcast:%17" DPPM "v_fmac_f32_dpp %2, %6, %14 row_newbcast:%17" DPPM "v_fmac_f32_dpp %3, %7, %15 row_newbcast:%17" DPPM
;                      : "+v"(s[0]), "+v"(s[1]), "+v"(s[2]), "+v"(s[3])
;                      : "v"(a[0]), "v"(a[1]), "v"(a[2]), "v"(a[3]), "v"(S[K]), "v"(S[K + 1]), "v"(S[K + 2]), "v"(S[K + 3]), "v"(S[K + 4]), "v"(S[K + 5]), "v"(S[K + 6]), "v"(S[K + 7]), "n"(N0), "n"(N1));
;         if constexpr (K + 8 < 64) ScanK<K + 8>::dot(S, a, s);
;     static __device__ __forceinline__ void updS(float (&S)[64], const In1& in, float sa, float vv) {
;         float t0, t1, t2, t3;
;         asm volatile("v_mul_f32_dpp %0, %8, %21 row_newbcast:%22" DPPM "v_mul_f32_dpp %1, %9, %21 row_newbcast:%22" DPPM "v_mul_f32_dpp %2, %10, %21 row_newbcast:%22" DPPM "v_mul_f32_dpp %3, %11, %21 row_newbcast:%22" DPPM
;                      "v_fmac_f32_dpp %0, %12, %4 row_newbcast:%22" DPPM "v_fmac_f32_dpp %1, %13, %5 row_newbcast:%22" DPPM "v_fmac_f32_dpp %2, %14, %6 row_newbcast:%22" DPPM "v_fmac_f32_dpp %3, %15, %7 row_newbcast:%22" DPPM
	v_fmac_f32_dpp v229, v245, v89 row_newbcast:6 row_mask:0xf bank_mask:0xf
	v_fmac_f32_dpp v228, v246, v90 row_newbcast:6 row_mask:0xf bank_mask:0xf
	v_fmac_f32_dpp v229, v247, v91 row_newbcast:6 row_mask:0xf bank_mask:0xf
	v_fmac_f32_dpp v228, v244, v92 row_newbcast:7 row_mask:0xf bank_mask:0xf
	v_fmac_f32_dpp v229, v245, v93 row_newbcast:7 row_mask:0xf bank_mask:0xf
	v_fmac_f32_dpp v228, v246, v94 row_newbcast:7 row_mask:0xf bank_mask:0xf
	v_fmac_f32_dpp v229, v247, v95 row_newbcast:7 row_mask:0xf bank_mask:0xf
	v_fmac_f32_dpp v228, v244, v96 row_newbcast:8 row_mask:0xf bank_mask:0xf
	v_fmac_f32_dpp v229, v245, v97 row_newbcast:8 row_mask:0xf bank_mask:0xf
	v_fmac_f32_dpp v228, v246, v98 row_newbcast:8 row_mask:0xf bank_mask:0xf
	v_fmac_f32_dpp v229, v247, v99 row_newbcast:8 row_mask:0xf bank_mask:0xf
	v_fmac_f32_dpp v228, v244, v100 row_newbcast:9 row_mask:0xf bank_mask:0xf
	v_fmac_f32_dpp v229, v245, v101 row_newbcast:9 row_mask:0xf bank_mask:0xf
	v_fmac_f32_dpp v228, v246, v102 row_newbcast:9 row_mask:0xf bank_mask:0xf
	v_fmac_f32_dpp v229, v247, v103 row_newbcast:9 row_mask:0xf bank_mask:0xf
	v_fmac_f32_dpp v228, v244, v104 row_newbcast:10 row_mask:0xf bank_mask:0xf
	v_fmac_f32_dpp v229, v245, v105 row_newbcast:10 row_mask:0xf bank_mask:0xf
	v_fmac_f32_dpp v228, v246, v106 row_newbcast:10 row_mask:0xf bank_mask:0xf
	v_fmac_f32_dpp v229, v247, v107 row_newbcast:10 row_mask:0xf bank_mask:0xf
	v_fmac_f32_dpp v228, v244, v108 row_newbcast:11 row_mask:0xf bank_mask:0xf
	v_fmac_f32_dpp v229, v245, v109 row_newbcast:11 row_mask:0xf bank_mask:0xf
	v_fmac_f32_dpp v228, v246, v110 row_newbcast:11 row_mask:0xf bank_mask:0xf
	v_fmac_f32_dpp v229, v247, v111 row_newbcast:11 row_mask:0xf bank_mask:0xf
	v_fmac_f32_dpp v228, v244, v112 row_newbcast:12 row_mask:0xf bank_mask:0xf
	v_fmac_f32_dpp v229, v245, v113 row_newbcast:12 row_mask:0xf bank_mask:0xf
	v_fmac_f32_dpp v228, v246, v114 row_newbcast:12 row_mask:0xf bank_mask:0xf
	v_fmac_f32_dpp v229, v247, v115 row_newbcast:12 row_mask:0xf bank_mask:0xf
	v_fmac_f32_dpp v228, v244, v116 row_newbcast:13 row_mask:0xf bank_mask:0xf
	v_fmac_f32_dpp v229, v245, v117 row_newbcast:13 row_mask:0xf bank_mask:0xf
	v_fmac_f32_dpp v228, v246, v118 row_newbcast:13 row_mask:0xf bank_mask:0xf
	v_fmac_f32_dpp v229, v247, v119 row_newbcast:13 row_mask:0xf bank_mask:0xf
	v_fmac_f32_dpp v228, v244, v120 row_newbcast:14 row_mask:0xf bank_mask:0xf
	v_fmac_f32_dpp v229, v245, v121 row_newbcast:14 row_mask:0xf bank_mask:0xf
	v_fmac_f32_dpp v228, v246, v122 row_newbcast:14 row_mask:0xf bank_mask:0xf
	v_fmac_f32_dpp v229, v247, v123 row_newbcast:14 row_mask:0xf bank_mask:0xf
	v_fmac_f32_dpp v228, v244, v124 row_newbcast:15 row_mask:0xf bank_mask:0xf
	v_fmac_f32_dpp v229, v245, v125 row_newbcast:15 row_mask:0xf bank_mask:0xf
	v_fmac_f32_dpp v228, v246, v126 row_newbcast:15 row_mask:0xf bank_mask:0xf
	v_fmac_f32_dpp v229, v247, v127 row_newbcast:15 row_mask:0xf bank_mask:0xf
	v_sub_f32_e64 v232, -v224, v225
	v_sub_f32_e64 v233, -v228, v229
	s_waitcnt lgkmcnt(0)
	s_nop 1
	v_mfma_f32_4x4x1_16b_f32 v[0:3], v128, v232, v[0:3]
	v_mfma_f32_4x4x1_16b_f32 v[4:7], v129, v232, v[4:7]
	v_mfma_f32_4x4x1_16b_f32 v[8:11], v130, v232, v[8:11]
	v_mfma_f32_4x4x1_16b_f32 v[12:15], v131, v232, v[12:15]
	v_mfma_f32_4x4x1_16b_f32 v[16:19], v132, v232, v[16:19]
	v_mfma_f32_4x4x1_16b_f32 v[20:23], v133, v232, v[20:23]
	v_mfma_f32_4x4x1_16b_f32 v[24:27], v134, v232, v[24:27]
	v_mfma_f32_4x4x1_16b_f32 v[28:31], v135, v232, v[28:31]
	v_mfma_f32_4x4x1_16b_f32 v[32:35], v136, v232, v[32:35]
	v_mfma_f32_4x4x1_16b_f32 v[36:39], v137, v232, v[36:39]
	v_mfma_f32_4x4x1_16b_f32 v[40:43], v138, v232, v[40:43]
	v_mfma_f32_4x4x1_16b_f32 v[44:47], v139, v232, v[44:47]
	v_mfma_f32_4x4x1_16b_f32 v[48:51], v140, v232, v[48:51]
	v_mfma_f32_4x4x1_16b_f32 v[52:55], v141, v232, v[52:55]
	v_mfma_f32_4x4x1_16b_f32 v[56:59], v142, v232, v[56:59]
	v_mfma_f32_4x4x1_16b_f32 v[60:63], v143, v232, v[60:63]
	v_mfma_f32_4x4x1_16b_f32 v[0:3], v144, v234, v[0:3]
	v_mfma_f32_4x4x1_16b_f32 v[4:7], v145, v234, v[4:7]
	v_mfma_f32_4x4x1_16b_f32 v[8:11], v146, v234, v[8:11]
	v_mfma_f32_4x4x1_16b_f32 v[12:15], v147, v234, v[12:15]
	v_mfma_f32_4x4x1_16b_f32 v[16:19], v148, v234, v[16:19]
	v_mfma_f32_4x4x1_16b_f32 v[20:23], v149, v234, v[20:23]
	v_mfma_f32_4x4x1_16b_f32 v[24:27], v150, v234, v[24:27]
	v_mfma_f32_4x4x1_16b_f32 v[28:31], v151, v234, v[28:31]
	v_mfma_f32_4x4x1_16b_f32 v[32:35], v152, v234, v[32:35]
	v_mfma_f32_4x4x1_16b_f32 v[36:39], v153, v234, v[36:39]
	v_mfma_f32_4x4x1_16b_f32 v[40:43], v154, v234, v[40:43]
	v_mfma_f32_4x4x1_16b_f32 v[44:47], v155, v234, v[44:47]
	v_mfma_f32_4x4x1_16b_f32 v[48:51], v156, v234, v[48:51]
	v_mfma_f32_4x4x1_16b_f32 v[52:55], v157, v234, v[52:55]
	v_mfma_f32_4x4x1_16b_f32 v[56:59], v158, v234, v[56:59]
	v_mfma_f32_4x4x1_16b_f32 v[60:63], v159, v234, v[60:63]
	v_mfma_f32_4x4x1_16b_f32 v[64:67], v128, v233, v[64:67]
	v_mfma_f32_4x4x1_16b_f32 v[68:71], v129, v233, v[68:71]
	v_mfma_f32_4x4x1_16b_f32 v[72:75], v130, v233, v[72:75]
	v_mfma_f32_4x4x1_16b_f32 v[76:79], v131, v233, v[76:79]
	v_mfma_f32_4x4x1_16b_f32 v[80:83], v132, v233, v[80:83]
	v_mfma_f32_4x4x1_16b_f32 v[84:87], v133, v233, v[84:87]
	v_mfma_f32_4x4x1_16b_f32 v[88:91], v134, v233, v[88:91]
	v_mfma_f32_4x4x1_16b_f32 v[92:95], v135, v233, v[92:95]
	v_mfma_f32_4x4x1_16b_f32 v[96:99], v136, v233, v[96:99]
	v_mfma_f32_4x4x1_16b_f32 v[100:103], v137, v233, v[100:103]
	v_mfma_f32_4x4x1_16b_f32 v[104:107], v138, v233, v[104:107]
	v_mfma_f32_4x4x1_16b_f32 v[108:111], v139, v233, v[108:111]
	v_mfma_f32_4x4x1_16b_f32 v[112:115], v140, v233, v[112:115]
	v_mfma_f32_4x4x1_16b_f32 v[116:119], v141, v233, v[116:119]
	v_mfma_f32_4x4x1_16b_f32 v[120:123], v142, v233, v[120:123]
	v_mfma_f32_4x4x1_16b_f32 v[124:127], v143, v233, v[124:127]
	s_waitcnt vmcnt(5)
; #define SB __builtin_amdgcn_sched_barrier(0)
; #define LD1(set, s) { const int e_ = min((int)(s), LC - 1) * (int)stp; const unsigned s4_ = ob4 + (unsigned)(e_ * 4), s2_ = ob2 + (unsigned)(e_ * 2); set.w = LDX(rW, s4_); set.a = LDX(rA, s4_); set.b = LDX(rB, s4_); \
;             set.kw = __builtin_amdgcn_raw_buffer_load_b64(rK, lo8, s2_, 0); set.v = __builtin_amdgcn_raw_buffer_load_b16(rV, lo2, s2_, 0); }
; #define TOUCH1(set) asm volatile("" :: "v"(set.w), "v"(set.a), "v"(set.b), "v"(set.kw), "v"(set.v))
; #define ST1(set) { DERIVE_BK(set); float sd[4]; ScanK<0>::dot(S, set.a, sd); ScanK<0>::updS(S, set, -((sd[0] + sd[1]) + (sd[2] + sd[3])), __uint_as_float(set.v << 16)); }
; #define LD1(set, s) { const int e_ = min((int)(s), LC - 1) * (int)stp; const unsigned s4_ = ob4 + (unsigned)(e_ * 4); set.w = LDX(rW, s4_); set.a = LDX(rA, s4_); set.b = LDX(rB, s4_); }
; #define TOUCH1(set) asm volatile("" :: "v"(set.w), "v"(set.a), "v"(set.b))
; #define ST1(set) { DERIVE_B(set); float sd[4]; ScanK<0>::dot(S, set.a, sd); ScanK<0>::updP(S, set, -((sd[0] + sd[1]) + (sd[2] + sd[3]))); }
; template <bool MIX> __device__ __forceinline__ void scan_pass1(const Params& p, int d, float* ldsf) {
;     ...
;             In1 i0, i1; LD1(i0, 0);
; #pragma unroll 1
;             for (int s = 0; s < LC; s += 2) { TOUCH1(i0); SB; LD1(i1, s + 1); SB; ST1(i0); TOUCH1(i1); SB; LD1(i0, s + 2); SB; ST1(i1); }
	buffer_load_dwordx4 v[176:179], v235, s[64:67], s72 offen
	buffer_load_dwordx4 v[180:183], v250, s[64:67], s72 offen
	buffer_load_dwordx4 v[184:187], v251, s[64:67], s72 offen
	buffer_load_dwordx2 v[188:189], v252, s[64:67], s76 offen
	buffer_load_ushort v190, v253, s[64:67], s76 offen
	s_add_i32 s72, s72, 0xfffff000
	s_max_i32 s72, s72, 0
	s_add_i32 s76, s76, 0xfffff800
	s_max_i32 s76, s76, 0
	v_pk_mul_f32 v[244:245], v[196:197], v[236:237]
	v_pk_mul_f32 v[246:247], v[198:199], v[238:239]
	v_pk_mul_f32 v[236:237], v[236:237], v[192:193]
	v_pk_mul_f32 v[238:239], v[238:239], v[194:195]
	v_pk_fma_f32 v[228:229], v[200:201], v[216:217], v[220:221]
	v_pk_fma_f32 v[230:231], v[202:203], v[218:219], v[222:223]
	v_pk_mul_f32 v[208:209], v[196:197], v[200:201]
	v_pk_mul_f32 v[210:211], v[198:199], v[202:203]
	v_rcp_f32_e32 v240, v236
	v_rcp_f32_e32 v241, v237
	v_rcp_f32_e32 v242, v238
	v_rcp_f32_e32 v243, v239
	v_lshlrev_b32_e32 v212, 16, v204
	v_and_b32_e32 v213, 0xffff0000, v204
	v_lshlrev_b32_e32 v214, 16, v205
	v_and_b32_e32 v215, 0xffff0000, v205
	v_pk_mul_f32 v[212:213], v[212:213], v[228:229]
	v_pk_mul_f32 v[214:215], v[214:215], v[230:231]
	v_lshlrev_b32_e32 v234, 16, v206
	v_pk_mul_f32 v[208:209], v[208:209], v[240:241]
	v_pk_mul_f32 v[210:211], v[210:211], v[242:243]
	v_pk_mul_f32 v[212:213], v[212:213], v[240:241]
	v_pk_mul_f32 v[214:215], v[214:215], v[242:243]
	ds_write2_b32 v248, v208, v209 offset0:0 offset1:16
	ds_write2_b32 v248, v210, v211 offset0:32 offset1:48
	ds_write2_b32 v248, v212, v213 offset0:64 offset1:80
	ds_write2_b32 v248, v214, v215 offset0:96 offset1:112
	ds_read_b128 v[128:131], v249 offset:0
	ds_read_b128 v[132:135], v249 offset:16
	ds_read_b128 v[136:139], v249 offset:32
	ds_read_b128 v[140:143], v249 offset:48
	ds_read_b128 v[144:147], v249 offset:256
	ds_read_b128 v[148:151], v249 offset:272
	ds_read_b128 v[152:155], v249 offset:288
	ds_read_b128 v[156:159], v249 offset:304
	v_mul_f32_dpp v224, v244, v0 row_newbcast:0 row_mask:0xf bank_mask:0xf
	v_mul_f32_dpp v225, v245, v1 row_newbcast:0 row_mask:0xf bank_mask:0xf
	v_fmac_f32_dpp v224, v246, v2 row_newbcast:0 row_mask:0xf bank_mask:0xf
	v_fmac_f32_dpp v225, v247, v3 row_newbcast:0 row_mask:0xf bank_mask:0xf
	v_fmac_f32_dpp v224, v244, v4 row_newbcast:1 row_mask:0xf bank_mask:0xf
	v_fmac_f32_dpp v225, v245, v5 row_newbcast:1 row_mask:0xf bank_mask:0xf
	v_fmac_f32_dpp v224, v246, v6 row_newbcast:1 row_mask:0xf bank_mask:0xf
	v_fmac_f32_dpp v225, v247, v7 row_newbcast:1 row_mask:0xf bank_mask:0xf
	v_fmac_f32_dpp v224, v244, v8 row_newbcast:2 row_mask:0xf bank_mask:0xf
	v_fmac_f32_dpp v225, v245, v9 row_newbcast:2 row_mask:0xf bank_mask:0xf
	v_fmac_f32_dpp v224, v246, v10 row_newbcast:2 row_mask:0xf bank_mask:0xf
	v_fmac_f32_dpp v225, v247, v11 row_newbcast:2 row_mask:0xf bank_mask:0xf
	v_fmac_f32_dpp v224, v244, v12 row_newbcast:3 row_mask:0xf bank_mask:0xf
	v_fmac_f32_dpp v225, v245, v13 row_newbcast:3 row_mask:0xf bank_mask:0xf
	v_fmac_f32_dpp v224, v246, v14 row_newbcast:3 row_mask:0xf bank_mask:0xf
	v_fmac_f32_dpp v225, v247, v15 row_newbcast:3 row_mask:0xf bank_mask:0xf
	v_fmac_f32_dpp v224, v244, v16 row_newbcast:4 row_mask:0xf bank_mask:0xf
	v_fmac_f32_dpp v225, v245, v17 row_newbcast:4 row_mask:0xf bank_mask:0xf
	v_fmac_f32_dpp v224, v246, v18 row_newbcast:4 row_mask:0xf bank_mask:0xf
	v_fmac_f32_dpp v225, v247, v19 row_newbcast:4 row_mask:0xf bank_mask:0xf
	v_fmac_f32_dpp v224, v244, v20 row_newbcast:5 row_mask:0xf bank_mask:0xf
	v_fmac_f32_dpp v225, v245, v21 row_newbcast:5 row_mask:0xf bank_mask:0xf
	v_fmac_f32_dpp v224, v246, v22 row_newbcast:5 row_mask:0xf bank_mask:0xf
	v_fmac_f32_dpp v225, v247, v23 row_newbcast:5 row_mask:0xf bank_mask:0xf
	v_fmac_f32_dpp v224, v244, v24 row_newbcast:6 row_mask:0xf bank_mask:0xf
	v_fmac_f32_dpp v225, v245, v25 row_newbcast:6 row_mask:0xf bank_mask:0xf
	v_fmac_f32_dpp v224, v246, v26 row_newbcast:6 row_mask:0xf bank_mask:0xf
	v_fmac_f32_dpp v225, v247, v27 row_newbcast:6 row_mask:0xf bank_mask:0xf
	v_fmac_f32_dpp v224, v244, v28 row_newbcast:7 row_mask:0xf bank_mask:0xf
	v_fmac_f32_dpp v225, v245, v29 row_newbcast:7 row_mask:0xf bank_mask:0xf
	v_fmac_f32_dpp v224, v246, v30 row_newbcast:7 row_mask:0xf bank_mask:0xf
	v_fmac_f32_dpp v225, v247, v31 row_newbcast:7 row_mask:0xf bank_mask:0xf
	v_fmac_f32_dpp v224, v244, v32 row_newbcast:8 row_mask:0xf bank_mask:0xf
	v_fmac_f32_dpp v225, v245, v33 row_newbcast:8 row_mask:0xf bank_mask:0xf
	v_fmac_f32_dpp v224, v246, v34 row_newbcast:8 row_mask:0xf bank_mask:0xf
	v_fmac_f32_dpp v225, v247, v35 row_newbcast:8 row_mask:0xf bank_mask:0xf
	v_fmac_f32_dpp v224, v244, v36 row_newbcast:9 row_mask:0xf bank_mask:0xf
	v_fmac_f32_dpp v225, v245, v37 row_newbcast:9 row_mask:0xf bank_mask:0xf
	v_fmac_f32_dpp v224, v246, v38 row_newbcast:9 row_mask:0xf bank_mask:0xf
	v_fmac_f32_dpp v225, v247, v39 row_newbcast:9 row_mask:0xf bank_mask:0xf
	v_fmac_f32_dpp v224, v244, v40 row_newbcast:10 row_mask:0xf bank_mask:0xf
	v_fmac_f32_dpp v225, v245, v41 row_newbcast:10 row_mask:0xf bank_mask:0xf
	v_fmac_f32_dpp v224, v246, v42 row_newbcast:10 row_mask:0xf bank_mask:0xf
	v_fmac_f32_dpp v225, v247, v43 row_newbcast:10 row_mask:0xf bank_mask:0xf
	v_fmac_f32_dpp v224, v244, v44 row_newbcast:11 row_mask:0xf bank_mask:0xf
	v_fmac_f32_dpp v225, v245, v45 row_newbcast:11 row_mask:0xf bank_mask:0xf
	v_fmac_f32_dpp v224, v246, v46 row_newbcast:11 row_mask:0xf bank_mask:0xf
	v_fmac_f32_dpp v225, v247, v47 row_newbcast:11 row_mask:0xf bank_mask:0xf
	v_fmac_f32_dpp v224, v244, v48 row_newbcast:12 row_mask:0xf bank_mask:0xf
	v_fmac_f32_dpp v225, v245, v49 row_newbcast:12 row_mask:0xf bank_mask:0xf
;     static __device__ __forceinline__ void dot(const float (&S)[64], const f32x4& a, float (&s)[4]) {
;         if constexpr (K == 0) {
;             asm volatile("v_mul_f32_dpp %0, %4, %8 row_newbcast:%16" DPPM "v_mul_f32_dpp %1, %5, %9 row_newbcast:%16" DPPM "v_mul_f32_dpp %2, %6, %10 row_newbcast:%16" DPPM "v_mul_f32_dpp %3, %7, %11 row_newbcast:%16" DPPM
;                          "v_fmac_f32_dpp %0, %4, %12 row_newbcast:%17" DPPM "v_fmac_f32_dpp %1, %5, %13 row_newbcast:%17" DPPM "v_fmac_f32_dpp %2, %6, %14 row_newbcast:%17" DPPM "v_fmac_f32_dpp %3, %7, %15 row_newbcast:%17" DPPM
;                          : "=&v"(s[0]), "=&v"(s[1]), "=&v"(s[2]), "=&v"(s[3])
;                          : "v"(a[0]), "v"(a[1]), "v"(a[2]), "v"(a[3]), "v"(S[K]), "v"(S[K + 1]), "v"(S[K + 2]), "v"(S[K + 3]), "v"(S[K + 4]), "v"(S[K + 5]), "v"(S[K + 6]), "v"(S[K + 7]), "n"(N0), "n"(N1));
;         } else
;         asm volatile("v_fmac_f32_dpp %0, %4, %8 row_newbcast:%16" DPPM "v_fmac_f32_dpp %1, %5, %9 row_newbcast:%16" DPPM "v_fmac_f32_dpp %2, %6, %10 row_newbcast:%16" DPPM "v_fmac_f32_dpp %3, %7, %11 row_newbcast:%16" DPPM
;                      "v_fmac_f32_dpp %0, %4, %12 row_newbcast:%17" DPPM "v_fmac_f32_dpp %1, %5, %13 row_newbcast:%17" DPPM "v_fmac_f32_dpp %2, %6, %14 row_newbcast:%17" DPPM "v_fmac_f32_dpp %3, %7, %15 row_newbcast:%17" DPPM
;                      : "+v"(s[0]), "+v"(s[1]), "+v"(s[2]), "+v"(s[3])
;                      : "v"(a[0]), "v"(a[1]), "v"(a[2]), "v"(a[3]), "v"(S[K]), "v"(S[K + 1]), "v"(S[K + 2]), "v"(S[K + 3]), "v"(S[K + 4]), "v"(S[K + 5]), "v"(S[K + 6]), "v"(S[K + 7]), "n"(N0), "n"(N1));
;         if constexpr (K + 8 < 64) ScanK<K + 8>::dot(S, a, s);
	v_fmac_f32_dpp v224, v246, v50 row_newbcast:12 row_mask:0xf bank_mask:0xf
	v_fmac_f32_dpp v225, v247, v51 row_newbcast:12 row_mask:0xf bank_mask:0xf
	v_fmac_f32_dpp v224, v244, v52 row_newbcast:13 row_mask:0xf bank_mask:0xf
	v_fmac_f32_dpp v225, v245, v53 row_newbcast:13 row_mask:0xf bank_mask:0xf
	v_fmac_f32_dpp v224, v246, v54 row_newbcast:13 row_mask:0xf bank_mask:0xf
	v_fmac_f32_dpp v225, v247, v55 row_newbcast:13 row_mask:0xf bank_mask:0xf
	v_fmac_f32_dpp v224, v244, v56 row_newbcast:14 row_mask:0xf bank_mask:0xf
	v_fmac_f32_dpp v225, v245, v57 row_newbcast:14 row_mask:0xf bank_mask:0xf
	v_fmac_f32_dpp v224, v246, v58 row_newbcast:14 row_mask:0xf bank_mask:0xf
	v_fmac_f32_dpp v225, v247, v59 row_newbcast:14 row_mask:0xf bank_mask:0xf
	v_fmac_f32_dpp v224, v244, v60 row_newbcast:15 row_mask:0xf bank_mask:0xf
	v_fmac_f32_dpp v225, v245, v61 row_newbcast:15 row_mask:0xf bank_mask:0xf
	v_fmac_f32_dpp v224, v246, v62 row_newbcast:15 row_mask:0xf bank_mask:0xf
	v_fmac_f32_dpp v225, v247, v63 row_newbcast:15 row_mask:0xf bank_mask:0xf
	v_mul_f32_dpp v228, v244, v64 row_newbcast:0 row_mask:0xf bank_mask:0xf
	v_mul_f32_dpp v229, v245, v65 row_newbcast:0 row_mask:0xf bank_mask:0xf
	v_fmac_f32_dpp v228, v246, v66 row_newbcast:0 row_mask:0xf bank_mask:0xf
	v_fmac_f32_dpp v229, v247, v67 row_newbcast:0 row_mask:0xf bank_mask:0xf
	v_fmac_f32_dpp v228, v244, v68 row_newbcast:1 row_mask:0xf bank_mask:0xf
	v_fmac_f32_dpp v229, v245, v69 row_newbcast:1 row_mask:0xf bank_mask:0xf
	v_fmac_f32_dpp v228, v246, v70 row_newbcast:1 row_mask:0xf bank_mask:0xf
	v_fmac_f32_dpp v229, v247, v71 row_newbcast:1 row_mask:0xf bank_mask:0xf
	v_fmac_f32_dpp v228, v244, v72 row_newbcast:2 row_mask:0xf bank_mask:0xf
	v_fmac_f32_dpp v229, v245, v73 row_newbcast:2 row_mask:0xf bank_mask:0xf
	v_fmac_f32_dpp v228, v246, v74 row_newbcast:2 row_mask:0xf bank_mask:0xf
	v_fmac_f32_dpp v229, v247, v75 row_newbcast:2 row_mask:0xf bank_mask:0xf
	v_fmac_f32_dpp v228, v244, v76 row_newbcast:3 row_mask:0xf bank_mask:0xf
	v_fmac_f32_dpp v229, v245, v77 row_newbcast:3 row_mask:0xf bank_mask:0xf
	v_fmac_f32_dpp v228, v246, v78 row_newbcast:3 row_mask:0xf bank_mask:0xf
	v_fmac_f32_dpp v229, v247, v79 row_newbcast:3 row_mask:0xf bank_mask:0xf
	v_fmac_f32_dpp v228, v244, v80 row_newbcast:4 row_mask:0xf bank_mask:0xf
	v_fmac_f32_dpp v229, v245, v81 row_newbcast:4 row_mask:0xf bank_mask:0xf
	v_fmac_f32_dpp v228, v246, v82 row_newbcast:4 row_mask:0xf bank_mask:0xf
	v_fmac_f32_dpp v229, v247, v83 row_newbcast:4 row_mask:0xf bank_mask:0xf
	v_fmac_f32_dpp v228, v244, v84 row_newbcast:5 row_mask:0xf bank_mask:0xf
	v_fmac_f32_dpp v229, v245, v85 row_newbcast:5 row_mask:0xf bank_mask:0xf
	v_fmac_f32_dpp v228, v246, v86 row_newbcast:5 row_mask:0xf bank_mask:0xf
	v_fmac_f32_dpp v229, v247, v87 row_newbcast:5 row_mask:0xf bank_mask:0xf
	v_fmac_f32_dpp v228, v244, v88 row_newbcast:6 row_mask:0xf bank_mask:0xf
	v_fmac_f32_dpp v229, v245, v89 row_newbcast:6 row_mask:0xf bank_mask:0xf
	v_fmac_f32_dpp v228, v246, v90 row_newbcast:6 row_mask:0xf bank_mask:0xf
	v_fmac_f32_dpp v229, v247, v91 row_newbcast:6 row_mask:0xf bank_mask:0xf
	v_fmac_f32_dpp v228, v244, v92 row_newbcast:7 row_mask:0xf bank_mask:0xf
	v_fmac_f32_dpp v229, v245, v93 row_newbcast:7 row_mask:0xf bank_mask:0xf
	v_fmac_f32_dpp v228, v246, v94 row_newbcast:7 row_mask:0xf bank_mask:0xf
	v_fmac_f32_dpp v229, v247, v95 row_newbcast:7 row_mask:0xf bank_mask:0xf
	v_fmac_f32_dpp v228, v244, v96 row_newbcast:8 row_mask:0xf bank_mask:0xf
	v_fmac_f32_dpp v229, v245, v97 row_newbcast:8 row_mask:0xf bank_mask:0xf
	v_fmac_f32_dpp v228, v246, v98 row_newbcast:8 row_mask:0xf bank_mask:0xf
	v_fmac_f32_dpp v229, v247, v99 row_newbcast:8 row_mask:0xf bank_mask:0xf
	v_fmac_f32_dpp v228, v244, v100 row_newbcast:9 row_mask:0xf bank_mask:0xf
	v_fmac_f32_dpp v229, v245, v101 row_newbcast:9 row_mask:0xf bank_mask:0xf
	v_fmac_f32_dpp v228, v246, v102 row_newbcast:9 row_mask:0xf bank_mask:0xf
	v_fmac_f32_dpp v229, v247, v103 row_newbcast:9 row_mask:0xf bank_mask:0xf
	v_fmac_f32_dpp v228, v244, v104 row_newbcast:10 row_mask:0xf bank_mask:0xf
	v_fmac_f32_dpp v229, v245, v105 row_newbcast:10 row_mask:0xf bank_mask:0xf
	v_fmac_f32_dpp v228, v246, v106 row_newbcast:10 row_mask:0xf bank_mask:0xf
	v_fmac_f32_dpp v229, v247, v107 row_newbcast:10 row_mask:0xf bank_mask:0xf
	v_fmac_f32_dpp v228, v244, v108 row_newbcast:11 row_mask:0xf bank_mask:0xf
	v_fmac_f32_dpp v229, v245, v109 row_newbcast:11 row_mask:0xf bank_mask:0xf
	v_fmac_f32_dpp v228, v246, v110 row_newbcast:11 row_mask:0xf bank_mask:0xf
	v_fmac_f32_dpp v229, v247, v111 row_newbcast:11 row_mask:0xf bank_mask:0xf
	v_fmac_f32_dpp v228, v244, v112 row_newbcast:12 row_mask:0xf bank_mask:0xf
	v_fmac_f32_dpp v229, v245, v113 row_newbcast:12 row_mask:0xf bank_mask:0xf
	v_fmac_f32_dpp v228, v246, v114 row_newbcast:12 row_mask:0xf bank_mask:0xf
	v_fmac_f32_dpp v229, v247, v115 row_newbcast:12 row_mask:0xf bank_mask:0xf
	v_fmac_f32_dpp v228, v244, v116 row_newbcast:13 row_mask:0xf bank_mask:0xf
	v_fmac_f32_dpp v229, v245, v117 row_newbcast:13 row_mask:0xf bank_mask:0xf
	v_fmac_f32_dpp v228, v246, v118 row_newbcast:13 row_mask:0xf bank_mask:0xf
	v_fmac_f32_dpp v229, v247, v119 row_newbcast:13 row_mask:0xf bank_mask:0xf
	v_fmac_f32_dpp v228, v244, v120 row_newbcast:14 row_mask:0xf bank_mask:0xf
	v_fmac_f32_dpp v229, v245, v121 row_newbcast:14 row_mask:0xf bank_mask:0xf
	v_fmac_f32_dpp v228, v246, v122 row_newbcast:14 row_mask:0xf bank_mask:0xf
	v_fmac_f32_dpp v229, v247, v123 row_newbcast:14 row_mask:0xf bank_mask:0xf
	v_fmac_f32_dpp v228, v244, v124 row_newbcast:15 row_mask:0xf bank_mask:0xf
	v_fmac_f32_dpp v229, v245, v125 row_newbcast:15 row_mask:0xf bank_mask:0xf
	v_fmac_f32_dpp v228, v246, v126 row_newbcast:15 row_mask:0xf bank_mask:0xf
	v_fmac_f32_dpp v229, v247, v127 row_newbcast:15 row_mask:0xf bank_mask:0xf
	v_sub_f32_e64 v232, -v224, v225
	v_sub_f32_e64 v233, -v228, v229
	s_waitcnt lgkmcnt(0)
;     static __device__ __forceinline__ void updS(float (&S)[64], const In1& in, float sa, float vv) {
;         float t0, t1, t2, t3;
;         asm volatile("v_mul_f32_dpp %0, %8, %21 row_newbcast:%22" DPPM "v_mul_f32_dpp %1, %9, %21 row_newbcast:%22" DPPM "v_mul_f32_dpp %2, %10, %21 row_newbcast:%22" DPPM "v_mul_f32_dpp %3, %11, %21 row_newbcast:%22" DPPM
;                      "v_fmac_f32_dpp %0, %12, %4 row_newbcast:%22" DPPM "v_fmac_f32_dpp %1, %13, %5 row_newbcast:%22" DPPM "v_fmac_f32_dpp %2, %14, %6 row_newbcast:%22" DPPM "v_fmac_f32_dpp %3, %15, %7 row_newbcast:%22" DPPM
;                      "v_fmac_f32_dpp %0, %16, %20 row_newbcast:%22" DPPM "v_fmac_f32_dpp %1, %17, %20 row_newbcast:%22" DPPM "v_fmac_f32_dpp %2, %18, %20 row_newbcast:%22" DPPM "v_fmac_f32_dpp %3, %19, %20 row_newbcast:%22" DPPM
;                      : "=&v"(t0), "=&v"(t1), "=&v"(t2), "=&v"(t3)
;                      : "v"(S[K]), "v"(S[K + 1]), "v"(S[K + 2]), "v"(S[K + 3]), "v"(in.kd[0]), "v"(in.kd[1]), "v"(in.kd[2]), "v"(in.kd[3]), "v"(in.w[0]), "v"(in.w[1]), "v"(in.w[2]), "v"(in.w[3]),
;                        "v"(in.b[0]), "v"(in.b[1]), "v"(in.b[2]), "v"(in.b[3]), "v"(sa), "v"(vv), "n"(N0));
;         S[K] = t0; S[K + 1] = t1; S[K + 2] = t2; S[K + 3] = t3;
;         if constexpr (K + 4 < 64) ScanK<K + 4>::updS(S, in, sa, vv);
;     }
;     static __device__ __forceinline__ void updP(float (&P)[64], const In1& in, float sa) {
;         float u0, u1, u2, u3;
;         asm volatile("v_mul_f32_dpp %0, %8, %4 row_newbcast:%17" DPPM "v_mul_f32_dpp %1, %9, %5 row_newbcast:%17" DPPM "v_mul_f32_dpp %2, %10, %6 row_newbcast:%17" DPPM "v_mul_f32_dpp %3, %11, %7 row_newbcast:%17" DPPM
;                      "v_fmac_f32_dpp %0, %12, %16 row_newbcast:%17" DPPM "v_fmac_f32_dpp %1, %13, %16 row_newbcast:%17" DPPM "v_fmac_f32_dpp %2, %14, %16 row_newbcast:%17" DPPM "v_fmac_f32_dpp %3, %15, %16 row_newbcast:%17" DPPM
;                      : "=&v"(u0), "=&v"(u1), "=&v"(u2), "=&v"(u3)
;                      : "v"(P[K]), "v"(P[K + 1]), "v"(P[K + 2]), "v"(P[K + 3]), "v"(in.w[0]), "v"(in.w[1]), "v"(in.w[2]), "v"(in.w[3]), "v"(in.b[0]), "v"(in.b[1]), "v"(in.b[2]), "v"(in.b[3]), "v"(sa), "n"(N0));
;         P[K] = u0; P[K + 1] = u1; P[K + 2] = u2; P[K + 3] = u3;
;         if constexpr (K + 4 < 64) ScanK<K + 4>::updP(P, in, sa);
;     }
	s_nop 1
	v_mfma_f32_4x4x1_16b_f32 v[0:3], v128, v232, v[0:3]
	v_mfma_f32_4x4x1_16b_f32 v[4:7], v129, v232, v[4:7]
	v_mfma_f32_4x4x1_16b_f32 v[8:11], v130, v232, v[8:11]
	v_mfma_f32_4x4x1_16b_f32 v[12:15], v131, v232, v[12:15]
	v_mfma_f32_4x4x1_16b_f32 v[16:19], v132, v232, v[16:19]
	v_mfma_f32_4x4x1_16b_f32 v[20:23], v133, v232, v[20:23]
	v_mfma_f32_4x4x1_16b_f32 v[24:27], v134, v232, v[24:27]
	v_mfma_f32_4x4x1_16b_f32 v[28:31], v135, v232, v[28:31]
	v_mfma_f32_4x4x1_16b_f32 v[32:35], v136, v232, v[32:35]
	v_mfma_f32_4x4x1_16b_f32 v[36:39], v137, v232, v[36:39]
	v_mfma_f32_4x4x1_16b_f32 v[40:43], v138, v232, v[40:43]
	v_mfma_f32_4x4x1_16b_f32 v[44:47], v139, v232, v[44:47]
	v_mfma_f32_4x4x1_16b_f32 v[48:51], v140, v232, v[48:51]
	v_mfma_f32_4x4x1_16b_f32 v[52:55], v141, v232, v[52:55]
	v_mfma_f32_4x4x1_16b_f32 v[56:59], v142, v232, v[56:59]
	v_mfma_f32_4x4x1_16b_f32 v[60:63], v143, v232, v[60:63]
	v_mfma_f32_4x4x1_16b_f32 v[0:3], v144, v234, v[0:3]
	v_mfma_f32_4x4x1_16b_f32 v[4:7], v145, v234, v[4:7]
	v_mfma_f32_4x4x1_16b_f32 v[8:11], v146, v234, v[8:11]
	v_mfma_f32_4x4x1_16b_f32 v[12:15], v147, v234, v[12:15]
	v_mfma_f32_4x4x1_16b_f32 v[16:19], v148, v234, v[16:19]
	v_mfma_f32_4x4x1_16b_f32 v[20:23], v149, v234, v[20:23]
	v_mfma_f32_4x4x1_16b_f32 v[24:27], v150, v234, v[24:27]
	v_mfma_f32_4x4x1_16b_f32 v[28:31], v151, v234, v[28:31]
	v_mfma_f32_4x4x1_16b_f32 v[32:35], v152, v234, v[32:35]
	v_mfma_f32_4x4x1_16b_f32 v[36:39], v153, v234, v[36:39]
	v_mfma_f32_4x4x1_16b_f32 v[40:43], v154, v234, v[40:43]
	v_mfma_f32_4x4x1_16b_f32 v[44:47], v155, v234, v[44:47]
	v_mfma_f32_4x4x1_16b_f32 v[48:51], v156, v234, v[48:51]
	v_mfma_f32_4x4x1_16b_f32 v[52:55], v157, v234, v[52:55]
	v_mfma_f32_4x4x1_16b_f32 v[56:59], v158, v234, v[56:59]
	v_mfma_f32_4x4x1_16b_f32 v[60:63], v159, v234, v[60:63]
	v_mfma_f32_4x4x1_16b_f32 v[64:67], v128, v233, v[64:67]
	v_mfma_f32_4x4x1_16b_f32 v[68:71], v129, v233, v[68:71]
	v_mfma_f32_4x4x1_16b_f32 v[72:75], v130, v233, v[72:75]
	v_mfma_f32_4x4x1_16b_f32 v[76:79], v131, v233, v[76:79]
	v_mfma_f32_4x4x1_16b_f32 v[80:83], v132, v233, v[80:83]
	v_mfma_f32_4x4x1_16b_f32 v[84:87], v133, v233, v[84:87]
	v_mfma_f32_4x4x1_16b_f32 v[88:91], v134, v233, v[88:91]
	v_mfma_f32_4x4x1_16b_f32 v[92:95], v135, v233, v[92:95]
	v_mfma_f32_4x4x1_16b_f32 v[96:99], v136, v233, v[96:99]
	v_mfma_f32_4x4x1_16b_f32 v[100:103], v137, v233, v[100:103]
	v_mfma_f32_4x4x1_16b_f32 v[104:107], v138, v233, v[104:107]
	v_mfma_f32_4x4x1_16b_f32 v[108:111], v139, v233, v[108:111]
	v_mfma_f32_4x4x1_16b_f32 v[112:115], v140, v233, v[112:115]
	v_mfma_f32_4x4x1_16b_f32 v[116:119], v141, v233, v[116:119]
	v_mfma_f32_4x4x1_16b_f32 v[120:123], v142, v233, v[120:123]
	v_mfma_f32_4x4x1_16b_f32 v[124:127], v143, v233, v[124:127]
	s_sub_u32 s83, s83, 1
	s_cmp_eq_u32 s83, 0
	s_cbranch_scc1 .Lmy_p1d1_ldone
	s_sub_u32 s9, s9, 1
	s_cmp_eq_u32 s9, 0
	s_cbranch_scc1 .Lmy_p1d1_renorm
	s_branch .Lmy_p1d1_loop
.Lmy_p1d1_ldone:
	s_waitcnt vmcnt(5)
	buffer_load_dwordx4 v[192:195], v235, s[64:67], s72 offen
	buffer_load_dwordx4 v[196:199], v250, s[64:67], s72 offen
	buffer_load_dwordx4 v[200:203], v251, s[64:67], s72 offen
	buffer_load_dwordx2 v[204:205], v252, s[64:67], s76 offen
	buffer_load_ushort v206, v253, s[64:67], s76 offen
	s_add_i32 s72, s72, 0xfffff000
	s_max_i32 s72, s72, 0
	s_add_i32 s76, s76, 0xfffff800
	s_max_i32 s76, s76, 0
	v_pk_mul_f32 v[244:245], v[164:165], v[236:237]
	v_pk_mul_f32 v[246:247], v[166:167], v[238:239]
	v_pk_mul_f32 v[236:237], v[236:237], v[160:161]
	v_pk_mul_f32 v[238:239], v[238:239], v[162:163]
	v_pk_fma_f32 v[228:229], v[168:169], v[216:217], v[220:221]
	v_pk_fma_f32 v[230:231], v[170:171], v[218:219], v[222:223]
	v_pk_mul_f32 v[208:209], v[164:165], v[168:169]
	v_pk_mul_f32 v[210:211], v[166:167], v[170:171]
	v_rcp_f32_e32 v240, v236
	v_rcp_f32_e32 v241, v237
	v_rcp_f32_e32 v242, v238
	v_rcp_f32_e32 v243, v239
	v_lshlrev_b32_e32 v212, 16, v172
	v_and_b32_e32 v213, 0xffff0000, v172
	v_lshlrev_b32_e32 v214, 16, v173
	v_and_b32_e32 v215, 0xffff0000, v173
	v_pk_mul_f32 v[212:213], v[212:213], v[228:229]
	v_pk_mul_f32 v[214:215], v[214:215], v[230:231]
	v_lshlrev_b32_e32 v234, 16, v174
	v_pk_mul_f32 v[208:209], v[208:209], v[240:241]
	v_pk_mul_f32 v[210:211], v[210:211], v[242:243]
	v_pk_mul_f32 v[212:213], v[212:213], v[240:241]
	v_pk_mul_f32 v[214:215], v[214:215], v[242:243]
	ds_write2_b32 v248, v208, v209 offset0:0 offset1:16
	ds_write2_b32 v248, v210, v211 offset0:32 offset1:48
	ds_write2_b32 v248, v212, v213 offset0:64 offset1:80
	ds_write2_b32 v248, v214, v215 offset0:96 offset1:112
	ds_read_b128 v[128:131], v249 offset:0
	ds_read_b128 v[132:135], v249 offset:16
	ds_read_b128 v[136:139], v249 offset:32
	ds_read_b128 v[140:143], v249 offset:48
	ds_read_b128 v[144:147], v249 offset:256
	ds_read_b128 v[148:151], v249 offset:272
	ds_read_b128 v[152:155], v249 offset:288
	ds_read_b128 v[156:159], v249 offset:304
	v_mul_f32_dpp v224, v244, v0 row_newbcast:0 row_mask:0xf bank_mask:0xf
	v_mul_f32_dpp v225, v245, v1 row_newbcast:0 row_mask:0xf bank_mask:0xf
	v_fmac_f32_dpp v224, v246, v2 row_newbcast:0 row_mask:0xf bank_mask:0xf
	v_fmac_f32_dpp v225, v247, v3 row_newbcast:0 row_mask:0xf bank_mask:0xf
	v_fmac_f32_dpp v224, v244, v4 row_newbcast:1 row_mask:0xf bank_mask:0xf
	v_fmac_f32_dpp v225, v245, v5 row_newbcast:1 row_mask:0xf bank_mask:0xf
	v_fmac_f32_dpp v224, v246, v6 row_newbcast:1 row_mask:0xf bank_mask:0xf
	v_fmac_f32_dpp v225, v247, v7 row_newbcast:1 row_mask:0xf bank_mask:0xf
	v_fmac_f32_dpp v224, v244, v8 row_newbcast:2 row_mask:0xf bank_mask:0xf
	v_fmac_f32_dpp v225, v245, v9 row_newbcast:2 row_mask:0xf bank_mask:0xf
;     static __device__ __forceinline__ void dot(const float (&S)[64], const f32x4& a, float (&s)[4]) {
;         if constexpr (K == 0) {
;             asm volatile("v_mul_f32_dpp %0, %4, %8 row_newbcast:%16" DPPM "v_mul_f32_dpp %1, %5, %9 row_newbcast:%16" DPPM "v_mul_f32_dpp %2, %6, %10 row_newbcast:%16" DPPM "v_mul_f32_dpp %3, %7, %11 row_newbcast:%16" DPPM
;                          "v_fmac_f32_dpp %0, %4, %12 row_newbcast:%17" DPPM "v_fmac_f32_dpp %1, %5, %13 row_newbcast:%17" DPPM "v_fmac_f32_dpp %2, %6, %14 row_newbcast:%17" DPPM "v_fmac_f32_dpp %3, %7, %15 row_newbcast:%17" DPPM
;                          : "=&v"(s[0]), "=&v"(s[1]), "=&v"(s[2]), "=&v"(s[3])
;                          : "v"(a[0]), "v"(a[1]), "v"(a[2]), "v"(a[3]), "v"(S[K]), "v"(S[K + 1]), "v"(S[K + 2]), "v"(S[K + 3]), "v"(S[K + 4]), "v"(S[K + 5]), "v"(S[K + 6]), "v"(S[K + 7]), "n"(N0), "n"(N1));
;         } else
;         asm volatile("v_fmac_f32_dpp %0, %4, %8 row_newbcast:%16" DPPM "v_fmac_f32_dpp %1, %5, %9 row_newbcast:%16" DPPM "v_fmac_f32_dpp %2, %6, %10 row_newbcast:%16" DPPM "v_fmac_f32_dpp %3, %7, %11 row_newbcast:%16" DPPM
;                      "v_fmac_f32_dpp %0, %4, %12 row_newbcast:%17" DPPM "v_fmac_f32_dpp %1, %5, %13 row_newbcast:%17" DPPM "v_fmac_f32_dpp %2, %6, %14 row_newbcast:%17" DPPM "v_fmac_f32_dpp %3, %7, %15 row_newbcast:%17" DPPM
;                      : "+v"(s[0]), "+v"(s[1]), "+v"(s[2]), "+v"(s[3])
;                      : "v"(a[0]), "v"(a[1]), "v"(a[2]), "v"(a[3]), "v"(S[K]), "v"(S[K + 1]), "v"(S[K + 2]), "v"(S[K + 3]), "v"(S[K + 4]), "v"(S[K + 5]), "v"(S[K + 6]), "v"(S[K + 7]), "n"(N0), "n"(N1));
;         if constexpr (K + 8 < 64) ScanK<K + 8>::dot(S, a, s);
	v_fmac_f32_dpp v224, v246, v10 row_newbcast:2 row_mask:0xf bank_mask:0xf
	v_fmac_f32_dpp v225, v247, v11 row_newbcast:2 row_mask:0xf bank_mask:0xf
	v_fmac_f32_dpp v224, v244, v12 row_newbcast:3 row_mask:0xf bank_mask:0xf
	v_fmac_f32_dpp v225, v245, v13 row_newbcast:3 row_mask:0xf bank_mask:0xf
	v_fmac_f32_dpp v224, v246, v14 row_newbcast:3 row_mask:0xf bank_mask:0xf
	v_fmac_f32_dpp v225, v247, v15 row_newbcast:3 row_mask:0xf bank_mask:0xf
	v_fmac_f32_dpp v224, v244, v16 row_newbcast:4 row_mask:0xf bank_mask:0xf
	v_fmac_f32_dpp v225, v245, v17 row_newbcast:4 row_mask:0xf bank_mask:0xf
	v_fmac_f32_dpp v224, v246, v18 row_newbcast:4 row_mask:0xf bank_mask:0xf
	v_fmac_f32_dpp v225, v247, v19 row_newbcast:4 row_mask:0xf bank_mask:0xf
	v_fmac_f32_dpp v224, v244, v20 row_newbcast:5 row_mask:0xf bank_mask:0xf
	v_fmac_f32_dpp v225, v245, v21 row_newbcast:5 row_mask:0xf bank_mask:0xf
	v_fmac_f32_dpp v224, v246, v22 row_newbcast:5 row_mask:0xf bank_mask:0xf
	v_fmac_f32_dpp v225, v247, v23 row_newbcast:5 row_mask:0xf bank_mask:0xf
	v_fmac_f32_dpp v224, v244, v24 row_newbcast:6 row_mask:0xf bank_mask:0xf
	v_fmac_f32_dpp v225, v245, v25 row_newbcast:6 row_mask:0xf bank_mask:0xf
	v_fmac_f32_dpp v224, v246, v26 row_newbcast:6 row_mask:0xf bank_mask:0xf
	v_fmac_f32_dpp v225, v247, v27 row_newbcast:6 row_mask:0xf bank_mask:0xf
	v_fmac_f32_dpp v224, v244, v28 row_newbcast:7 row_mask:0xf bank_mask:0xf
	v_fmac_f32_dpp v225, v245, v29 row_newbcast:7 row_mask:0xf bank_mask:0xf
	v_fmac_f32_dpp v224, v246, v30 row_newbcast:7 row_mask:0xf bank_mask:0xf
	v_fmac_f32_dpp v225, v247, v31 row_newbcast:7 row_mask:0xf bank_mask:0xf
	v_fmac_f32_dpp v224, v244, v32 row_newbcast:8 row_mask:0xf bank_mask:0xf
	v_fmac_f32_dpp v225, v245, v33 row_newbcast:8 row_mask:0xf bank_mask:0xf
	v_fmac_f32_dpp v224, v246, v34 row_newbcast:8 row_mask:0xf bank_mask:0xf
	v_fmac_f32_dpp v225, v247, v35 row_newbcast:8 row_mask:0xf bank_mask:0xf
	v_fmac_f32_dpp v224, v244, v36 row_newbcast:9 row_mask:0xf bank_mask:0xf
	v_fmac_f32_dpp v225, v245, v37 row_newbcast:9 row_mask:0xf bank_mask:0xf
	v_fmac_f32_dpp v224, v246, v38 row_newbcast:9 row_mask:0xf bank_mask:0xf
	v_fmac_f32_dpp v225, v247, v39 row_newbcast:9 row_mask:0xf bank_mask:0xf
	v_fmac_f32_dpp v224, v244, v40 row_newbcast:10 row_mask:0xf bank_mask:0xf
	v_fmac_f32_dpp v225, v245, v41 row_newbcast:10 row_mask:0xf bank_mask:0xf
	v_fmac_f32_dpp v224, v246, v42 row_newbcast:10 row_mask:0xf bank_mask:0xf
	v_fmac_f32_dpp v225, v247, v43 row_newbcast:10 row_mask:0xf bank_mask:0xf
	v_fmac_f32_dpp v224, v244, v44 row_newbcast:11 row_mask:0xf bank_mask:0xf
	v_fmac_f32_dpp v225, v245, v45 row_newbcast:11 row_mask:0xf bank_mask:0xf
	v_fmac_f32_dpp v224, v246, v46 row_newbcast:11 row_mask:0xf bank_mask:0xf
	v_fmac_f32_dpp v225, v247, v47 row_newbcast:11 row_mask:0xf bank_mask:0xf
	v_fmac_f32_dpp v224, v244, v48 row_newbcast:12 row_mask:0xf bank_mask:0xf
	v_fmac_f32_dpp v225, v245, v49 row_newbcast:12 row_mask:0xf bank_mask:0xf
	v_fmac_f32_dpp v224, v246, v50 row_newbcast:12 row_mask:0xf bank_mask:0xf
	v_fmac_f32_dpp v225, v247, v51 row_newbcast:12 row_mask:0xf bank_mask:0xf
	v_fmac_f32_dpp v224, v244, v52 row_newbcast:13 row_mask:0xf bank_mask:0xf
	v_fmac_f32_dpp v225, v245, v53 row_newbcast:13 row_mask:0xf bank_mask:0xf
	v_fmac_f32_dpp v224, v246, v54 row_newbcast:13 row_mask:0xf bank_mask:0xf
	v_fmac_f32_dpp v225, v247, v55 row_newbcast:13 row_mask:0xf bank_mask:0xf
	v_fmac_f32_dpp v224, v244, v56 row_newbcast:14 row_mask:0xf bank_mask:0xf
	v_fmac_f32_dpp v225, v245, v57 row_newbcast:14 row_mask:0xf bank_mask:0xf
	v_fmac_f32_dpp v224, v246, v58 row_newbcast:14 row_mask:0xf bank_mask:0xf
	v_fmac_f32_dpp v225, v247, v59 row_newbcast:14 row_mask:0xf bank_mask:0xf
	v_fmac_f32_dpp v224, v244, v60 row_newbcast:15 row_mask:0xf bank_mask:0xf
	v_fmac_f32_dpp v225, v245, v61 row_newbcast:15 row_mask:0xf bank_mask:0xf
	v_fmac_f32_dpp v224, v246, v62 row_newbcast:15 row_mask:0xf bank_mask:0xf
	v_fmac_f32_dpp v225, v247, v63 row_newbcast:15 row_mask:0xf bank_mask:0xf
	v_mul_f32_dpp v228, v244, v64 row_newbcast:0 row_mask:0xf bank_mask:0xf
	v_mul_f32_dpp v229, v245, v65 row_newbcast:0 row_mask:0xf bank_mask:0xf
	v_fmac_f32_dpp v228, v246, v66 row_newbcast:0 row_mask:0xf bank_mask:0xf
	v_fmac_f32_dpp v229, v247, v67 row_newbcast:0 row_mask:0xf bank_mask:0xf
	v_fmac_f32_dpp v228, v244, v68 row_newbcast:1 row_mask:0xf bank_mask:0xf
	v_fmac_f32_dpp v229, v245, v69 row_newbcast:1 row_mask:0xf bank_mask:0xf
	v_fmac_f32_dpp v228, v246, v70 row_newbcast:1 row_mask:0xf bank_mask:0xf
	v_fmac_f32_dpp v229, v247, v71 row_newbcast:1 row_mask:0xf bank_mask:0xf
	v_fmac_f32_dpp v228, v244, v72 row_newbcast:2 row_mask:0xf bank_mask:0xf
	v_fmac_f32_dpp v229, v245, v73 row_newbcast:2 row_mask:0xf bank_mask:0xf
	v_fmac_f32_dpp v228, v246, v74 row_newbcast:2 row_mask:0xf bank_mask:0xf
	v_fmac_f32_dpp v229, v247, v75 row_newbcast:2 row_mask:0xf bank_mask:0xf
	v_fmac_f32_dpp v228, v244, v76 row_newbcast:3 row_mask:0xf bank_mask:0xf
	v_fmac_f32_dpp v229, v245, v77 row_newbcast:3 row_mask:0xf bank_mask:0xf
	v_fmac_f32_dpp v228, v246, v78 row_newbcast:3 row_mask:0xf bank_mask:0xf
	v_fmac_f32_dpp v229, v247, v79 row_newbcast:3 row_mask:0xf bank_mask:0xf
	v_fmac_f32_dpp v228, v244, v80 row_newbcast:4 row_mask:0xf bank_mask:0xf
	v_fmac_f32_dpp v229, v245, v81 row_newbcast:4 row_mask:0xf bank_mask:0xf
	v_fmac_f32_dpp v228, v246, v82 row_newbcast:4 row_mask:0xf bank_mask:0xf
	v_fmac_f32_dpp v229, v247, v83 row_newbcast:4 row_mask:0xf bank_mask:0xf
	v_fmac_f32_dpp v228, v244, v84 row_newbcast:5 row_mask:0xf bank_mask:0xf
	v_fmac_f32_dpp v229, v245, v85 row_newbcast:5 row_mask:0xf bank_mask:0xf
;     static __device__ __forceinline__ void dot(const float (&S)[64], const f32x4& a, float (&s)[4]) {
;         if constexpr (K == 0) {
;             asm volatile("v_mul_f32_dpp %0, %4, %8 row_newbcast:%16" DPPM "v_mul_f32_dpp %1, %5, %9 row_newbcast:%16" DPPM "v_mul_f32_dpp %2, %6, %10 row_newbcast:%16" DPPM "v_mul_f32_dpp %3, %7, %11 row_newbcast:%16" DPPM
;                          "v_fmac_f32_dpp %0, %4, %12 row_newbcast:%17" DPPM "v_fmac_f32_dpp %1, %5, %13 row_newbcast:%17" DPPM "v_fmac_f32_dpp %2, %6, %14 row_newbcast:%17" DPPM "v_fmac_f32_dpp %3, %7, %15 row_newbcast:%17" DPPM
;                          : "=&v"(s[0]), "=&v"(s[1]), "=&v"(s[2]), "=&v"(s[3])
;                          : "v"(a[0]), "v"(a[1]), "v"(a[2]), "v"(a[3]), "v"(S[K]), "v"(S[K + 1]), "v"(S[K + 2]), "v"(S[K + 3]), "v"(S[K + 4]), "v"(S[K + 5]), "v"(S[K + 6]), "v"(S[K + 7]), "n"(N0), "n"(N1));
;         } else
;         asm volatile("v_fmac_f32_dpp %0, %4, %8 row_newbcast:%16" DPPM "v_fmac_f32_dpp %1, %5, %9 row_newbcast:%16" DPPM "v_fmac_f32_dpp %2, %6, %10 row_newbcast:%16" DPPM "v_fmac_f32_dpp %3, %7, %11 row_newbcast:%16" DPPM
;                      "v_fmac_f32_dpp %0, %4, %12 row_newbcast:%17" DPPM "v_fmac_f32_dpp %1, %5, %13 row_newbcast:%17" DPPM "v_fmac_f32_dpp %2, %6, %14 row_newbcast:%17" DPPM "v_fmac_f32_dpp %3, %7, %15 row_newbcast:%17" DPPM
;                      : "+v"(s[0]), "+v"(s[1]), "+v"(s[2]), "+v"(s[3])
;                      : "v"(a[0]), "v"(a[1]), "v"(a[2]), "v"(a[3]), "v"(S[K]), "v"(S[K + 1]), "v"(S[K + 2]), "v"(S[K + 3]), "v"(S[K + 4]), "v"(S[K + 5]), "v"(S[K + 6]), "v"(S[K + 7]), "n"(N0), "n"(N1));
;         if constexpr (K + 8 < 64) ScanK<K + 8>::dot(S, a, s);
;     static __device__ __forceinline__ void updS(float (&S)[64], const In1& in, float sa, float vv) {
;         float t0, t1, t2, t3;
;         asm volatile("v_mul_f32_dpp %0, %8, %21 row_newbcast:%22" DPPM "v_mul_f32_dpp %1, %9, %21 row_newbcast:%22" DPPM "v_mul_f32_dpp %2, %10, %21 row_newbcast:%22" DPPM "v_mul_f32_dpp %3, %11, %21 row_newbcast:%22" DPPM
;                      "v_fmac_f32_dpp %0, %12, %4 row_newbcast:%22" DPPM "v_fmac_f32_dpp %1, %13, %5 row_newbcast:%22" DPPM "v_fmac_f32_dpp %2, %14, %6 row_newbcast:%22" DPPM "v_fmac_f32_dpp %3, %15, %7 row_newbcast:%22" DPPM
	v_fmac_f32_dpp v228, v246, v86 row_newbcast:5 row_mask:0xf bank_mask:0xf
	v_fmac_f32_dpp v229, v247, v87 row_newbcast:5 row_mask:0xf bank_mask:0xf
	v_fmac_f32_dpp v228, v244, v88 row_newbcast:6 row_mask:0xf bank_mask:0xf
	v_fmac_f32_dpp v229, v245, v89 row_newbcast:6 row_mask:0xf bank_mask:0xf
	v_fmac_f32_dpp v228, v246, v90 row_newbcast:6 row_mask:0xf bank_mask:0xf
	v_fmac_f32_dpp v229, v247, v91 row_newbcast:6 row_mask:0xf bank_mask:0xf
	v_fmac_f32_dpp v228, v244, v92 row_newbcast:7 row_mask:0xf bank_mask:0xf
	v_fmac_f32_dpp v229, v245, v93 row_newbcast:7 row_mask:0xf bank_mask:0xf
	v_fmac_f32_dpp v228, v246, v94 row_newbcast:7 row_mask:0xf bank_mask:0xf
	v_fmac_f32_dpp v229, v247, v95 row_newbcast:7 row_mask:0xf bank_mask:0xf
	v_fmac_f32_dpp v228, v244, v96 row_newbcast:8 row_mask:0xf bank_mask:0xf
	v_fmac_f32_dpp v229, v245, v97 row_newbcast:8 row_mask:0xf bank_mask:0xf
	v_fmac_f32_dpp v228, v246, v98 row_newbcast:8 row_mask:0xf bank_mask:0xf
	v_fmac_f32_dpp v229, v247, v99 row_newbcast:8 row_mask:0xf bank_mask:0xf
	v_fmac_f32_dpp v228, v244, v100 row_newbcast:9 row_mask:0xf bank_mask:0xf
	v_fmac_f32_dpp v229, v245, v101 row_newbcast:9 row_mask:0xf bank_mask:0xf
	v_fmac_f32_dpp v228, v246, v102 row_newbcast:9 row_mask:0xf bank_mask:0xf
	v_fmac_f32_dpp v229, v247, v103 row_newbcast:9 row_mask:0xf bank_mask:0xf
	v_fmac_f32_dpp v228, v244, v104 row_newbcast:10 row_mask:0xf bank_mask:0xf
	v_fmac_f32_dpp v229, v245, v105 row_newbcast:10 row_mask:0xf bank_mask:0xf
	v_fmac_f32_dpp v228, v246, v106 row_newbcast:10 row_mask:0xf bank_mask:0xf
	v_fmac_f32_dpp v229, v247, v107 row_newbcast:10 row_mask:0xf bank_mask:0xf
	v_fmac_f32_dpp v228, v244, v108 row_newbcast:11 row_mask:0xf bank_mask:0xf
	v_fmac_f32_dpp v229, v245, v109 row_newbcast:11 row_mask:0xf bank_mask:0xf
	v_fmac_f32_dpp v228, v246, v110 row_newbcast:11 row_mask:0xf bank_mask:0xf
	v_fmac_f32_dpp v229, v247, v111 row_newbcast:11 row_mask:0xf bank_mask:0xf
	v_fmac_f32_dpp v228, v244, v112 row_newbcast:12 row_mask:0xf bank_mask:0xf
	v_fmac_f32_dpp v229, v245, v113 row_newbcast:12 row_mask:0xf bank_mask:0xf
	v_fmac_f32_dpp v228, v246, v114 row_newbcast:12 row_mask:0xf bank_mask:0xf
	v_fmac_f32_dpp v229, v247, v115 row_newbcast:12 row_mask:0xf bank_mask:0xf
	v_fmac_f32_dpp v228, v244, v116 row_newbcast:13 row_mask:0xf bank_mask:0xf
	v_fmac_f32_dpp v229, v245, v117 row_newbcast:13 row_mask:0xf bank_mask:0xf
	v_fmac_f32_dpp v228, v246, v118 row_newbcast:13 row_mask:0xf bank_mask:0xf
	v_fmac_f32_dpp v229, v247, v119 row_newbcast:13 row_mask:0xf bank_mask:0xf
	v_fmac_f32_dpp v228, v244, v120 row_newbcast:14 row_mask:0xf bank_mask:0xf
	v_fmac_f32_dpp v229, v245, v121 row_newbcast:14 row_mask:0xf bank_mask:0xf
	v_fmac_f32_dpp v228, v246, v122 row_newbcast:14 row_mask:0xf bank_mask:0xf
	v_fmac_f32_dpp v229, v247, v123 row_newbcast:14 row_mask:0xf bank_mask:0xf
	v_fmac_f32_dpp v228, v244, v124 row_newbcast:15 row_mask:0xf bank_mask:0xf
	v_fmac_f32_dpp v229, v245, v125 row_newbcast:15 row_mask:0xf bank_mask:0xf
	v_fmac_f32_dpp v228, v246, v126 row_newbcast:15 row_mask:0xf bank_mask:0xf
	v_fmac_f32_dpp v229, v247, v127 row_newbcast:15 row_mask:0xf bank_mask:0xf
	v_sub_f32_e64 v232, -v224, v225
	v_sub_f32_e64 v233, -v228, v229
	s_waitcnt lgkmcnt(0)
	s_nop 1
	v_mfma_f32_4x4x1_16b_f32 v[0:3], v128, v232, v[0:3]
	v_mfma_f32_4x4x1_16b_f32 v[4:7], v129, v232, v[4:7]
	v_mfma_f32_4x4x1_16b_f32 v[8:11], v130, v232, v[8:11]
	v_mfma_f32_4x4x1_16b_f32 v[12:15], v131, v232, v[12:15]
	v_mfma_f32_4x4x1_16b_f32 v[16:19], v132, v232, v[16:19]
	v_mfma_f32_4x4x1_16b_f32 v[20:23], v133, v232, v[20:23]
	v_mfma_f32_4x4x1_16b_f32 v[24:27], v134, v232, v[24:27]
	v_mfma_f32_4x4x1_16b_f32 v[28:31], v135, v232, v[28:31]
	v_mfma_f32_4x4x1_16b_f32 v[32:35], v136, v232, v[32:35]
	v_mfma_f32_4x4x1_16b_f32 v[36:39], v137, v232, v[36:39]
	v_mfma_f32_4x4x1_16b_f32 v[40:43], v138, v232, v[40:43]
	v_mfma_f32_4x4x1_16b_f32 v[44:47], v139, v232, v[44:47]
	v_mfma_f32_4x4x1_16b_f32 v[48:51], v140, v232, v[48:51]
	v_mfma_f32_4x4x1_16b_f32 v[52:55], v141, v232, v[52:55]
	v_mfma_f32_4x4x1_16b_f32 v[56:59], v142, v232, v[56:59]
	v_mfma_f32_4x4x1_16b_f32 v[60:63], v143, v232, v[60:63]
	v_mfma_f32_4x4x1_16b_f32 v[0:3], v144, v234, v[0:3]
	v_mfma_f32_4x4x1_16b_f32 v[4:7], v145, v234, v[4:7]
	v_mfma_f32_4x4x1_16b_f32 v[8:11], v146, v234, v[8:11]
	v_mfma_f32_4x4x1_16b_f32 v[12:15], v147, v234, v[12:15]
	v_mfma_f32_4x4x1_16b_f32 v[16:19], v148, v234, v[16:19]
	v_mfma_f32_4x4x1_16b_f32 v[20:23], v149, v234, v[20:23]
	v_mfma_f32_4x4x1_16b_f32 v[24:27], v150, v234, v[24:27]
	v_mfma_f32_4x4x1_16b_f32 v[28:31], v151, v234, v[28:31]
	v_mfma_f32_4x4x1_16b_f32 v[32:35], v152, v234, v[32:35]
	v_mfma_f32_4x4x1_16b_f32 v[36:39], v153, v234, v[36:39]
	v_mfma_f32_4x4x1_16b_f32 v[40:43], v154, v234, v[40:43]
	v_mfma_f32_4x4x1_16b_f32 v[44:47], v155, v234, v[44:47]
	v_mfma_f32_4x4x1_16b_f32 v[48:51], v156, v234, v[48:51]
	v_mfma_f32_4x4x1_16b_f32 v[52:55], v157, v234, v[52:55]
	v_mfma_f32_4x4x1_16b_f32 v[56:59], v158, v234, v[56:59]
	v_mfma_f32_4x4x1_16b_f32 v[60:63], v159, v234, v[60:63]
	v_mfma_f32_4x4x1_16b_f32 v[64:67], v128, v233, v[64:67]
	v_mfma_f32_4x4x1_16b_f32 v[68:71], v129, v233, v[68:71]
	v_mfma_f32_4x4x1_16b_f32 v[72:75], v130, v233, v[72:75]
	v_mfma_f32_4x4x1_16b_f32 v[76:79], v131, v233, v[76:79]
	v_mfma_f32_4x4x1_16b_f32 v[80:83], v132, v233, v[80:83]
	v_mfma_f32_4x4x1_16b_f32 v[84:87], v133, v233, v[84:87]
	v_mfma_f32_4x4x1_16b_f32 v[88:91], v134, v233, v[88:91]
	v_mfma_f32_4x4x1_16b_f32 v[92:95], v135, v233, v[92:95]
	v_mfma_f32_4x4x1_16b_f32 v[96:99], v136, v233, v[96:99]
	v_mfma_f32_4x4x1_16b_f32 v[100:103], v137, v233, v[100:103]
;     static __device__ __forceinline__ void updS(float (&S)[64], const In1& in, float sa, float vv) {
;         float t0, t1, t2, t3;
;         asm volatile("v_mul_f32_dpp %0, %8, %21 row_newbcast:%22" DPPM "v_mul_f32_dpp %1, %9, %21 row_newbcast:%22" DPPM "v_mul_f32_dpp %2, %10, %21 row_newbcast:%22" DPPM "v_mul_f32_dpp %3, %11, %21 row_newbcast:%22" DPPM
;                      "v_fmac_f32_dpp %0, %12, %4 row_newbcast:%22" DPPM "v_fmac_f32_dpp %1, %13, %5 row_newbcast:%22" DPPM "v_fmac_f32_dpp %2, %14, %6 row_newbcast:%22" DPPM "v_fmac_f32_dpp %3, %15, %7 row_newbcast:%22" DPPM
;                      "v_fmac_f32_dpp %0, %16, %20 row_newbcast:%22" DPPM "v_fmac_f32_dpp %1, %17, %20 row_newbcast:%22" DPPM "v_fmac_f32_dpp %2, %18, %20 row_newbcast:%22" DPPM "v_fmac_f32_dpp %3, %19, %20 row_newbcast:%22" DPPM
;                      : "=&v"(t0), "=&v"(t1), "=&v"(t2), "=&v"(t3)
;                      : "v"(S[K]), "v"(S[K + 1]), "v"(S[K + 2]), "v"(S[K + 3]), "v"(in.kd[0]), "v"(in.kd[1]), "v"(in.kd[2]), "v"(in.kd[3]), "v"(in.w[0]), "v"(in.w[1]), "v"(in.w[2]), "v"(in.w[3]),
;                        "v"(in.b[0]), "v"(in.b[1]), "v"(in.b[2]), "v"(in.b[3]), "v"(sa), "v"(vv), "n"(N0));
;         S[K] = t0; S[K + 1] = t1; S[K + 2] = t2; S[K + 3] = t3;
;         if constexpr (K + 4 < 64) ScanK<K + 4>::updS(S, in, sa, vv);
;     }
;     static __device__ __forceinline__ void updP(float (&P)[64], const In1& in, float sa) {
;         float u0, u1, u2, u3;
;         asm volatile("v_mul_f32_dpp %0, %8, %4 row_newbcast:%17" DPPM "v_mul_f32_dpp %1, %9, %5 row_newbcast:%17" DPPM "v_mul_f32_dpp %2, %10, %6 row_newbcast:%17" DPPM "v_mul_f32_dpp %3, %11, %7 row_newbcast:%17" DPPM
;                      "v_fmac_f32_dpp %0, %12, %16 row_newbcast:%17" DPPM "v_fmac_f32_dpp %1, %13, %16 row_newbcast:%17" DPPM "v_fmac_f32_dpp %2, %14, %16 row_newbcast:%17" DPPM "v_fmac_f32_dpp %3, %15, %16 row_newbcast:%17" DPPM
;                      : "=&v"(u0), "=&v"(u1), "=&v"(u2), "=&v"(u3)
;                      : "v"(P[K]), "v"(P[K + 1]), "v"(P[K + 2]), "v"(P[K + 3]), "v"(in.w[0]), "v"(in.w[1]), "v"(in.w[2]), "v"(in.w[3]), "v"(in.b[0]), "v"(in.b[1]), "v"(in.b[2]), "v"(in.b[3]), "v"(sa), "n"(N0));
;         P[K] = u0; P[K + 1] = u1; P[K + 2] = u2; P[K + 3] = u3;
;         if constexpr (K + 4 < 64) ScanK<K + 4>::updP(P, in, sa);
;     }
	v_mfma_f32_4x4x1_16b_f32 v[104:107], v138, v233, v[104:107]
	v_mfma_f32_4x4x1_16b_f32 v[108:111], v139, v233, v[108:111]
	v_mfma_f32_4x4x1_16b_f32 v[112:115], v140, v233, v[112:115]
	v_mfma_f32_4x4x1_16b_f32 v[116:119], v141, v233, v[116:119]
	v_mfma_f32_4x4x1_16b_f32 v[120:123], v142, v233, v[120:123]
	v_mfma_f32_4x4x1_16b_f32 v[124:127], v143, v233, v[124:127]
	v_mul_f32_dpp v0, v236, v0 row_newbcast:0 row_mask:0xf bank_mask:0xf
	v_mul_f32_dpp v1, v237, v1 row_newbcast:0 row_mask:0xf bank_mask:0xf
	v_mul_f32_dpp v2, v238, v2 row_newbcast:0 row_mask:0xf bank_mask:0xf
	v_mul_f32_dpp v3, v239, v3 row_newbcast:0 row_mask:0xf bank_mask:0xf
	v_mul_f32_dpp v4, v236, v4 row_newbcast:1 row_mask:0xf bank_mask:0xf
	v_mul_f32_dpp v5, v237, v5 row_newbcast:1 row_mask:0xf bank_mask:0xf
	v_mul_f32_dpp v6, v238, v6 row_newbcast:1 row_mask:0xf bank_mask:0xf
	v_mul_f32_dpp v7, v239, v7 row_newbcast:1 row_mask:0xf bank_mask:0xf
	v_mul_f32_dpp v8, v236, v8 row_newbcast:2 row_mask:0xf bank_mask:0xf
	v_mul_f32_dpp v9, v237, v9 row_newbcast:2 row_mask:0xf bank_mask:0xf
	v_mul_f32_dpp v10, v238, v10 row_newbcast:2 row_mask:0xf bank_mask:0xf
	v_mul_f32_dpp v11, v239, v11 row_newbcast:2 row_mask:0xf bank_mask:0xf
	v_mul_f32_dpp v12, v236, v12 row_newbcast:3 row_mask:0xf bank_mask:0xf
	v_mul_f32_dpp v13, v237, v13 row_newbcast:3 row_mask:0xf bank_mask:0xf
	v_mul_f32_dpp v14, v238, v14 row_newbcast:3 row_mask:0xf bank_mask:0xf
	v_mul_f32_dpp v15, v239, v15 row_newbcast:3 row_mask:0xf bank_mask:0xf
	v_mul_f32_dpp v16, v236, v16 row_newbcast:4 row_mask:0xf bank_mask:0xf
	v_mul_f32_dpp v17, v237, v17 row_newbcast:4 row_mask:0xf bank_mask:0xf
	v_mul_f32_dpp v18, v238, v18 row_newbcast:4 row_mask:0xf bank_mask:0xf
	v_mul_f32_dpp v19, v239, v19 row_newbcast:4 row_mask:0xf bank_mask:0xf
	v_mul_f32_dpp v20, v236, v20 row_newbcast:5 row_mask:0xf bank_mask:0xf
	v_mul_f32_dpp v21, v237, v21 row_newbcast:5 row_mask:0xf bank_mask:0xf
	v_mul_f32_dpp v22, v238, v22 row_newbcast:5 row_mask:0xf bank_mask:0xf
	v_mul_f32_dpp v23, v239, v23 row_newbcast:5 row_mask:0xf bank_mask:0xf
	v_mul_f32_dpp v24, v236, v24 row_newbcast:6 row_mask:0xf bank_mask:0xf
	v_mul_f32_dpp v25, v237, v25 row_newbcast:6 row_mask:0xf bank_mask:0xf
	v_mul_f32_dpp v26, v238, v26 row_newbcast:6 row_mask:0xf bank_mask:0xf
	v_mul_f32_dpp v27, v239, v27 row_newbcast:6 row_mask:0xf bank_mask:0xf
	v_mul_f32_dpp v28, v236, v28 row_newbcast:7 row_mask:0xf bank_mask:0xf
	v_mul_f32_dpp v29, v237, v29 row_newbcast:7 row_mask:0xf bank_mask:0xf
	v_mul_f32_dpp v30, v238, v30 row_newbcast:7 row_mask:0xf bank_mask:0xf
	v_mul_f32_dpp v31, v239, v31 row_newbcast:7 row_mask:0xf bank_mask:0xf
	v_mul_f32_dpp v32, v236, v32 row_newbcast:8 row_mask:0xf bank_mask:0xf
	v_mul_f32_dpp v33, v237, v33 row_newbcast:8 row_mask:0xf bank_mask:0xf
	v_mul_f32_dpp v34, v238, v34 row_newbcast:8 row_mask:0xf bank_mask:0xf
	v_mul_f32_dpp v35, v239, v35 row_newbcast:8 row_mask:0xf bank_mask:0xf
	v_mul_f32_dpp v36, v236, v36 row_newbcast:9 row_mask:0xf bank_mask:0xf
	v_mul_f32_dpp v37, v237, v37 row_newbcast:9 row_mask:0xf bank_mask:0xf
	v_mul_f32_dpp v38, v238, v38 row_newbcast:9 row_mask:0xf bank_mask:0xf
	v_mul_f32_dpp v39, v239, v39 row_newbcast:9 row_mask:0xf bank_mask:0xf
	v_mul_f32_dpp v40, v236, v40 row_newbcast:10 row_mask:0xf bank_mask:0xf
	v_mul_f32_dpp v41, v237, v41 row_newbcast:10 row_mask:0xf bank_mask:0xf
	v_mul_f32_dpp v42, v238, v42 row_newbcast:10 row_mask:0xf bank_mask:0xf
	v_mul_f32_dpp v43, v239, v43 row_newbcast:10 row_mask:0xf bank_mask:0xf
	v_mul_f32_dpp v44, v236, v44 row_newbcast:11 row_mask:0xf bank_mask:0xf
	v_mul_f32_dpp v45, v237, v45 row_newbcast:11 row_mask:0xf bank_mask:0xf
	v_mul_f32_dpp v46, v238, v46 row_newbcast:11 row_mask:0xf bank_mask:0xf
	v_mul_f32_dpp v47, v239, v47 row_newbcast:11 row_mask:0xf bank_mask:0xf
	v_mul_f32_dpp v48, v236, v48 row_newbcast:12 row_mask:0xf bank_mask:0xf
	v_mul_f32_dpp v49, v237, v49 row_newbcast:12 row_mask:0xf bank_mask:0xf
	v_mul_f32_dpp v50, v238, v50 row_newbcast:12 row_mask:0xf bank_mask:0xf
	v_mul_f32_dpp v51, v239, v51 row_newbcast:12 row_mask:0xf bank_mask:0xf
	v_mul_f32_dpp v52, v236, v52 row_newbcast:13 row_mask:0xf bank_mask:0xf
	v_mul_f32_dpp v53, v237, v53 row_newbcast:13 row_mask:0xf bank_mask:0xf
	v_mul_f32_dpp v54, v238, v54 row_newbcast:13 row_mask:0xf bank_mask:0xf
	v_mul_f32_dpp v55, v239, v55 row_newbcast:13 row_mask:0xf bank_mask:0xf
	v_mul_f32_dpp v56, v236, v56 row_newbcast:14 row_mask:0xf bank_mask:0xf
	v_mul_f32_dpp v57, v237, v57 row_newbcast:14 row_mask:0xf bank_mask:0xf
	v_mul_f32_dpp v58, v238, v58 row_newbcast:14 row_mask:0xf bank_mask:0xf
	v_mul_f32_dpp v59, v239, v59 row_newbcast:14 row_mask:0xf bank_mask:0xf
	v_mul_f32_dpp v60, v236, v60 row_newbcast:15 row_mask:0xf bank_mask:0xf
	v_mul_f32_dpp v61, v237, v61 row_newbcast:15 row_mask:0xf bank_mask:0xf
	v_mul_f32_dpp v62, v238, v62 row_newbcast:15 row_mask:0xf bank_mask:0xf
	v_mul_f32_dpp v63, v239, v63 row_newbcast:15 row_mask:0xf bank_mask:0xf
	v_mul_f32_dpp v64, v236, v64 row_newbcast:0 row_mask:0xf bank_mask:0xf
	v_mul_f32_dpp v65, v237, v65 row_newbcast:0 row_mask:0xf bank_mask:0xf
	v_mul_f32_dpp v66, v238, v66 row_newbcast:0 row_mask:0xf bank_mask:0xf
	v_mul_f32_dpp v67, v239, v67 row_newbcast:0 row_mask:0xf bank_mask:0xf
	v_mul_f32_dpp v68, v236, v68 row_newbcast:1 row_mask:0xf bank_mask:0xf
	v_mul_f32_dpp v69, v237, v69 row_newbcast:1 row_mask:0xf bank_mask:0xf
	v_mul_f32_dpp v70, v238, v70 row_newbcast:1 row_mask:0xf bank_mask:0xf
	v_mul_f32_dpp v71, v239, v71 row_newbcast:1 row_mask:0xf bank_mask:0xf
	v_mul_f32_dpp v72, v236, v72 row_newbcast:2 row_mask:0xf bank_mask:0xf
;     static __device__ __forceinline__ void updS(float (&S)[64], const In1& in, float sa, float vv) {
;         float t0, t1, t2, t3;
;         asm volatile("v_mul_f32_dpp %0, %8, %21 row_newbcast:%22" DPPM "v_mul_f32_dpp %1, %9, %21 row_newbcast:%22" DPPM "v_mul_f32_dpp %2, %10, %21 row_newbcast:%22" DPPM "v_mul_f32_dpp %3, %11, %21 row_newbcast:%22" DPPM
;                      "v_fmac_f32_dpp %0, %12, %4 row_newbcast:%22" DPPM "v_fmac_f32_dpp %1, %13, %5 row_newbcast:%22" DPPM "v_fmac_f32_dpp %2, %14, %6 row_newbcast:%22" DPPM "v_fmac_f32_dpp %3, %15, %7 row_newbcast:%22" DPPM
;                      "v_fmac_f32_dpp %0, %16, %20 row_newbcast:%22" DPPM "v_fmac_f32_dpp %1, %17, %20 row_newbcast:%22" DPPM "v_fmac_f32_dpp %2, %18, %20 row_newbcast:%22" DPPM "v_fmac_f32_dpp %3, %19, %20 row_newbcast:%22" DPPM
;                      : "=&v"(t0), "=&v"(t1), "=&v"(t2), "=&v"(t3)
;                      : "v"(S[K]), "v"(S[K + 1]), "v"(S[K + 2]), "v"(S[K + 3]), "v"(in.kd[0]), "v"(in.kd[1]), "v"(in.kd[2]), "v"(in.kd[3]), "v"(in.w[0]), "v"(in.w[1]), "v"(in.w[2]), "v"(in.w[3]),
;                        "v"(in.b[0]), "v"(in.b[1]), "v"(in.b[2]), "v"(in.b[3]), "v"(sa), "v"(vv), "n"(N0));
;         S[K] = t0; S[K + 1] = t1; S[K + 2] = t2; S[K + 3] = t3;
;         if constexpr (K + 4 < 64) ScanK<K + 4>::updS(S, in, sa, vv);
;     }
	v_mul_f32_dpp v73, v237, v73 row_newbcast:2 row_mask:0xf bank_mask:0xf
	v_mul_f32_dpp v74, v238, v74 row_newbcast:2 row_mask:0xf bank_mask:0xf
	v_mul_f32_dpp v75, v239, v75 row_newbcast:2 row_mask:0xf bank_mask:0xf
	v_mul_f32_dpp v76, v236, v76 row_newbcast:3 row_mask:0xf bank_mask:0xf
	v_mul_f32_dpp v77, v237, v77 row_newbcast:3 row_mask:0xf bank_mask:0xf
	v_mul_f32_dpp v78, v238, v78 row_newbcast:3 row_mask:0xf bank_mask:0xf
	v_mul_f32_dpp v79, v239, v79 row_newbcast:3 row_mask:0xf bank_mask:0xf
	v_mul_f32_dpp v80, v236, v80 row_newbcast:4 row_mask:0xf bank_mask:0xf
	v_mul_f32_dpp v81, v237, v81 row_newbcast:4 row_mask:0xf bank_mask:0xf
	v_mul_f32_dpp v82, v238, v82 row_newbcast:4 row_mask:0xf bank_mask:0xf
	v_mul_f32_dpp v83, v239, v83 row_newbcast:4 row_mask:0xf bank_mask:0xf
	v_mul_f32_dpp v84, v236, v84 row_newbcast:5 row_mask:0xf bank_mask:0xf
	v_mul_f32_dpp v85, v237, v85 row_newbcast:5 row_mask:0xf bank_mask:0xf
	v_mul_f32_dpp v86, v238, v86 row_newbcast:5 row_mask:0xf bank_mask:0xf
	v_mul_f32_dpp v87, v239, v87 row_newbcast:5 row_mask:0xf bank_mask:0xf
	v_mul_f32_dpp v88, v236, v88 row_newbcast:6 row_mask:0xf bank_mask:0xf
	v_mul_f32_dpp v89, v237, v89 row_newbcast:6 row_mask:0xf bank_mask:0xf
	v_mul_f32_dpp v90, v238, v90 row_newbcast:6 row_mask:0xf bank_mask:0xf
	v_mul_f32_dpp v91, v239, v91 row_newbcast:6 row_mask:0xf bank_mask:0xf
	v_mul_f32_dpp v92, v236, v92 row_newbcast:7 row_mask:0xf bank_mask:0xf
	v_mul_f32_dpp v93, v237, v93 row_newbcast:7 row_mask:0xf bank_mask:0xf
	v_mul_f32_dpp v94, v238, v94 row_newbcast:7 row_mask:0xf bank_mask:0xf
	v_mul_f32_dpp v95, v239, v95 row_newbcast:7 row_mask:0xf bank_mask:0xf
	v_mul_f32_dpp v96, v236, v96 row_newbcast:8 row_mask:0xf bank_mask:0xf
	v_mul_f32_dpp v97, v237, v97 row_newbcast:8 row_mask:0xf bank_mask:0xf
	v_mul_f32_dpp v98, v238, v98 row_newbcast:8 row_mask:0xf bank_mask:0xf
	v_mul_f32_dpp v99, v239, v99 row_newbcast:8 row_mask:0xf bank_mask:0xf
	v_mul_f32_dpp v100, v236, v100 row_newbcast:9 row_mask:0xf bank_mask:0xf
	v_mul_f32_dpp v101, v237, v101 row_newbcast:9 row_mask:0xf bank_mask:0xf
	v_mul_f32_dpp v102, v238, v102 row_newbcast:9 row_mask:0xf bank_mask:0xf
	v_mul_f32_dpp v103, v239, v103 row_newbcast:9 row_mask:0xf bank_mask:0xf
	v_mul_f32_dpp v104, v236, v104 row_newbcast:10 row_mask:0xf bank_mask:0xf
	v_mul_f32_dpp v105, v237, v105 row_newbcast:10 row_mask:0xf bank_mask:0xf
	v_mul_f32_dpp v106, v238, v106 row_newbcast:10 row_mask:0xf bank_mask:0xf
	v_mul_f32_dpp v107, v239, v107 row_newbcast:10 row_mask:0xf bank_mask:0xf
	v_mul_f32_dpp v108, v236, v108 row_newbcast:11 row_mask:0xf bank_mask:0xf
	v_mul_f32_dpp v109, v237, v109 row_newbcast:11 row_mask:0xf bank_mask:0xf
	v_mul_f32_dpp v110, v238, v110 row_newbcast:11 row_mask:0xf bank_mask:0xf
	v_mul_f32_dpp v111, v239, v111 row_newbcast:11 row_mask:0xf bank_mask:0xf
	v_mul_f32_dpp v112, v236, v112 row_newbcast:12 row_mask:0xf bank_mask:0xf
	v_mul_f32_dpp v113, v237, v113 row_newbcast:12 row_mask:0xf bank_mask:0xf
	v_mul_f32_dpp v114, v238, v114 row_newbcast:12 row_mask:0xf bank_mask:0xf
	v_mul_f32_dpp v115, v239, v115 row_newbcast:12 row_mask:0xf bank_mask:0xf
	v_mul_f32_dpp v116, v236, v116 row_newbcast:13 row_mask:0xf bank_mask:0xf
	v_mul_f32_dpp v117, v237, v117 row_newbcast:13 row_mask:0xf bank_mask:0xf
	v_mul_f32_dpp v118, v238, v118 row_newbcast:13 row_mask:0xf bank_mask:0xf
	v_mul_f32_dpp v119, v239, v119 row_newbcast:13 row_mask:0xf bank_mask:0xf
	v_mul_f32_dpp v120, v236, v120 row_newbcast:14 row_mask:0xf bank_mask:0xf
	v_mul_f32_dpp v121, v237, v121 row_newbcast:14 row_mask:0xf bank_mask:0xf
	v_mul_f32_dpp v122, v238, v122 row_newbcast:14 row_mask:0xf bank_mask:0xf
	v_mul_f32_dpp v123, v239, v123 row_newbcast:14 row_mask:0xf bank_mask:0xf
	v_mul_f32_dpp v124, v236, v124 row_newbcast:15 row_mask:0xf bank_mask:0xf
	v_mul_f32_dpp v125, v237, v125 row_newbcast:15 row_mask:0xf bank_mask:0xf
	v_mul_f32_dpp v126, v238, v126 row_newbcast:15 row_mask:0xf bank_mask:0xf
	v_mul_f32_dpp v127, v239, v127 row_newbcast:15 row_mask:0xf bank_mask:0xf
	v_mov_b32_e32 v236, 1.0
	v_mov_b32_e32 v237, 1.0
	v_mov_b32_e32 v238, 1.0
	v_mov_b32_e32 v239, 1.0
	s_waitcnt vmcnt(0)
; #define NEXT_ITEM() (MIX ? (int)__builtin_amdgcn_readfirstlane(lane == 0 ? __hip_atomic_fetch_add(qctr, 1u, __ATOMIC_RELAXED, __HIP_MEMORY_SCOPE_AGENT) : 0u) : item + (int)gridDim.x * 8)
; template <bool MIX> __device__ __forceinline__ void scan_pass1(const Params& p, int d, float* ldsf) {
;     ...
;     for (int item = MIX ? NEXT_ITEM() : (int)(blockIdx.x * 8 + wid); item < 2 * NS; item = NEXT_ITEM()) {
;     ...
;         float* po = (isP ? PT : SLT) + ((size_t)(bh * NC + c)) * 4096 + lane * 64;
; #pragma unroll
;         for (int i = 0; i < 16; ++i) *(f32x4*)(po + 4 * i) = (f32x4){S[4 * i], S[4 * i + 1], S[4 * i + 2], S[4 * i + 3]};
	s_nop 1
	v_and_b32_e32 v128, 63, v254
	v_lshlrev_b32_e32 v129, 8, v128
	v_lshlrev_b32_e32 v130, 2, v128
	global_store_dwordx4 v129, v[0:3], s[90:91] offset:0
	global_store_dwordx4 v129, v[4:7], s[90:91] offset:16
	global_store_dwordx4 v129, v[8:11], s[90:91] offset:32
	global_store_dwordx4 v129, v[12:15], s[90:91] offset:48
	global_store_dwordx4 v129, v[16:19], s[90:91] offset:64
	global_store_dwordx4 v129, v[20:23], s[90:91] offset:80
	global_store_dwordx4 v129, v[24:27], s[90:91] offset:96
	global_store_dwordx4 v129, v[28:31], s[90:91] offset:112
	global_store_dwordx4 v129, v[32:35], s[90:91] offset:128
	global_store_dwordx4 v129, v[36:39], s[90:91] offset:144
	global_store_dwordx4 v129, v[40:43], s[90:91] offset:160
	global_store_dwordx4 v129, v[44:47], s[90:91] offset:176
	global_store_dwordx4 v129, v[48:51], s[90:91] offset:192
	global_store_dwordx4 v129, v[52:55], s[90:91] offset:208
	global_store_dwordx4 v129, v[56:59], s[90:91] offset:224
	global_store_dwordx4 v129, v[60:63], s[90:91] offset:240
	global_store_dword v130, v64, s[92:93] offset:0
	global_store_dword v130, v65, s[92:93] offset:256
	global_store_dword v130, v66, s[92:93] offset:512
	global_store_dword v130, v67, s[92:93] offset:768
	global_store_dword v130, v68, s[92:93] offset:1024
	global_store_dword v130, v69, s[92:93] offset:1280
	global_store_dword v130, v70, s[92:93] offset:1536
	global_store_dword v130, v71, s[92:93] offset:1792
	global_store_dword v130, v72, s[92:93] offset:2048
	global_store_dword v130, v73, s[92:93] offset:2304
	global_store_dword v130, v74, s[92:93] offset:2560
	global_store_dword v130, v75, s[92:93] offset:2816
	global_store_dword v130, v76, s[92:93] offset:3072
	global_store_dword v130, v77, s[92:93] offset:3328
	global_store_dword v130, v78, s[92:93] offset:3584
	global_store_dword v130, v79, s[92:93] offset:3840
	s_add_u32 s92, s92, 0x1000
	s_addc_u32 s93, s93, 0
	global_store_dword v130, v80, s[92:93] offset:0
	global_store_dword v130, v81, s[92:93] offset:256
	global_store_dword v130, v82, s[92:93] offset:512
	global_store_dword v130, v83, s[92:93] offset:768
	global_store_dword v130, v84, s[92:93] offset:1024
	global_store_dword v130, v85, s[92:93] offset:1280
	global_store_dword v130, v86, s[92:93] offset:1536
	global_store_dword v130, v87, s[92:93] offset:1792
	global_store_dword v130, v88, s[92:93] offset:2048
	global_store_dword v130, v89, s[92:93] offset:2304
	global_store_dword v130, v90, s[92:93] offset:2560
	global_store_dword v130, v91, s[92:93] offset:2816
	global_store_dword v130, v92, s[92:93] offset:3072
	global_store_dword v130, v93, s[92:93] offset:3328
	global_store_dword v130, v94, s[92:93] offset:3584
	global_store_dword v130, v95, s[92:93] offset:3840
	s_add_u32 s92, s92, 0x1000
	s_addc_u32 s93, s93, 0
	global_store_dword v130, v96, s[92:93] offset:0
	global_store_dword v130, v97, s[92:93] offset:256
	global_store_dword v130, v98, s[92:93] offset:512
	global_store_dword v130, v99, s[92:93] offset:768
	global_store_dword v130, v100, s[92:93] offset:1024
	global_store_dword v130, v101, s[92:93] offset:1280
	global_store_dword v130, v102, s[92:93] offset:1536
	global_store_dword v130, v103, s[92:93] offset:1792
	global_store_dword v130, v104, s[92:93] offset:2048
	global_store_dword v130, v105, s[92:93] offset:2304
	global_store_dword v130, v106, s[92:93] offset:2560
	global_store_dword v130, v107, s[92:93] offset:2816
	global_store_dword v130, v108, s[92:93] offset:3072
	global_store_dword v130, v109, s[92:93] offset:3328
	global_store_dword v130, v110, s[92:93] offset:3584
	global_store_dword v130, v111, s[92:93] offset:3840
	s_add_u32 s92, s92, 0x1000
	s_addc_u32 s93, s93, 0
	global_store_dword v130, v112, s[92:93] offset:0
	global_store_dword v130, v113, s[92:93] offset:256
	global_store_dword v130, v114, s[92:93] offset:512
	global_store_dword v130, v115, s[92:93] offset:768
	global_store_dword v130, v116, s[92:93] offset:1024
	global_store_dword v130, v117, s[92:93] offset:1280
	global_store_dword v130, v118, s[92:93] offset:1536
	global_store_dword v130, v119, s[92:93] offset:1792
	global_store_dword v130, v120, s[92:93] offset:2048
	global_store_dword v130, v121, s[92:93] offset:2304
	global_store_dword v130, v122, s[92:93] offset:2560
	global_store_dword v130, v123, s[92:93] offset:2816
	global_store_dword v130, v124, s[92:93] offset:3072
	global_store_dword v130, v125, s[92:93] offset:3328
	global_store_dword v130, v126, s[92:93] offset:3584
	global_store_dword v130, v127, s[92:93] offset:3840
	s_nop 1
	s_lshl_b32 s6, s96, 3
	s_add_i32 s0, s0, s6
	s_branch .Lmy_p1d1_item
